# GEMM K-loops: LDS-DMA addresses as SGPR base + 32-bit VGPR offset (saddr form) instead of a 64-bit VALU add per load, all seven GEMM phases
# speedup vs baseline: 1.0042x; 1.0042x over previous
.LBB0_270:
	s_ashr_i32 s25, s24, 31
	s_lshl_b64 s[22:23], s[24:25], 19
	s_add_u32 s26, s16, s22
	s_addc_u32 s27, s17, s23
	s_and_b64 s[22:23], s[4:5], exec
	s_cselect_b32 s25, s27, s15
	s_cselect_b32 s56, s26, s14
	s_ashr_i32 s21, s20, 31
	s_lshl_b64 s[22:23], s[20:21], 19
	s_add_u32 s28, s34, s22
	s_addc_u32 s29, s35, s23
	s_and_b64 s[22:23], s[4:5], exec
	s_cselect_b32 s21, s29, s3
	s_cselect_b32 s57, s28, s2
	s_add_u32 s14, s14, 0x40080
	s_addc_u32 s15, s15, 0
	s_add_u32 s58, s2, 0x100
	s_addc_u32 s59, s3, 0
	s_mov_b32 s64, -2
	s_waitcnt lgkmcnt(0)
	s_waitcnt vmcnt(0)
	ds_read_b128 v[136:139], v159
	ds_read_b128 v[164:167], v159 offset:1024
	ds_read_b128 v[180:183], v159 offset:2048
	ds_read_b128 v[184:187], v159 offset:3072
	ds_read_b128 v[188:191], v160
	ds_read_b128 v[196:199], v160 offset:1024
	ds_read_b128 v[200:203], v160 offset:2048
	ds_read_b128 v[204:207], v160 offset:3072
	s_add_u32 s2, s14, 0xfffc0080
	s_addc_u32 s3, s15, -1
	s_cmp_eq_u32 s64, 12
	s_cselect_b32 s23, s25, s3
	s_cselect_b32 s22, s56, s2
	s_cselect_b32 s3, s21, s59
	s_cselect_b32 s2, s57, s58
	s_add_i32 m0, s31, 0xc000
	ds_read_b128 v[208:211], v161
	ds_read_b128 v[212:215], v161 offset:1024
	ds_read_b128 v[216:219], v161 offset:2048
	ds_read_b128 v[220:223], v161 offset:3072
	ds_read_b128 v[224:227], v161 offset:4096
	ds_read_b128 v[228:231], v161 offset:5120
	ds_read_b128 v[232:235], v161 offset:6144
	ds_read_b128 v[236:239], v161 offset:7168
	global_load_lds_dwordx4 v128, s[14:15]
	s_add_i32 m0, s31, 0xe000
	s_nop 0
	global_load_lds_dwordx4 v130, s[14:15]
	s_waitcnt vmcnt(8)
	s_waitcnt lgkmcnt(0)
	s_barrier
	s_setprio 1
	v_mfma_f32_16x16x32_bf16 v[116:119], v[136:139], v[208:211], 0
	v_mfma_f32_16x16x32_bf16 v[112:115], v[180:183], v[208:211], 0
	v_mfma_f32_16x16x32_bf16 v[108:111], v[136:139], v[216:219], 0
	v_mfma_f32_16x16x32_bf16 v[104:107], v[180:183], v[216:219], 0
	v_mfma_f32_16x16x32_bf16 v[92:95], v[136:139], v[224:227], 0
	v_mfma_f32_16x16x32_bf16 v[88:91], v[180:183], v[224:227], 0
	v_mfma_f32_16x16x32_bf16 v[76:79], v[136:139], v[232:235], 0
	v_mfma_f32_16x16x32_bf16 v[72:75], v[180:183], v[232:235], 0
	v_mfma_f32_16x16x32_bf16 v[116:119], v[164:167], v[212:215], v[116:119]
	v_mfma_f32_16x16x32_bf16 v[112:115], v[184:187], v[212:215], v[112:115]
	v_mfma_f32_16x16x32_bf16 v[108:111], v[164:167], v[220:223], v[108:111]
	v_mfma_f32_16x16x32_bf16 v[104:107], v[184:187], v[220:223], v[104:107]
	v_mfma_f32_16x16x32_bf16 v[92:95], v[164:167], v[228:231], v[92:95]
	v_mfma_f32_16x16x32_bf16 v[88:91], v[184:187], v[228:231], v[88:91]
	v_mfma_f32_16x16x32_bf16 v[76:79], v[164:167], v[236:239], v[76:79]
	v_mfma_f32_16x16x32_bf16 v[72:75], v[184:187], v[236:239], v[72:75]
	v_mfma_f32_16x16x32_bf16 v[124:127], v[188:191], v[208:211], 0
	v_mfma_f32_16x16x32_bf16 v[120:123], v[200:203], v[208:211], 0
	v_mfma_f32_16x16x32_bf16 v[100:103], v[188:191], v[216:219], 0
	v_mfma_f32_16x16x32_bf16 v[96:99], v[200:203], v[216:219], 0
	v_mfma_f32_16x16x32_bf16 v[84:87], v[188:191], v[224:227], 0
	v_mfma_f32_16x16x32_bf16 v[80:83], v[200:203], v[224:227], 0
	v_mfma_f32_16x16x32_bf16 v[68:71], v[188:191], v[232:235], 0
	v_mfma_f32_16x16x32_bf16 v[64:67], v[200:203], v[232:235], 0
	v_mfma_f32_16x16x32_bf16 v[124:127], v[196:199], v[212:215], v[124:127]
	v_mfma_f32_16x16x32_bf16 v[120:123], v[204:207], v[212:215], v[120:123]
	v_mfma_f32_16x16x32_bf16 v[100:103], v[196:199], v[220:223], v[100:103]
	v_mfma_f32_16x16x32_bf16 v[96:99], v[204:207], v[220:223], v[96:99]
	v_mfma_f32_16x16x32_bf16 v[84:87], v[196:199], v[228:231], v[84:87]
	v_mfma_f32_16x16x32_bf16 v[80:83], v[204:207], v[228:231], v[80:83]
	v_mfma_f32_16x16x32_bf16 v[68:71], v[196:199], v[236:239], v[68:71]
	v_mfma_f32_16x16x32_bf16 v[64:67], v[204:207], v[236:239], v[64:67]
	s_barrier
	s_setprio 0
	s_add_i32 s65, s49, s37
	s_add_u32 s98, s2, s10
	s_addc_u32 s99, s3, s11
	s_mov_b32 m0, s65
	ds_read_b128 v[208:211], v161 offset:16384
	ds_read_b128 v[212:215], v161 offset:17408
	ds_read_b128 v[216:219], v161 offset:18432
	ds_read_b128 v[220:223], v161 offset:19456
	ds_read_b128 v[224:227], v161 offset:20480
	ds_read_b128 v[228:231], v161 offset:21504
	ds_read_b128 v[232:235], v161 offset:22528
	ds_read_b128 v[236:239], v161 offset:23552
	global_load_lds_dwordx4 v142, s[2:3]
	s_add_i32 m0, s65, 0x2000
	s_add_u32 s66, s2, 0x40000
	s_addc_u32 s67, s3, 0
	s_add_i32 s65, s50, s37
	global_load_lds_dwordx4 v146, s[2:3]
	s_mov_b32 m0, s65
	s_nop 0
	global_load_lds_dwordx4 v142, s[66:67]
	s_add_i32 m0, s65, 0x2000
	s_nop 0
	global_load_lds_dwordx4 v146, s[66:67]
	s_add_u32 s100, s22, s10
	s_addc_u32 s101, s23, s11
	s_mov_b32 m0, s31
	s_nop 0
	global_load_lds_dwordx4 v140, s[22:23]
	s_mov_b32 m0, s38
	s_nop 0
	global_load_lds_dwordx4 v144, s[22:23]
	s_waitcnt vmcnt(8)
	s_waitcnt lgkmcnt(0)
	s_barrier
	s_setprio 1
	v_mfma_f32_16x16x32_bf16 v[52:55], v[136:139], v[208:211], 0
	v_mfma_f32_16x16x32_bf16 v[48:51], v[180:183], v[208:211], 0
	v_mfma_f32_16x16x32_bf16 v[44:47], v[136:139], v[216:219], 0
	v_mfma_f32_16x16x32_bf16 v[40:43], v[180:183], v[216:219], 0
	v_mfma_f32_16x16x32_bf16 v[28:31], v[136:139], v[224:227], 0
	v_mfma_f32_16x16x32_bf16 v[24:27], v[180:183], v[224:227], 0
	v_mfma_f32_16x16x32_bf16 v[12:15], v[136:139], v[232:235], 0
	v_mfma_f32_16x16x32_bf16 v[8:11], v[180:183], v[232:235], 0
	v_mfma_f32_16x16x32_bf16 v[52:55], v[164:167], v[212:215], v[52:55]
	v_mfma_f32_16x16x32_bf16 v[48:51], v[184:187], v[212:215], v[48:51]
	v_mfma_f32_16x16x32_bf16 v[44:47], v[164:167], v[220:223], v[44:47]
	v_mfma_f32_16x16x32_bf16 v[40:43], v[184:187], v[220:223], v[40:43]
	v_mfma_f32_16x16x32_bf16 v[28:31], v[164:167], v[228:231], v[28:31]
	v_mfma_f32_16x16x32_bf16 v[24:27], v[184:187], v[228:231], v[24:27]
	v_mfma_f32_16x16x32_bf16 v[12:15], v[164:167], v[236:239], v[12:15]
	v_mfma_f32_16x16x32_bf16 v[8:11], v[184:187], v[236:239], v[8:11]
	v_mfma_f32_16x16x32_bf16 v[60:63], v[188:191], v[208:211], 0
	v_mfma_f32_16x16x32_bf16 v[56:59], v[200:203], v[208:211], 0
	v_mfma_f32_16x16x32_bf16 v[36:39], v[188:191], v[216:219], 0
	v_mfma_f32_16x16x32_bf16 v[32:35], v[200:203], v[216:219], 0
	v_mfma_f32_16x16x32_bf16 v[20:23], v[188:191], v[224:227], 0
	v_mfma_f32_16x16x32_bf16 v[16:19], v[200:203], v[224:227], 0
	v_mfma_f32_16x16x32_bf16 v[4:7], v[188:191], v[232:235], 0
	v_mfma_f32_16x16x32_bf16 v[0:3], v[200:203], v[232:235], 0
	v_mfma_f32_16x16x32_bf16 v[60:63], v[196:199], v[212:215], v[60:63]
	v_mfma_f32_16x16x32_bf16 v[56:59], v[204:207], v[212:215], v[56:59]
	v_mfma_f32_16x16x32_bf16 v[36:39], v[196:199], v[220:223], v[36:39]
	v_mfma_f32_16x16x32_bf16 v[32:35], v[204:207], v[220:223], v[32:35]
	v_mfma_f32_16x16x32_bf16 v[20:23], v[196:199], v[228:231], v[20:23]
	v_mfma_f32_16x16x32_bf16 v[16:19], v[204:207], v[228:231], v[16:19]
	v_mfma_f32_16x16x32_bf16 v[4:7], v[196:199], v[236:239], v[4:7]
	v_mfma_f32_16x16x32_bf16 v[0:3], v[204:207], v[236:239], v[0:3]
	s_barrier
	s_setprio 0
	s_add_i32 s65, 0, 0x18000
	v_add_u32_e32 v163, s65, v156
	s_add_i32 s66, 0, 0x1c000
	ds_read_b128 v[136:139], v163
	ds_read_b128 v[164:167], v163 offset:1024
	ds_read_b128 v[180:183], v163 offset:2048
	ds_read_b128 v[184:187], v163 offset:3072
	v_add_u32_e32 v163, s66, v156
	ds_read_b128 v[188:191], v163
	ds_read_b128 v[196:199], v163 offset:1024
	ds_read_b128 v[200:203], v163 offset:2048
	ds_read_b128 v[204:207], v163 offset:3072
	s_add_u32 s22, s22, 0x40000
	s_addc_u32 s23, s23, 0
	s_mov_b32 m0, s39
	ds_read_b128 v[208:211], v161 offset:32768
	ds_read_b128 v[212:215], v161 offset:33792
	ds_read_b128 v[216:219], v161 offset:34816
	ds_read_b128 v[220:223], v161 offset:35840
	ds_read_b128 v[224:227], v161 offset:36864
	ds_read_b128 v[228:231], v161 offset:37888
	ds_read_b128 v[232:235], v161 offset:38912
	ds_read_b128 v[236:239], v161 offset:39936
	global_load_lds_dwordx4 v140, s[22:23]
	s_mov_b32 m0, s40
	s_nop 0
	global_load_lds_dwordx4 v144, s[22:23]
	s_waitcnt vmcnt(8)
	s_waitcnt lgkmcnt(0)
	s_barrier
	s_setprio 1
	v_mfma_f32_16x16x32_bf16 v[116:119], v[136:139], v[208:211], v[116:119]
	v_mfma_f32_16x16x32_bf16 v[112:115], v[180:183], v[208:211], v[112:115]
	v_mfma_f32_16x16x32_bf16 v[108:111], v[136:139], v[216:219], v[108:111]
	v_mfma_f32_16x16x32_bf16 v[104:107], v[180:183], v[216:219], v[104:107]
	v_mfma_f32_16x16x32_bf16 v[92:95], v[136:139], v[224:227], v[92:95]
	v_mfma_f32_16x16x32_bf16 v[88:91], v[180:183], v[224:227], v[88:91]
	v_mfma_f32_16x16x32_bf16 v[76:79], v[136:139], v[232:235], v[76:79]
	v_mfma_f32_16x16x32_bf16 v[72:75], v[180:183], v[232:235], v[72:75]
	v_mfma_f32_16x16x32_bf16 v[116:119], v[164:167], v[212:215], v[116:119]
	v_mfma_f32_16x16x32_bf16 v[112:115], v[184:187], v[212:215], v[112:115]
	v_mfma_f32_16x16x32_bf16 v[108:111], v[164:167], v[220:223], v[108:111]
	v_mfma_f32_16x16x32_bf16 v[104:107], v[184:187], v[220:223], v[104:107]
	v_mfma_f32_16x16x32_bf16 v[92:95], v[164:167], v[228:231], v[92:95]
	v_mfma_f32_16x16x32_bf16 v[88:91], v[184:187], v[228:231], v[88:91]
	v_mfma_f32_16x16x32_bf16 v[76:79], v[164:167], v[236:239], v[76:79]
	v_mfma_f32_16x16x32_bf16 v[72:75], v[184:187], v[236:239], v[72:75]
	v_mfma_f32_16x16x32_bf16 v[124:127], v[188:191], v[208:211], v[124:127]
	v_mfma_f32_16x16x32_bf16 v[120:123], v[200:203], v[208:211], v[120:123]
	v_mfma_f32_16x16x32_bf16 v[100:103], v[188:191], v[216:219], v[100:103]
	v_mfma_f32_16x16x32_bf16 v[96:99], v[200:203], v[216:219], v[96:99]
	v_mfma_f32_16x16x32_bf16 v[84:87], v[188:191], v[224:227], v[84:87]
	v_mfma_f32_16x16x32_bf16 v[80:83], v[200:203], v[224:227], v[80:83]
	v_mfma_f32_16x16x32_bf16 v[68:71], v[188:191], v[232:235], v[68:71]
	v_mfma_f32_16x16x32_bf16 v[64:67], v[200:203], v[232:235], v[64:67]
	v_mfma_f32_16x16x32_bf16 v[124:127], v[196:199], v[212:215], v[124:127]
	v_mfma_f32_16x16x32_bf16 v[120:123], v[204:207], v[212:215], v[120:123]
	v_mfma_f32_16x16x32_bf16 v[100:103], v[196:199], v[220:223], v[100:103]
	v_mfma_f32_16x16x32_bf16 v[96:99], v[204:207], v[220:223], v[96:99]
	v_mfma_f32_16x16x32_bf16 v[84:87], v[196:199], v[228:231], v[84:87]
	v_mfma_f32_16x16x32_bf16 v[80:83], v[204:207], v[228:231], v[80:83]
	v_mfma_f32_16x16x32_bf16 v[68:71], v[196:199], v[236:239], v[68:71]
	v_mfma_f32_16x16x32_bf16 v[64:67], v[204:207], v[236:239], v[64:67]
	s_barrier
	s_setprio 0
	s_add_i32 s22, s65, s37
	s_mov_b32 m0, s22
	ds_read_b128 v[208:211], v161 offset:49152
	ds_read_b128 v[212:215], v161 offset:50176
	ds_read_b128 v[216:219], v161 offset:51200
	ds_read_b128 v[220:223], v161 offset:52224
	ds_read_b128 v[224:227], v161 offset:53248
	ds_read_b128 v[228:231], v161 offset:54272
	ds_read_b128 v[232:235], v161 offset:55296
	ds_read_b128 v[236:239], v161 offset:56320
	global_load_lds_dwordx4 v142, s[98:99]
	s_add_i32 m0, s22, 0x2000
	s_add_u32 s2, s2, 0x40080
	s_addc_u32 s3, s3, 0
	s_add_i32 s22, s66, s37
	global_load_lds_dwordx4 v146, s[98:99]
	s_mov_b32 m0, s22
	s_nop 0
	global_load_lds_dwordx4 v142, s[2:3]
	s_add_i32 m0, s22, 0x2000
	s_nop 0
	global_load_lds_dwordx4 v146, s[2:3]
	s_mov_b32 m0, s43
	s_nop 0
	global_load_lds_dwordx4 v140, s[100:101]
	s_mov_b32 m0, s44
	s_nop 0
	global_load_lds_dwordx4 v144, s[100:101]
	s_waitcnt vmcnt(8)
	s_waitcnt lgkmcnt(0)
	s_barrier
	s_setprio 1
	v_mfma_f32_16x16x32_bf16 v[52:55], v[136:139], v[208:211], v[52:55]
	v_mfma_f32_16x16x32_bf16 v[48:51], v[180:183], v[208:211], v[48:51]
	v_mfma_f32_16x16x32_bf16 v[44:47], v[136:139], v[216:219], v[44:47]
	v_mfma_f32_16x16x32_bf16 v[40:43], v[180:183], v[216:219], v[40:43]
	v_mfma_f32_16x16x32_bf16 v[28:31], v[136:139], v[224:227], v[28:31]
	v_mfma_f32_16x16x32_bf16 v[24:27], v[180:183], v[224:227], v[24:27]
	v_mfma_f32_16x16x32_bf16 v[12:15], v[136:139], v[232:235], v[12:15]
	v_mfma_f32_16x16x32_bf16 v[8:11], v[180:183], v[232:235], v[8:11]
	v_mfma_f32_16x16x32_bf16 v[52:55], v[164:167], v[212:215], v[52:55]
	v_mfma_f32_16x16x32_bf16 v[48:51], v[184:187], v[212:215], v[48:51]
	v_mfma_f32_16x16x32_bf16 v[44:47], v[164:167], v[220:223], v[44:47]
	v_mfma_f32_16x16x32_bf16 v[40:43], v[184:187], v[220:223], v[40:43]
	v_mfma_f32_16x16x32_bf16 v[28:31], v[164:167], v[228:231], v[28:31]
	v_mfma_f32_16x16x32_bf16 v[24:27], v[184:187], v[228:231], v[24:27]
	v_mfma_f32_16x16x32_bf16 v[12:15], v[164:167], v[236:239], v[12:15]
	v_mfma_f32_16x16x32_bf16 v[8:11], v[184:187], v[236:239], v[8:11]
	v_mfma_f32_16x16x32_bf16 v[60:63], v[188:191], v[208:211], v[60:63]
	v_mfma_f32_16x16x32_bf16 v[56:59], v[200:203], v[208:211], v[56:59]
	v_mfma_f32_16x16x32_bf16 v[36:39], v[188:191], v[216:219], v[36:39]
	v_mfma_f32_16x16x32_bf16 v[32:35], v[200:203], v[216:219], v[32:35]
	v_mfma_f32_16x16x32_bf16 v[20:23], v[188:191], v[224:227], v[20:23]
	v_mfma_f32_16x16x32_bf16 v[16:19], v[200:203], v[224:227], v[16:19]
	v_mfma_f32_16x16x32_bf16 v[4:7], v[188:191], v[232:235], v[4:7]
	v_mfma_f32_16x16x32_bf16 v[0:3], v[200:203], v[232:235], v[0:3]
	v_mfma_f32_16x16x32_bf16 v[60:63], v[196:199], v[212:215], v[60:63]
	v_mfma_f32_16x16x32_bf16 v[56:59], v[204:207], v[212:215], v[56:59]
	v_mfma_f32_16x16x32_bf16 v[36:39], v[196:199], v[220:223], v[36:39]
	v_mfma_f32_16x16x32_bf16 v[32:35], v[204:207], v[220:223], v[32:35]
	v_mfma_f32_16x16x32_bf16 v[20:23], v[196:199], v[228:231], v[20:23]
	v_mfma_f32_16x16x32_bf16 v[16:19], v[204:207], v[228:231], v[16:19]
	v_mfma_f32_16x16x32_bf16 v[4:7], v[196:199], v[236:239], v[4:7]
	v_mfma_f32_16x16x32_bf16 v[0:3], v[204:207], v[236:239], v[0:3]
	s_barrier
	s_setprio 0
	s_add_i32 s64, s64, 2
	s_add_u32 s14, s14, 0x100
	s_addc_u32 s15, s15, 0
	s_add_u32 s58, s58, 0x100
	s_addc_u32 s59, s59, 0
	s_cmp_gt_u32 s64, 13
	s_cbranch_scc1 .Lgemm_kdone_0
.LBB0_271:
	ds_read_b128 v[136:139], v159
	ds_read_b128 v[164:167], v159 offset:1024
	ds_read_b128 v[180:183], v159 offset:2048
	ds_read_b128 v[184:187], v159 offset:3072
	ds_read_b128 v[188:191], v160
	ds_read_b128 v[196:199], v160 offset:1024
	ds_read_b128 v[200:203], v160 offset:2048
	ds_read_b128 v[204:207], v160 offset:3072
	s_add_u32 s2, s14, 0xfffc0080
	s_addc_u32 s3, s15, -1
	s_cmp_eq_u32 s64, 12
	s_cselect_b32 s23, s25, s3
	s_cselect_b32 s22, s56, s2
	s_cselect_b32 s3, s21, s59
	s_cselect_b32 s2, s57, s58
	s_add_i32 m0, s31, 0xc000
	ds_read_b128 v[208:211], v161
	ds_read_b128 v[212:215], v161 offset:1024
	ds_read_b128 v[216:219], v161 offset:2048
	ds_read_b128 v[220:223], v161 offset:3072
	ds_read_b128 v[224:227], v161 offset:4096
	ds_read_b128 v[228:231], v161 offset:5120
	ds_read_b128 v[232:235], v161 offset:6144
	ds_read_b128 v[236:239], v161 offset:7168
	global_load_lds_dwordx4 v128, s[14:15]
	s_add_i32 m0, s31, 0xe000
	s_nop 0
	global_load_lds_dwordx4 v130, s[14:15]
	s_waitcnt vmcnt(8)
	s_waitcnt lgkmcnt(0)
	s_barrier
	s_setprio 1
	v_mfma_f32_16x16x32_bf16 v[116:119], v[136:139], v[208:211], v[116:119]
	v_mfma_f32_16x16x32_bf16 v[112:115], v[180:183], v[208:211], v[112:115]
	v_mfma_f32_16x16x32_bf16 v[108:111], v[136:139], v[216:219], v[108:111]
	v_mfma_f32_16x16x32_bf16 v[104:107], v[180:183], v[216:219], v[104:107]
	v_mfma_f32_16x16x32_bf16 v[92:95], v[136:139], v[224:227], v[92:95]
	v_mfma_f32_16x16x32_bf16 v[88:91], v[180:183], v[224:227], v[88:91]
	v_mfma_f32_16x16x32_bf16 v[76:79], v[136:139], v[232:235], v[76:79]
	v_mfma_f32_16x16x32_bf16 v[72:75], v[180:183], v[232:235], v[72:75]
	v_mfma_f32_16x16x32_bf16 v[116:119], v[164:167], v[212:215], v[116:119]
	v_mfma_f32_16x16x32_bf16 v[112:115], v[184:187], v[212:215], v[112:115]
	v_mfma_f32_16x16x32_bf16 v[108:111], v[164:167], v[220:223], v[108:111]
	v_mfma_f32_16x16x32_bf16 v[104:107], v[184:187], v[220:223], v[104:107]
	v_mfma_f32_16x16x32_bf16 v[92:95], v[164:167], v[228:231], v[92:95]
	v_mfma_f32_16x16x32_bf16 v[88:91], v[184:187], v[228:231], v[88:91]
	v_mfma_f32_16x16x32_bf16 v[76:79], v[164:167], v[236:239], v[76:79]
	v_mfma_f32_16x16x32_bf16 v[72:75], v[184:187], v[236:239], v[72:75]
	v_mfma_f32_16x16x32_bf16 v[124:127], v[188:191], v[208:211], v[124:127]
	v_mfma_f32_16x16x32_bf16 v[120:123], v[200:203], v[208:211], v[120:123]
	v_mfma_f32_16x16x32_bf16 v[100:103], v[188:191], v[216:219], v[100:103]
	v_mfma_f32_16x16x32_bf16 v[96:99], v[200:203], v[216:219], v[96:99]
	v_mfma_f32_16x16x32_bf16 v[84:87], v[188:191], v[224:227], v[84:87]
	v_mfma_f32_16x16x32_bf16 v[80:83], v[200:203], v[224:227], v[80:83]
	v_mfma_f32_16x16x32_bf16 v[68:71], v[188:191], v[232:235], v[68:71]
	v_mfma_f32_16x16x32_bf16 v[64:67], v[200:203], v[232:235], v[64:67]
	v_mfma_f32_16x16x32_bf16 v[124:127], v[196:199], v[212:215], v[124:127]
	v_mfma_f32_16x16x32_bf16 v[120:123], v[204:207], v[212:215], v[120:123]
	v_mfma_f32_16x16x32_bf16 v[100:103], v[196:199], v[220:223], v[100:103]
	v_mfma_f32_16x16x32_bf16 v[96:99], v[204:207], v[220:223], v[96:99]
	v_mfma_f32_16x16x32_bf16 v[84:87], v[196:199], v[228:231], v[84:87]
	v_mfma_f32_16x16x32_bf16 v[80:83], v[204:207], v[228:231], v[80:83]
	v_mfma_f32_16x16x32_bf16 v[68:71], v[196:199], v[236:239], v[68:71]
	v_mfma_f32_16x16x32_bf16 v[64:67], v[204:207], v[236:239], v[64:67]
	s_barrier
	s_setprio 0
	s_add_i32 s65, s49, s37
	s_add_u32 s98, s2, s10
	s_addc_u32 s99, s3, s11
	s_mov_b32 m0, s65
	ds_read_b128 v[208:211], v161 offset:16384
	ds_read_b128 v[212:215], v161 offset:17408
	ds_read_b128 v[216:219], v161 offset:18432
	ds_read_b128 v[220:223], v161 offset:19456
	ds_read_b128 v[224:227], v161 offset:20480
	ds_read_b128 v[228:231], v161 offset:21504
	ds_read_b128 v[232:235], v161 offset:22528
	ds_read_b128 v[236:239], v161 offset:23552
	global_load_lds_dwordx4 v142, s[2:3]
	s_add_i32 m0, s65, 0x2000
	s_add_u32 s66, s2, 0x40000
	s_addc_u32 s67, s3, 0
	s_add_i32 s65, s50, s37
	global_load_lds_dwordx4 v146, s[2:3]
	s_mov_b32 m0, s65
	s_nop 0
	global_load_lds_dwordx4 v142, s[66:67]
	s_add_i32 m0, s65, 0x2000
	s_nop 0
	global_load_lds_dwordx4 v146, s[66:67]
	s_add_u32 s100, s22, s10
	s_addc_u32 s101, s23, s11
	s_mov_b32 m0, s31
	s_nop 0
	global_load_lds_dwordx4 v140, s[22:23]
	s_mov_b32 m0, s38
	s_nop 0
	global_load_lds_dwordx4 v144, s[22:23]
	s_waitcnt vmcnt(8)
	s_waitcnt lgkmcnt(0)
	s_barrier
	s_setprio 1
	v_mfma_f32_16x16x32_bf16 v[52:55], v[136:139], v[208:211], v[52:55]
	v_mfma_f32_16x16x32_bf16 v[48:51], v[180:183], v[208:211], v[48:51]
	v_mfma_f32_16x16x32_bf16 v[44:47], v[136:139], v[216:219], v[44:47]
	v_mfma_f32_16x16x32_bf16 v[40:43], v[180:183], v[216:219], v[40:43]
	v_mfma_f32_16x16x32_bf16 v[28:31], v[136:139], v[224:227], v[28:31]
	v_mfma_f32_16x16x32_bf16 v[24:27], v[180:183], v[224:227], v[24:27]
	v_mfma_f32_16x16x32_bf16 v[12:15], v[136:139], v[232:235], v[12:15]
	v_mfma_f32_16x16x32_bf16 v[8:11], v[180:183], v[232:235], v[8:11]
	v_mfma_f32_16x16x32_bf16 v[52:55], v[164:167], v[212:215], v[52:55]
	v_mfma_f32_16x16x32_bf16 v[48:51], v[184:187], v[212:215], v[48:51]
	v_mfma_f32_16x16x32_bf16 v[44:47], v[164:167], v[220:223], v[44:47]
	v_mfma_f32_16x16x32_bf16 v[40:43], v[184:187], v[220:223], v[40:43]
	v_mfma_f32_16x16x32_bf16 v[28:31], v[164:167], v[228:231], v[28:31]
	v_mfma_f32_16x16x32_bf16 v[24:27], v[184:187], v[228:231], v[24:27]
	v_mfma_f32_16x16x32_bf16 v[12:15], v[164:167], v[236:239], v[12:15]
	v_mfma_f32_16x16x32_bf16 v[8:11], v[184:187], v[236:239], v[8:11]
	v_mfma_f32_16x16x32_bf16 v[60:63], v[188:191], v[208:211], v[60:63]
	v_mfma_f32_16x16x32_bf16 v[56:59], v[200:203], v[208:211], v[56:59]
	v_mfma_f32_16x16x32_bf16 v[36:39], v[188:191], v[216:219], v[36:39]
	v_mfma_f32_16x16x32_bf16 v[32:35], v[200:203], v[216:219], v[32:35]
	v_mfma_f32_16x16x32_bf16 v[20:23], v[188:191], v[224:227], v[20:23]
	v_mfma_f32_16x16x32_bf16 v[16:19], v[200:203], v[224:227], v[16:19]
	v_mfma_f32_16x16x32_bf16 v[4:7], v[188:191], v[232:235], v[4:7]
	v_mfma_f32_16x16x32_bf16 v[0:3], v[200:203], v[232:235], v[0:3]
	v_mfma_f32_16x16x32_bf16 v[60:63], v[196:199], v[212:215], v[60:63]
	v_mfma_f32_16x16x32_bf16 v[56:59], v[204:207], v[212:215], v[56:59]
	v_mfma_f32_16x16x32_bf16 v[36:39], v[196:199], v[220:223], v[36:39]
	v_mfma_f32_16x16x32_bf16 v[32:35], v[204:207], v[220:223], v[32:35]
	v_mfma_f32_16x16x32_bf16 v[20:23], v[196:199], v[228:231], v[20:23]
	v_mfma_f32_16x16x32_bf16 v[16:19], v[204:207], v[228:231], v[16:19]
	v_mfma_f32_16x16x32_bf16 v[4:7], v[196:199], v[236:239], v[4:7]
	v_mfma_f32_16x16x32_bf16 v[0:3], v[204:207], v[236:239], v[0:3]
	s_barrier
	s_setprio 0
	s_add_i32 s65, 0, 0x18000
	v_add_u32_e32 v163, s65, v156
	s_add_i32 s66, 0, 0x1c000
	ds_read_b128 v[136:139], v163
	ds_read_b128 v[164:167], v163 offset:1024
	ds_read_b128 v[180:183], v163 offset:2048
	ds_read_b128 v[184:187], v163 offset:3072
	v_add_u32_e32 v163, s66, v156
	ds_read_b128 v[188:191], v163
	ds_read_b128 v[196:199], v163 offset:1024
	ds_read_b128 v[200:203], v163 offset:2048
	ds_read_b128 v[204:207], v163 offset:3072
	s_add_u32 s22, s22, 0x40000
	s_addc_u32 s23, s23, 0
	s_mov_b32 m0, s39
	ds_read_b128 v[208:211], v161 offset:32768
	ds_read_b128 v[212:215], v161 offset:33792
	ds_read_b128 v[216:219], v161 offset:34816
	ds_read_b128 v[220:223], v161 offset:35840
	ds_read_b128 v[224:227], v161 offset:36864
	ds_read_b128 v[228:231], v161 offset:37888
	ds_read_b128 v[232:235], v161 offset:38912
	ds_read_b128 v[236:239], v161 offset:39936
	global_load_lds_dwordx4 v140, s[22:23]
	s_mov_b32 m0, s40
	s_nop 0
	global_load_lds_dwordx4 v144, s[22:23]
	s_waitcnt vmcnt(8)
	s_waitcnt lgkmcnt(0)
	s_barrier
	s_setprio 1
	v_mfma_f32_16x16x32_bf16 v[116:119], v[136:139], v[208:211], v[116:119]
	v_mfma_f32_16x16x32_bf16 v[112:115], v[180:183], v[208:211], v[112:115]
	v_mfma_f32_16x16x32_bf16 v[108:111], v[136:139], v[216:219], v[108:111]
	v_mfma_f32_16x16x32_bf16 v[104:107], v[180:183], v[216:219], v[104:107]
	v_mfma_f32_16x16x32_bf16 v[92:95], v[136:139], v[224:227], v[92:95]
	v_mfma_f32_16x16x32_bf16 v[88:91], v[180:183], v[224:227], v[88:91]
	v_mfma_f32_16x16x32_bf16 v[76:79], v[136:139], v[232:235], v[76:79]
	v_mfma_f32_16x16x32_bf16 v[72:75], v[180:183], v[232:235], v[72:75]
	v_mfma_f32_16x16x32_bf16 v[116:119], v[164:167], v[212:215], v[116:119]
	v_mfma_f32_16x16x32_bf16 v[112:115], v[184:187], v[212:215], v[112:115]
	v_mfma_f32_16x16x32_bf16 v[108:111], v[164:167], v[220:223], v[108:111]
	v_mfma_f32_16x16x32_bf16 v[104:107], v[184:187], v[220:223], v[104:107]
	v_mfma_f32_16x16x32_bf16 v[92:95], v[164:167], v[228:231], v[92:95]
	v_mfma_f32_16x16x32_bf16 v[88:91], v[184:187], v[228:231], v[88:91]
	v_mfma_f32_16x16x32_bf16 v[76:79], v[164:167], v[236:239], v[76:79]
	v_mfma_f32_16x16x32_bf16 v[72:75], v[184:187], v[236:239], v[72:75]
	v_mfma_f32_16x16x32_bf16 v[124:127], v[188:191], v[208:211], v[124:127]
	v_mfma_f32_16x16x32_bf16 v[120:123], v[200:203], v[208:211], v[120:123]
	v_mfma_f32_16x16x32_bf16 v[100:103], v[188:191], v[216:219], v[100:103]
	v_mfma_f32_16x16x32_bf16 v[96:99], v[200:203], v[216:219], v[96:99]
	v_mfma_f32_16x16x32_bf16 v[84:87], v[188:191], v[224:227], v[84:87]
	v_mfma_f32_16x16x32_bf16 v[80:83], v[200:203], v[224:227], v[80:83]
	v_mfma_f32_16x16x32_bf16 v[68:71], v[188:191], v[232:235], v[68:71]
	v_mfma_f32_16x16x32_bf16 v[64:67], v[200:203], v[232:235], v[64:67]
	v_mfma_f32_16x16x32_bf16 v[124:127], v[196:199], v[212:215], v[124:127]
	v_mfma_f32_16x16x32_bf16 v[120:123], v[204:207], v[212:215], v[120:123]
	v_mfma_f32_16x16x32_bf16 v[100:103], v[196:199], v[220:223], v[100:103]
	v_mfma_f32_16x16x32_bf16 v[96:99], v[204:207], v[220:223], v[96:99]
	v_mfma_f32_16x16x32_bf16 v[84:87], v[196:199], v[228:231], v[84:87]
	v_mfma_f32_16x16x32_bf16 v[80:83], v[204:207], v[228:231], v[80:83]
	v_mfma_f32_16x16x32_bf16 v[68:71], v[196:199], v[236:239], v[68:71]
	v_mfma_f32_16x16x32_bf16 v[64:67], v[204:207], v[236:239], v[64:67]
	s_barrier
	s_setprio 0
	s_add_i32 s22, s65, s37
	s_mov_b32 m0, s22
	ds_read_b128 v[208:211], v161 offset:49152
	ds_read_b128 v[212:215], v161 offset:50176
	ds_read_b128 v[216:219], v161 offset:51200
	ds_read_b128 v[220:223], v161 offset:52224
	ds_read_b128 v[224:227], v161 offset:53248
	ds_read_b128 v[228:231], v161 offset:54272
	ds_read_b128 v[232:235], v161 offset:55296
	ds_read_b128 v[236:239], v161 offset:56320
	global_load_lds_dwordx4 v142, s[98:99]
	s_add_i32 m0, s22, 0x2000
	s_add_u32 s2, s2, 0x40080
	s_addc_u32 s3, s3, 0
	s_add_i32 s22, s66, s37
	global_load_lds_dwordx4 v146, s[98:99]
	s_mov_b32 m0, s22
	s_nop 0
	global_load_lds_dwordx4 v142, s[2:3]
	s_add_i32 m0, s22, 0x2000
	s_nop 0
	global_load_lds_dwordx4 v146, s[2:3]
	s_mov_b32 m0, s43
	s_nop 0
	global_load_lds_dwordx4 v140, s[100:101]
	s_mov_b32 m0, s44
	s_nop 0
	global_load_lds_dwordx4 v144, s[100:101]
	s_waitcnt vmcnt(8)
	s_waitcnt lgkmcnt(0)
	s_barrier
	s_setprio 1
	v_mfma_f32_16x16x32_bf16 v[52:55], v[136:139], v[208:211], v[52:55]
	v_mfma_f32_16x16x32_bf16 v[48:51], v[180:183], v[208:211], v[48:51]
	v_mfma_f32_16x16x32_bf16 v[44:47], v[136:139], v[216:219], v[44:47]
	v_mfma_f32_16x16x32_bf16 v[40:43], v[180:183], v[216:219], v[40:43]
	v_mfma_f32_16x16x32_bf16 v[28:31], v[136:139], v[224:227], v[28:31]
	v_mfma_f32_16x16x32_bf16 v[24:27], v[180:183], v[224:227], v[24:27]
	v_mfma_f32_16x16x32_bf16 v[12:15], v[136:139], v[232:235], v[12:15]
	v_mfma_f32_16x16x32_bf16 v[8:11], v[180:183], v[232:235], v[8:11]
	v_mfma_f32_16x16x32_bf16 v[52:55], v[164:167], v[212:215], v[52:55]
	v_mfma_f32_16x16x32_bf16 v[48:51], v[184:187], v[212:215], v[48:51]
	v_mfma_f32_16x16x32_bf16 v[44:47], v[164:167], v[220:223], v[44:47]
	v_mfma_f32_16x16x32_bf16 v[40:43], v[184:187], v[220:223], v[40:43]
	v_mfma_f32_16x16x32_bf16 v[28:31], v[164:167], v[228:231], v[28:31]
	v_mfma_f32_16x16x32_bf16 v[24:27], v[184:187], v[228:231], v[24:27]
	v_mfma_f32_16x16x32_bf16 v[12:15], v[164:167], v[236:239], v[12:15]
	v_mfma_f32_16x16x32_bf16 v[8:11], v[184:187], v[236:239], v[8:11]
	v_mfma_f32_16x16x32_bf16 v[60:63], v[188:191], v[208:211], v[60:63]
	v_mfma_f32_16x16x32_bf16 v[56:59], v[200:203], v[208:211], v[56:59]
	v_mfma_f32_16x16x32_bf16 v[36:39], v[188:191], v[216:219], v[36:39]
	v_mfma_f32_16x16x32_bf16 v[32:35], v[200:203], v[216:219], v[32:35]
	v_mfma_f32_16x16x32_bf16 v[20:23], v[188:191], v[224:227], v[20:23]
	v_mfma_f32_16x16x32_bf16 v[16:19], v[200:203], v[224:227], v[16:19]
	v_mfma_f32_16x16x32_bf16 v[4:7], v[188:191], v[232:235], v[4:7]
	v_mfma_f32_16x16x32_bf16 v[0:3], v[200:203], v[232:235], v[0:3]
	v_mfma_f32_16x16x32_bf16 v[60:63], v[196:199], v[212:215], v[60:63]
	v_mfma_f32_16x16x32_bf16 v[56:59], v[204:207], v[212:215], v[56:59]
	v_mfma_f32_16x16x32_bf16 v[36:39], v[196:199], v[220:223], v[36:39]
	v_mfma_f32_16x16x32_bf16 v[32:35], v[204:207], v[220:223], v[32:35]
	v_mfma_f32_16x16x32_bf16 v[20:23], v[196:199], v[228:231], v[20:23]
	v_mfma_f32_16x16x32_bf16 v[16:19], v[204:207], v[228:231], v[16:19]
	v_mfma_f32_16x16x32_bf16 v[4:7], v[196:199], v[236:239], v[4:7]
	v_mfma_f32_16x16x32_bf16 v[0:3], v[204:207], v[236:239], v[0:3]
	s_barrier
	s_setprio 0
	s_add_i32 s64, s64, 2
	s_add_u32 s14, s14, 0x100
	s_addc_u32 s15, s15, 0
	s_add_u32 s58, s58, 0x100
	s_addc_u32 s59, s59, 0
	s_cmp_gt_u32 s64, 13
	s_cbranch_scc0 .LBB0_271

.LBB0_367:
	s_ashr_i32 s25, s24, 31
	s_lshl_b64 s[22:23], s[24:25], 19
	s_add_u32 s26, s84, s22
	s_addc_u32 s27, s85, s23
	s_and_b64 s[22:23], s[0:1], exec
	s_cselect_b32 s25, s27, s15
	s_cselect_b32 s50, s26, s14
	s_ashr_i32 s21, s20, 31
	s_lshl_b64 s[22:23], s[20:21], 19
	s_add_u32 s28, s30, s22
	s_addc_u32 s29, s31, s23
	s_and_b64 s[22:23], s[0:1], exec
	s_cselect_b32 s21, s29, s3
	s_cselect_b32 s51, s28, s2
	s_add_u32 s14, s14, 0x40080
	s_addc_u32 s15, s15, 0
	s_add_u32 s52, s2, 0x100
	s_addc_u32 s53, s3, 0
	s_mov_b32 s54, -2
	s_waitcnt vmcnt(0)
	ds_read_b128 v[158:161], v154
	ds_read_b128 v[162:165], v154 offset:1024
	ds_read_b128 v[166:169], v154 offset:2048
	ds_read_b128 v[182:185], v154 offset:3072
	ds_read_b128 v[186:189], v155
	ds_read_b128 v[190:193], v155 offset:1024
	ds_read_b128 v[196:199], v155 offset:2048
	ds_read_b128 v[200:203], v155 offset:3072
	s_add_u32 s2, s14, 0xfffc0080
	s_addc_u32 s3, s15, -1
	s_cmp_eq_u32 s54, 12
	s_cselect_b32 s23, s25, s3
	s_cselect_b32 s22, s50, s2
	s_cselect_b32 s3, s21, s53
	s_cselect_b32 s2, s51, s52
	s_add_i32 m0, s37, 0xc000
	ds_read_b128 v[204:207], v156
	ds_read_b128 v[208:211], v156 offset:1024
	ds_read_b128 v[212:215], v156 offset:2048
	ds_read_b128 v[216:219], v156 offset:3072
	ds_read_b128 v[220:223], v156 offset:4096
	ds_read_b128 v[224:227], v156 offset:5120
	ds_read_b128 v[228:231], v156 offset:6144
	ds_read_b128 v[232:235], v156 offset:7168
	global_load_lds_dwordx4 v128, s[14:15]
	s_add_i32 m0, s37, 0xe000
	s_nop 0
	global_load_lds_dwordx4 v130, s[14:15]
	s_waitcnt vmcnt(8)
	s_waitcnt lgkmcnt(0)
	s_barrier
	s_setprio 1
	v_mfma_f32_16x16x32_bf16 v[112:115], v[158:161], v[204:207], 0
	v_mfma_f32_16x16x32_bf16 v[108:111], v[166:169], v[204:207], 0
	v_mfma_f32_16x16x32_bf16 v[104:107], v[158:161], v[212:215], 0
	v_mfma_f32_16x16x32_bf16 v[100:103], v[166:169], v[212:215], 0
	v_mfma_f32_16x16x32_bf16 v[92:95], v[158:161], v[220:223], 0
	v_mfma_f32_16x16x32_bf16 v[84:87], v[166:169], v[220:223], 0
	v_mfma_f32_16x16x32_bf16 v[76:79], v[158:161], v[228:231], 0
	v_mfma_f32_16x16x32_bf16 v[68:71], v[166:169], v[228:231], 0
	v_mfma_f32_16x16x32_bf16 v[112:115], v[162:165], v[208:211], v[112:115]
	v_mfma_f32_16x16x32_bf16 v[108:111], v[182:185], v[208:211], v[108:111]
	v_mfma_f32_16x16x32_bf16 v[104:107], v[162:165], v[216:219], v[104:107]
	v_mfma_f32_16x16x32_bf16 v[100:103], v[182:185], v[216:219], v[100:103]
	v_mfma_f32_16x16x32_bf16 v[92:95], v[162:165], v[224:227], v[92:95]
	v_mfma_f32_16x16x32_bf16 v[84:87], v[182:185], v[224:227], v[84:87]
	v_mfma_f32_16x16x32_bf16 v[76:79], v[162:165], v[232:235], v[76:79]
	v_mfma_f32_16x16x32_bf16 v[68:71], v[182:185], v[232:235], v[68:71]
	v_mfma_f32_16x16x32_bf16 v[124:127], v[186:189], v[204:207], 0
	v_mfma_f32_16x16x32_bf16 v[120:123], v[196:199], v[204:207], 0
	v_mfma_f32_16x16x32_bf16 v[116:119], v[186:189], v[212:215], 0
	v_mfma_f32_16x16x32_bf16 v[96:99], v[196:199], v[212:215], 0
	v_mfma_f32_16x16x32_bf16 v[88:91], v[186:189], v[220:223], 0
	v_mfma_f32_16x16x32_bf16 v[80:83], v[196:199], v[220:223], 0
	v_mfma_f32_16x16x32_bf16 v[72:75], v[186:189], v[228:231], 0
	v_mfma_f32_16x16x32_bf16 v[64:67], v[196:199], v[228:231], 0
	v_mfma_f32_16x16x32_bf16 v[124:127], v[190:193], v[208:211], v[124:127]
	v_mfma_f32_16x16x32_bf16 v[120:123], v[200:203], v[208:211], v[120:123]
	v_mfma_f32_16x16x32_bf16 v[116:119], v[190:193], v[216:219], v[116:119]
	v_mfma_f32_16x16x32_bf16 v[96:99], v[200:203], v[216:219], v[96:99]
	v_mfma_f32_16x16x32_bf16 v[88:91], v[190:193], v[224:227], v[88:91]
	v_mfma_f32_16x16x32_bf16 v[80:83], v[200:203], v[224:227], v[80:83]
	v_mfma_f32_16x16x32_bf16 v[72:75], v[190:193], v[232:235], v[72:75]
	v_mfma_f32_16x16x32_bf16 v[64:67], v[200:203], v[232:235], v[64:67]
	s_barrier
	s_setprio 0
	s_add_i32 s55, s46, s34
	s_add_u32 s98, s2, s8
	s_addc_u32 s99, s3, s9
	s_mov_b32 m0, s55
	ds_read_b128 v[204:207], v156 offset:16384
	ds_read_b128 v[208:211], v156 offset:17408
	ds_read_b128 v[212:215], v156 offset:18432
	ds_read_b128 v[216:219], v156 offset:19456
	ds_read_b128 v[220:223], v156 offset:20480
	ds_read_b128 v[224:227], v156 offset:21504
	ds_read_b128 v[228:231], v156 offset:22528
	ds_read_b128 v[232:235], v156 offset:23552
	global_load_lds_dwordx4 v142, s[2:3]
	s_add_i32 m0, s55, 0x2000
	s_add_u32 s56, s2, 0x40000
	s_addc_u32 s57, s3, 0
	s_add_i32 s55, s47, s34
	global_load_lds_dwordx4 v146, s[2:3]
	s_mov_b32 m0, s55
	s_nop 0
	global_load_lds_dwordx4 v142, s[56:57]
	s_add_i32 m0, s55, 0x2000
	s_nop 0
	global_load_lds_dwordx4 v146, s[56:57]
	s_add_u32 s100, s22, s8
	s_addc_u32 s101, s23, s9
	s_mov_b32 m0, s37
	s_nop 0
	global_load_lds_dwordx4 v140, s[22:23]
	s_mov_b32 m0, s38
	s_nop 0
	global_load_lds_dwordx4 v144, s[22:23]
	s_waitcnt vmcnt(8)
	s_waitcnt lgkmcnt(0)
	s_barrier
	s_setprio 1
	v_mfma_f32_16x16x32_bf16 v[60:63], v[158:161], v[204:207], 0
	v_mfma_f32_16x16x32_bf16 v[52:55], v[166:169], v[204:207], 0
	v_mfma_f32_16x16x32_bf16 v[44:47], v[158:161], v[212:215], 0
	v_mfma_f32_16x16x32_bf16 v[36:39], v[166:169], v[212:215], 0
	v_mfma_f32_16x16x32_bf16 v[28:31], v[158:161], v[220:223], 0
	v_mfma_f32_16x16x32_bf16 v[20:23], v[166:169], v[220:223], 0
	v_mfma_f32_16x16x32_bf16 v[12:15], v[158:161], v[228:231], 0
	v_mfma_f32_16x16x32_bf16 v[4:7], v[166:169], v[228:231], 0
	v_mfma_f32_16x16x32_bf16 v[60:63], v[162:165], v[208:211], v[60:63]
	v_mfma_f32_16x16x32_bf16 v[52:55], v[182:185], v[208:211], v[52:55]
	v_mfma_f32_16x16x32_bf16 v[44:47], v[162:165], v[216:219], v[44:47]
	v_mfma_f32_16x16x32_bf16 v[36:39], v[182:185], v[216:219], v[36:39]
	v_mfma_f32_16x16x32_bf16 v[28:31], v[162:165], v[224:227], v[28:31]
	v_mfma_f32_16x16x32_bf16 v[20:23], v[182:185], v[224:227], v[20:23]
	v_mfma_f32_16x16x32_bf16 v[12:15], v[162:165], v[232:235], v[12:15]
	v_mfma_f32_16x16x32_bf16 v[4:7], v[182:185], v[232:235], v[4:7]
	v_mfma_f32_16x16x32_bf16 v[56:59], v[186:189], v[204:207], 0
	v_mfma_f32_16x16x32_bf16 v[48:51], v[196:199], v[204:207], 0
	v_mfma_f32_16x16x32_bf16 v[40:43], v[186:189], v[212:215], 0
	v_mfma_f32_16x16x32_bf16 v[32:35], v[196:199], v[212:215], 0
	v_mfma_f32_16x16x32_bf16 v[24:27], v[186:189], v[220:223], 0
	v_mfma_f32_16x16x32_bf16 v[16:19], v[196:199], v[220:223], 0
	v_mfma_f32_16x16x32_bf16 v[8:11], v[186:189], v[228:231], 0
	v_mfma_f32_16x16x32_bf16 v[0:3], v[196:199], v[228:231], 0
	v_mfma_f32_16x16x32_bf16 v[56:59], v[190:193], v[208:211], v[56:59]
	v_mfma_f32_16x16x32_bf16 v[48:51], v[200:203], v[208:211], v[48:51]
	v_mfma_f32_16x16x32_bf16 v[40:43], v[190:193], v[216:219], v[40:43]
	v_mfma_f32_16x16x32_bf16 v[32:35], v[200:203], v[216:219], v[32:35]
	v_mfma_f32_16x16x32_bf16 v[24:27], v[190:193], v[224:227], v[24:27]
	v_mfma_f32_16x16x32_bf16 v[16:19], v[200:203], v[224:227], v[16:19]
	v_mfma_f32_16x16x32_bf16 v[8:11], v[190:193], v[232:235], v[8:11]
	v_mfma_f32_16x16x32_bf16 v[0:3], v[200:203], v[232:235], v[0:3]
	s_barrier
	s_setprio 0
	s_add_i32 s55, 0, 0x18000
	s_add_i32 s56, 0, 0x1c000
	v_add_u32_e32 v182, s55, v139
	v_add_u32_e32 v200, s56, v139
	ds_read_b128 v[158:161], v182
	ds_read_b128 v[162:165], v182 offset:1024
	ds_read_b128 v[166:169], v182 offset:2048
	ds_read_b128 v[182:185], v182 offset:3072
	ds_read_b128 v[186:189], v200
	ds_read_b128 v[190:193], v200 offset:1024
	ds_read_b128 v[196:199], v200 offset:2048
	ds_read_b128 v[200:203], v200 offset:3072
	s_add_u32 s22, s22, 0x40000
	s_addc_u32 s23, s23, 0
	s_mov_b32 m0, s39
	ds_read_b128 v[204:207], v156 offset:32768
	ds_read_b128 v[208:211], v156 offset:33792
	ds_read_b128 v[212:215], v156 offset:34816
	ds_read_b128 v[216:219], v156 offset:35840
	ds_read_b128 v[220:223], v156 offset:36864
	ds_read_b128 v[224:227], v156 offset:37888
	ds_read_b128 v[228:231], v156 offset:38912
	ds_read_b128 v[232:235], v156 offset:39936
	global_load_lds_dwordx4 v140, s[22:23]
	s_mov_b32 m0, s40
	s_nop 0
	global_load_lds_dwordx4 v144, s[22:23]
	s_waitcnt vmcnt(8)
	s_waitcnt lgkmcnt(0)
	s_barrier
	s_setprio 1
	v_mfma_f32_16x16x32_bf16 v[112:115], v[158:161], v[204:207], v[112:115]
	v_mfma_f32_16x16x32_bf16 v[108:111], v[166:169], v[204:207], v[108:111]
	v_mfma_f32_16x16x32_bf16 v[104:107], v[158:161], v[212:215], v[104:107]
	v_mfma_f32_16x16x32_bf16 v[100:103], v[166:169], v[212:215], v[100:103]
	v_mfma_f32_16x16x32_bf16 v[92:95], v[158:161], v[220:223], v[92:95]
	v_mfma_f32_16x16x32_bf16 v[84:87], v[166:169], v[220:223], v[84:87]
	v_mfma_f32_16x16x32_bf16 v[76:79], v[158:161], v[228:231], v[76:79]
	v_mfma_f32_16x16x32_bf16 v[68:71], v[166:169], v[228:231], v[68:71]
	v_mfma_f32_16x16x32_bf16 v[112:115], v[162:165], v[208:211], v[112:115]
	v_mfma_f32_16x16x32_bf16 v[108:111], v[182:185], v[208:211], v[108:111]
	v_mfma_f32_16x16x32_bf16 v[104:107], v[162:165], v[216:219], v[104:107]
	v_mfma_f32_16x16x32_bf16 v[100:103], v[182:185], v[216:219], v[100:103]
	v_mfma_f32_16x16x32_bf16 v[92:95], v[162:165], v[224:227], v[92:95]
	v_mfma_f32_16x16x32_bf16 v[84:87], v[182:185], v[224:227], v[84:87]
	v_mfma_f32_16x16x32_bf16 v[76:79], v[162:165], v[232:235], v[76:79]
	v_mfma_f32_16x16x32_bf16 v[68:71], v[182:185], v[232:235], v[68:71]
	v_mfma_f32_16x16x32_bf16 v[124:127], v[186:189], v[204:207], v[124:127]
	v_mfma_f32_16x16x32_bf16 v[120:123], v[196:199], v[204:207], v[120:123]
	v_mfma_f32_16x16x32_bf16 v[116:119], v[186:189], v[212:215], v[116:119]
	v_mfma_f32_16x16x32_bf16 v[96:99], v[196:199], v[212:215], v[96:99]
	v_mfma_f32_16x16x32_bf16 v[88:91], v[186:189], v[220:223], v[88:91]
	v_mfma_f32_16x16x32_bf16 v[80:83], v[196:199], v[220:223], v[80:83]
	v_mfma_f32_16x16x32_bf16 v[72:75], v[186:189], v[228:231], v[72:75]
	v_mfma_f32_16x16x32_bf16 v[64:67], v[196:199], v[228:231], v[64:67]
	v_mfma_f32_16x16x32_bf16 v[124:127], v[190:193], v[208:211], v[124:127]
	v_mfma_f32_16x16x32_bf16 v[120:123], v[200:203], v[208:211], v[120:123]
	v_mfma_f32_16x16x32_bf16 v[116:119], v[190:193], v[216:219], v[116:119]
	v_mfma_f32_16x16x32_bf16 v[96:99], v[200:203], v[216:219], v[96:99]
	v_mfma_f32_16x16x32_bf16 v[88:91], v[190:193], v[224:227], v[88:91]
	v_mfma_f32_16x16x32_bf16 v[80:83], v[200:203], v[224:227], v[80:83]
	v_mfma_f32_16x16x32_bf16 v[72:75], v[190:193], v[232:235], v[72:75]
	v_mfma_f32_16x16x32_bf16 v[64:67], v[200:203], v[232:235], v[64:67]
	s_barrier
	s_setprio 0
	s_add_i32 s22, s55, s34
	s_mov_b32 m0, s22
	ds_read_b128 v[204:207], v156 offset:49152
	ds_read_b128 v[208:211], v156 offset:50176
	ds_read_b128 v[212:215], v156 offset:51200
	ds_read_b128 v[216:219], v156 offset:52224
	ds_read_b128 v[220:223], v156 offset:53248
	ds_read_b128 v[224:227], v156 offset:54272
	ds_read_b128 v[228:231], v156 offset:55296
	ds_read_b128 v[232:235], v156 offset:56320
	global_load_lds_dwordx4 v142, s[98:99]
	s_add_i32 m0, s22, 0x2000
	s_add_u32 s2, s2, 0x40080
	s_addc_u32 s3, s3, 0
	s_add_i32 s22, s56, s34
	global_load_lds_dwordx4 v146, s[98:99]
	s_mov_b32 m0, s22
	s_nop 0
	global_load_lds_dwordx4 v142, s[2:3]
	s_add_i32 m0, s22, 0x2000
	s_nop 0
	global_load_lds_dwordx4 v146, s[2:3]
	s_mov_b32 m0, s42
	s_nop 0
	global_load_lds_dwordx4 v140, s[100:101]
	s_mov_b32 m0, s43
	s_nop 0
	global_load_lds_dwordx4 v144, s[100:101]
	s_waitcnt vmcnt(8)
	s_waitcnt lgkmcnt(0)
	s_barrier
	s_setprio 1
	v_mfma_f32_16x16x32_bf16 v[60:63], v[158:161], v[204:207], v[60:63]
	v_mfma_f32_16x16x32_bf16 v[52:55], v[166:169], v[204:207], v[52:55]
	v_mfma_f32_16x16x32_bf16 v[44:47], v[158:161], v[212:215], v[44:47]
	v_mfma_f32_16x16x32_bf16 v[36:39], v[166:169], v[212:215], v[36:39]
	v_mfma_f32_16x16x32_bf16 v[28:31], v[158:161], v[220:223], v[28:31]
	v_mfma_f32_16x16x32_bf16 v[20:23], v[166:169], v[220:223], v[20:23]
	v_mfma_f32_16x16x32_bf16 v[12:15], v[158:161], v[228:231], v[12:15]
	v_mfma_f32_16x16x32_bf16 v[4:7], v[166:169], v[228:231], v[4:7]
	v_mfma_f32_16x16x32_bf16 v[60:63], v[162:165], v[208:211], v[60:63]
	v_mfma_f32_16x16x32_bf16 v[52:55], v[182:185], v[208:211], v[52:55]
	v_mfma_f32_16x16x32_bf16 v[44:47], v[162:165], v[216:219], v[44:47]
	v_mfma_f32_16x16x32_bf16 v[36:39], v[182:185], v[216:219], v[36:39]
	v_mfma_f32_16x16x32_bf16 v[28:31], v[162:165], v[224:227], v[28:31]
	v_mfma_f32_16x16x32_bf16 v[20:23], v[182:185], v[224:227], v[20:23]
	v_mfma_f32_16x16x32_bf16 v[12:15], v[162:165], v[232:235], v[12:15]
	v_mfma_f32_16x16x32_bf16 v[4:7], v[182:185], v[232:235], v[4:7]
	v_mfma_f32_16x16x32_bf16 v[56:59], v[186:189], v[204:207], v[56:59]
	v_mfma_f32_16x16x32_bf16 v[48:51], v[196:199], v[204:207], v[48:51]
	v_mfma_f32_16x16x32_bf16 v[40:43], v[186:189], v[212:215], v[40:43]
	v_mfma_f32_16x16x32_bf16 v[32:35], v[196:199], v[212:215], v[32:35]
	v_mfma_f32_16x16x32_bf16 v[24:27], v[186:189], v[220:223], v[24:27]
	v_mfma_f32_16x16x32_bf16 v[16:19], v[196:199], v[220:223], v[16:19]
	v_mfma_f32_16x16x32_bf16 v[8:11], v[186:189], v[228:231], v[8:11]
	v_mfma_f32_16x16x32_bf16 v[0:3], v[196:199], v[228:231], v[0:3]
	v_mfma_f32_16x16x32_bf16 v[56:59], v[190:193], v[208:211], v[56:59]
	v_mfma_f32_16x16x32_bf16 v[48:51], v[200:203], v[208:211], v[48:51]
	v_mfma_f32_16x16x32_bf16 v[40:43], v[190:193], v[216:219], v[40:43]
	v_mfma_f32_16x16x32_bf16 v[32:35], v[200:203], v[216:219], v[32:35]
	v_mfma_f32_16x16x32_bf16 v[24:27], v[190:193], v[224:227], v[24:27]
	v_mfma_f32_16x16x32_bf16 v[16:19], v[200:203], v[224:227], v[16:19]
	v_mfma_f32_16x16x32_bf16 v[8:11], v[190:193], v[232:235], v[8:11]
	v_mfma_f32_16x16x32_bf16 v[0:3], v[200:203], v[232:235], v[0:3]
	s_barrier
	s_setprio 0
	s_add_i32 s54, s54, 2
	s_add_u32 s14, s14, 0x100
	s_addc_u32 s15, s15, 0
	s_add_u32 s52, s52, 0x100
	s_addc_u32 s53, s53, 0
	s_cmp_gt_u32 s54, 13
	s_cbranch_scc1 .Lgemm_kdone_1
.LBB0_368:
	ds_read_b128 v[158:161], v154
	ds_read_b128 v[162:165], v154 offset:1024
	ds_read_b128 v[166:169], v154 offset:2048
	ds_read_b128 v[182:185], v154 offset:3072
	ds_read_b128 v[186:189], v155
	ds_read_b128 v[190:193], v155 offset:1024
	ds_read_b128 v[196:199], v155 offset:2048
	ds_read_b128 v[200:203], v155 offset:3072
	s_add_u32 s2, s14, 0xfffc0080
	s_addc_u32 s3, s15, -1
	s_cmp_eq_u32 s54, 12
	s_cselect_b32 s23, s25, s3
	s_cselect_b32 s22, s50, s2
	s_cselect_b32 s3, s21, s53
	s_cselect_b32 s2, s51, s52
	s_add_i32 m0, s37, 0xc000
	ds_read_b128 v[204:207], v156
	ds_read_b128 v[208:211], v156 offset:1024
	ds_read_b128 v[212:215], v156 offset:2048
	ds_read_b128 v[216:219], v156 offset:3072
	ds_read_b128 v[220:223], v156 offset:4096
	ds_read_b128 v[224:227], v156 offset:5120
	ds_read_b128 v[228:231], v156 offset:6144
	ds_read_b128 v[232:235], v156 offset:7168
	global_load_lds_dwordx4 v128, s[14:15]
	s_add_i32 m0, s37, 0xe000
	s_nop 0
	global_load_lds_dwordx4 v130, s[14:15]
	s_waitcnt vmcnt(8)
	s_waitcnt lgkmcnt(0)
	s_barrier
	s_setprio 1
	v_mfma_f32_16x16x32_bf16 v[112:115], v[158:161], v[204:207], v[112:115]
	v_mfma_f32_16x16x32_bf16 v[108:111], v[166:169], v[204:207], v[108:111]
	v_mfma_f32_16x16x32_bf16 v[104:107], v[158:161], v[212:215], v[104:107]
	v_mfma_f32_16x16x32_bf16 v[100:103], v[166:169], v[212:215], v[100:103]
	v_mfma_f32_16x16x32_bf16 v[92:95], v[158:161], v[220:223], v[92:95]
	v_mfma_f32_16x16x32_bf16 v[84:87], v[166:169], v[220:223], v[84:87]
	v_mfma_f32_16x16x32_bf16 v[76:79], v[158:161], v[228:231], v[76:79]
	v_mfma_f32_16x16x32_bf16 v[68:71], v[166:169], v[228:231], v[68:71]
	v_mfma_f32_16x16x32_bf16 v[112:115], v[162:165], v[208:211], v[112:115]
	v_mfma_f32_16x16x32_bf16 v[108:111], v[182:185], v[208:211], v[108:111]
	v_mfma_f32_16x16x32_bf16 v[104:107], v[162:165], v[216:219], v[104:107]
	v_mfma_f32_16x16x32_bf16 v[100:103], v[182:185], v[216:219], v[100:103]
	v_mfma_f32_16x16x32_bf16 v[92:95], v[162:165], v[224:227], v[92:95]
	v_mfma_f32_16x16x32_bf16 v[84:87], v[182:185], v[224:227], v[84:87]
	v_mfma_f32_16x16x32_bf16 v[76:79], v[162:165], v[232:235], v[76:79]
	v_mfma_f32_16x16x32_bf16 v[68:71], v[182:185], v[232:235], v[68:71]
	v_mfma_f32_16x16x32_bf16 v[124:127], v[186:189], v[204:207], v[124:127]
	v_mfma_f32_16x16x32_bf16 v[120:123], v[196:199], v[204:207], v[120:123]
	v_mfma_f32_16x16x32_bf16 v[116:119], v[186:189], v[212:215], v[116:119]
	v_mfma_f32_16x16x32_bf16 v[96:99], v[196:199], v[212:215], v[96:99]
	v_mfma_f32_16x16x32_bf16 v[88:91], v[186:189], v[220:223], v[88:91]
	v_mfma_f32_16x16x32_bf16 v[80:83], v[196:199], v[220:223], v[80:83]
	v_mfma_f32_16x16x32_bf16 v[72:75], v[186:189], v[228:231], v[72:75]
	v_mfma_f32_16x16x32_bf16 v[64:67], v[196:199], v[228:231], v[64:67]
	v_mfma_f32_16x16x32_bf16 v[124:127], v[190:193], v[208:211], v[124:127]
	v_mfma_f32_16x16x32_bf16 v[120:123], v[200:203], v[208:211], v[120:123]
	v_mfma_f32_16x16x32_bf16 v[116:119], v[190:193], v[216:219], v[116:119]
	v_mfma_f32_16x16x32_bf16 v[96:99], v[200:203], v[216:219], v[96:99]
	v_mfma_f32_16x16x32_bf16 v[88:91], v[190:193], v[224:227], v[88:91]
	v_mfma_f32_16x16x32_bf16 v[80:83], v[200:203], v[224:227], v[80:83]
	v_mfma_f32_16x16x32_bf16 v[72:75], v[190:193], v[232:235], v[72:75]
	v_mfma_f32_16x16x32_bf16 v[64:67], v[200:203], v[232:235], v[64:67]
	s_barrier
	s_setprio 0
	s_add_i32 s55, s46, s34
	s_add_u32 s98, s2, s8
	s_addc_u32 s99, s3, s9
	s_mov_b32 m0, s55
	ds_read_b128 v[204:207], v156 offset:16384
	ds_read_b128 v[208:211], v156 offset:17408
	ds_read_b128 v[212:215], v156 offset:18432
	ds_read_b128 v[216:219], v156 offset:19456
	ds_read_b128 v[220:223], v156 offset:20480
	ds_read_b128 v[224:227], v156 offset:21504
	ds_read_b128 v[228:231], v156 offset:22528
	ds_read_b128 v[232:235], v156 offset:23552
	global_load_lds_dwordx4 v142, s[2:3]
	s_add_i32 m0, s55, 0x2000
	s_add_u32 s56, s2, 0x40000
	s_addc_u32 s57, s3, 0
	s_add_i32 s55, s47, s34
	global_load_lds_dwordx4 v146, s[2:3]
	s_mov_b32 m0, s55
	s_nop 0
	global_load_lds_dwordx4 v142, s[56:57]
	s_add_i32 m0, s55, 0x2000
	s_nop 0
	global_load_lds_dwordx4 v146, s[56:57]
	s_add_u32 s100, s22, s8
	s_addc_u32 s101, s23, s9
	s_mov_b32 m0, s37
	s_nop 0
	global_load_lds_dwordx4 v140, s[22:23]
	s_mov_b32 m0, s38
	s_nop 0
	global_load_lds_dwordx4 v144, s[22:23]
	s_waitcnt vmcnt(8)
	s_waitcnt lgkmcnt(0)
	s_barrier
	s_setprio 1
	v_mfma_f32_16x16x32_bf16 v[60:63], v[158:161], v[204:207], v[60:63]
	v_mfma_f32_16x16x32_bf16 v[52:55], v[166:169], v[204:207], v[52:55]
	v_mfma_f32_16x16x32_bf16 v[44:47], v[158:161], v[212:215], v[44:47]
	v_mfma_f32_16x16x32_bf16 v[36:39], v[166:169], v[212:215], v[36:39]
	v_mfma_f32_16x16x32_bf16 v[28:31], v[158:161], v[220:223], v[28:31]
	v_mfma_f32_16x16x32_bf16 v[20:23], v[166:169], v[220:223], v[20:23]
	v_mfma_f32_16x16x32_bf16 v[12:15], v[158:161], v[228:231], v[12:15]
	v_mfma_f32_16x16x32_bf16 v[4:7], v[166:169], v[228:231], v[4:7]
	v_mfma_f32_16x16x32_bf16 v[60:63], v[162:165], v[208:211], v[60:63]
	v_mfma_f32_16x16x32_bf16 v[52:55], v[182:185], v[208:211], v[52:55]
	v_mfma_f32_16x16x32_bf16 v[44:47], v[162:165], v[216:219], v[44:47]
	v_mfma_f32_16x16x32_bf16 v[36:39], v[182:185], v[216:219], v[36:39]
	v_mfma_f32_16x16x32_bf16 v[28:31], v[162:165], v[224:227], v[28:31]
	v_mfma_f32_16x16x32_bf16 v[20:23], v[182:185], v[224:227], v[20:23]
	v_mfma_f32_16x16x32_bf16 v[12:15], v[162:165], v[232:235], v[12:15]
	v_mfma_f32_16x16x32_bf16 v[4:7], v[182:185], v[232:235], v[4:7]
	v_mfma_f32_16x16x32_bf16 v[56:59], v[186:189], v[204:207], v[56:59]
	v_mfma_f32_16x16x32_bf16 v[48:51], v[196:199], v[204:207], v[48:51]
	v_mfma_f32_16x16x32_bf16 v[40:43], v[186:189], v[212:215], v[40:43]
	v_mfma_f32_16x16x32_bf16 v[32:35], v[196:199], v[212:215], v[32:35]
	v_mfma_f32_16x16x32_bf16 v[24:27], v[186:189], v[220:223], v[24:27]
	v_mfma_f32_16x16x32_bf16 v[16:19], v[196:199], v[220:223], v[16:19]
	v_mfma_f32_16x16x32_bf16 v[8:11], v[186:189], v[228:231], v[8:11]
	v_mfma_f32_16x16x32_bf16 v[0:3], v[196:199], v[228:231], v[0:3]
	v_mfma_f32_16x16x32_bf16 v[56:59], v[190:193], v[208:211], v[56:59]
	v_mfma_f32_16x16x32_bf16 v[48:51], v[200:203], v[208:211], v[48:51]
	v_mfma_f32_16x16x32_bf16 v[40:43], v[190:193], v[216:219], v[40:43]
	v_mfma_f32_16x16x32_bf16 v[32:35], v[200:203], v[216:219], v[32:35]
	v_mfma_f32_16x16x32_bf16 v[24:27], v[190:193], v[224:227], v[24:27]
	v_mfma_f32_16x16x32_bf16 v[16:19], v[200:203], v[224:227], v[16:19]
	v_mfma_f32_16x16x32_bf16 v[8:11], v[190:193], v[232:235], v[8:11]
	v_mfma_f32_16x16x32_bf16 v[0:3], v[200:203], v[232:235], v[0:3]
	s_barrier
	s_setprio 0
	s_add_i32 s55, 0, 0x18000
	s_add_i32 s56, 0, 0x1c000
	v_add_u32_e32 v182, s55, v139
	v_add_u32_e32 v200, s56, v139
	ds_read_b128 v[158:161], v182
	ds_read_b128 v[162:165], v182 offset:1024
	ds_read_b128 v[166:169], v182 offset:2048
	ds_read_b128 v[182:185], v182 offset:3072
	ds_read_b128 v[186:189], v200
	ds_read_b128 v[190:193], v200 offset:1024
	ds_read_b128 v[196:199], v200 offset:2048
	ds_read_b128 v[200:203], v200 offset:3072
	s_add_u32 s22, s22, 0x40000
	s_addc_u32 s23, s23, 0
	s_mov_b32 m0, s39
	ds_read_b128 v[204:207], v156 offset:32768
	ds_read_b128 v[208:211], v156 offset:33792
	ds_read_b128 v[212:215], v156 offset:34816
	ds_read_b128 v[216:219], v156 offset:35840
	ds_read_b128 v[220:223], v156 offset:36864
	ds_read_b128 v[224:227], v156 offset:37888
	ds_read_b128 v[228:231], v156 offset:38912
	ds_read_b128 v[232:235], v156 offset:39936
	global_load_lds_dwordx4 v140, s[22:23]
	s_mov_b32 m0, s40
	s_nop 0
	global_load_lds_dwordx4 v144, s[22:23]
	s_waitcnt vmcnt(8)
	s_waitcnt lgkmcnt(0)
	s_barrier
	s_setprio 1
	v_mfma_f32_16x16x32_bf16 v[112:115], v[158:161], v[204:207], v[112:115]
	v_mfma_f32_16x16x32_bf16 v[108:111], v[166:169], v[204:207], v[108:111]
	v_mfma_f32_16x16x32_bf16 v[104:107], v[158:161], v[212:215], v[104:107]
	v_mfma_f32_16x16x32_bf16 v[100:103], v[166:169], v[212:215], v[100:103]
	v_mfma_f32_16x16x32_bf16 v[92:95], v[158:161], v[220:223], v[92:95]
	v_mfma_f32_16x16x32_bf16 v[84:87], v[166:169], v[220:223], v[84:87]
	v_mfma_f32_16x16x32_bf16 v[76:79], v[158:161], v[228:231], v[76:79]
	v_mfma_f32_16x16x32_bf16 v[68:71], v[166:169], v[228:231], v[68:71]
	v_mfma_f32_16x16x32_bf16 v[112:115], v[162:165], v[208:211], v[112:115]
	v_mfma_f32_16x16x32_bf16 v[108:111], v[182:185], v[208:211], v[108:111]
	v_mfma_f32_16x16x32_bf16 v[104:107], v[162:165], v[216:219], v[104:107]
	v_mfma_f32_16x16x32_bf16 v[100:103], v[182:185], v[216:219], v[100:103]
	v_mfma_f32_16x16x32_bf16 v[92:95], v[162:165], v[224:227], v[92:95]
	v_mfma_f32_16x16x32_bf16 v[84:87], v[182:185], v[224:227], v[84:87]
	v_mfma_f32_16x16x32_bf16 v[76:79], v[162:165], v[232:235], v[76:79]
	v_mfma_f32_16x16x32_bf16 v[68:71], v[182:185], v[232:235], v[68:71]
	v_mfma_f32_16x16x32_bf16 v[124:127], v[186:189], v[204:207], v[124:127]
	v_mfma_f32_16x16x32_bf16 v[120:123], v[196:199], v[204:207], v[120:123]
	v_mfma_f32_16x16x32_bf16 v[116:119], v[186:189], v[212:215], v[116:119]
	v_mfma_f32_16x16x32_bf16 v[96:99], v[196:199], v[212:215], v[96:99]
	v_mfma_f32_16x16x32_bf16 v[88:91], v[186:189], v[220:223], v[88:91]
	v_mfma_f32_16x16x32_bf16 v[80:83], v[196:199], v[220:223], v[80:83]
	v_mfma_f32_16x16x32_bf16 v[72:75], v[186:189], v[228:231], v[72:75]
	v_mfma_f32_16x16x32_bf16 v[64:67], v[196:199], v[228:231], v[64:67]
	v_mfma_f32_16x16x32_bf16 v[124:127], v[190:193], v[208:211], v[124:127]
	v_mfma_f32_16x16x32_bf16 v[120:123], v[200:203], v[208:211], v[120:123]
	v_mfma_f32_16x16x32_bf16 v[116:119], v[190:193], v[216:219], v[116:119]
	v_mfma_f32_16x16x32_bf16 v[96:99], v[200:203], v[216:219], v[96:99]
	v_mfma_f32_16x16x32_bf16 v[88:91], v[190:193], v[224:227], v[88:91]
	v_mfma_f32_16x16x32_bf16 v[80:83], v[200:203], v[224:227], v[80:83]
	v_mfma_f32_16x16x32_bf16 v[72:75], v[190:193], v[232:235], v[72:75]
	v_mfma_f32_16x16x32_bf16 v[64:67], v[200:203], v[232:235], v[64:67]
	s_barrier
	s_setprio 0
	s_add_i32 s22, s55, s34
	s_mov_b32 m0, s22
	ds_read_b128 v[204:207], v156 offset:49152
	ds_read_b128 v[208:211], v156 offset:50176
	ds_read_b128 v[212:215], v156 offset:51200
	ds_read_b128 v[216:219], v156 offset:52224
	ds_read_b128 v[220:223], v156 offset:53248
	ds_read_b128 v[224:227], v156 offset:54272
	ds_read_b128 v[228:231], v156 offset:55296
	ds_read_b128 v[232:235], v156 offset:56320
	global_load_lds_dwordx4 v142, s[98:99]
	s_add_i32 m0, s22, 0x2000
	s_add_u32 s2, s2, 0x40080
	s_addc_u32 s3, s3, 0
	s_add_i32 s22, s56, s34
	global_load_lds_dwordx4 v146, s[98:99]
	s_mov_b32 m0, s22
	s_nop 0
	global_load_lds_dwordx4 v142, s[2:3]
	s_add_i32 m0, s22, 0x2000
	s_nop 0
	global_load_lds_dwordx4 v146, s[2:3]
	s_mov_b32 m0, s42
	s_nop 0
	global_load_lds_dwordx4 v140, s[100:101]
	s_mov_b32 m0, s43
	s_nop 0
	global_load_lds_dwordx4 v144, s[100:101]
	s_waitcnt vmcnt(8)
	s_waitcnt lgkmcnt(0)
	s_barrier
	s_setprio 1
	v_mfma_f32_16x16x32_bf16 v[60:63], v[158:161], v[204:207], v[60:63]
	v_mfma_f32_16x16x32_bf16 v[52:55], v[166:169], v[204:207], v[52:55]
	v_mfma_f32_16x16x32_bf16 v[44:47], v[158:161], v[212:215], v[44:47]
	v_mfma_f32_16x16x32_bf16 v[36:39], v[166:169], v[212:215], v[36:39]
	v_mfma_f32_16x16x32_bf16 v[28:31], v[158:161], v[220:223], v[28:31]
	v_mfma_f32_16x16x32_bf16 v[20:23], v[166:169], v[220:223], v[20:23]
	v_mfma_f32_16x16x32_bf16 v[12:15], v[158:161], v[228:231], v[12:15]
	v_mfma_f32_16x16x32_bf16 v[4:7], v[166:169], v[228:231], v[4:7]
	v_mfma_f32_16x16x32_bf16 v[60:63], v[162:165], v[208:211], v[60:63]
	v_mfma_f32_16x16x32_bf16 v[52:55], v[182:185], v[208:211], v[52:55]
	v_mfma_f32_16x16x32_bf16 v[44:47], v[162:165], v[216:219], v[44:47]
	v_mfma_f32_16x16x32_bf16 v[36:39], v[182:185], v[216:219], v[36:39]
	v_mfma_f32_16x16x32_bf16 v[28:31], v[162:165], v[224:227], v[28:31]
	v_mfma_f32_16x16x32_bf16 v[20:23], v[182:185], v[224:227], v[20:23]
	v_mfma_f32_16x16x32_bf16 v[12:15], v[162:165], v[232:235], v[12:15]
	v_mfma_f32_16x16x32_bf16 v[4:7], v[182:185], v[232:235], v[4:7]
	v_mfma_f32_16x16x32_bf16 v[56:59], v[186:189], v[204:207], v[56:59]
	v_mfma_f32_16x16x32_bf16 v[48:51], v[196:199], v[204:207], v[48:51]
	v_mfma_f32_16x16x32_bf16 v[40:43], v[186:189], v[212:215], v[40:43]
	v_mfma_f32_16x16x32_bf16 v[32:35], v[196:199], v[212:215], v[32:35]
	v_mfma_f32_16x16x32_bf16 v[24:27], v[186:189], v[220:223], v[24:27]
	v_mfma_f32_16x16x32_bf16 v[16:19], v[196:199], v[220:223], v[16:19]
	v_mfma_f32_16x16x32_bf16 v[8:11], v[186:189], v[228:231], v[8:11]
	v_mfma_f32_16x16x32_bf16 v[0:3], v[196:199], v[228:231], v[0:3]
	v_mfma_f32_16x16x32_bf16 v[56:59], v[190:193], v[208:211], v[56:59]
	v_mfma_f32_16x16x32_bf16 v[48:51], v[200:203], v[208:211], v[48:51]
	v_mfma_f32_16x16x32_bf16 v[40:43], v[190:193], v[216:219], v[40:43]
	v_mfma_f32_16x16x32_bf16 v[32:35], v[200:203], v[216:219], v[32:35]
	v_mfma_f32_16x16x32_bf16 v[24:27], v[190:193], v[224:227], v[24:27]
	v_mfma_f32_16x16x32_bf16 v[16:19], v[200:203], v[224:227], v[16:19]
	v_mfma_f32_16x16x32_bf16 v[8:11], v[190:193], v[232:235], v[8:11]
	v_mfma_f32_16x16x32_bf16 v[0:3], v[200:203], v[232:235], v[0:3]
	s_barrier
	s_setprio 0
	s_add_i32 s54, s54, 2
	s_add_u32 s14, s14, 0x100
	s_addc_u32 s15, s15, 0
	s_add_u32 s52, s52, 0x100
	s_addc_u32 s53, s53, 0
	s_cmp_gt_u32 s54, 13
	s_cbranch_scc0 .LBB0_368

.LBB0_454:
	s_add_u32 s14, s14, 0xb0080
	s_addc_u32 s15, s15, 0
	s_add_u32 s65, s2, 0x100
	s_addc_u32 s66, s3, 0
	s_mov_b32 s67, -2
	s_waitcnt lgkmcnt(0)
	s_waitcnt vmcnt(0)
	ds_read_b128 v[128:131], v147
	ds_read_b128 v[132:135], v147 offset:1024
	ds_read_b128 v[136:139], v147 offset:2048
	ds_read_b128 v[164:167], v147 offset:3072
	ds_read_b128 v[188:191], v184
	ds_read_b128 v[196:199], v184 offset:1024
	ds_read_b128 v[200:203], v184 offset:2048
	ds_read_b128 v[204:207], v184 offset:3072
	s_add_u32 s2, s14, 0xfff50080
	s_addc_u32 s3, s15, -1
	s_cmp_eq_u32 s67, 40
	s_cselect_b32 s23, s1, s3
	s_cselect_b32 s22, s0, s2
	s_cselect_b32 s3, s31, s66
	s_cselect_b32 s2, s30, s65
	s_add_i32 m0, s37, 0xc000
	ds_read_b128 v[208:211], v185
	ds_read_b128 v[212:215], v185 offset:1024
	ds_read_b128 v[216:219], v185 offset:2048
	ds_read_b128 v[220:223], v185 offset:3072
	ds_read_b128 v[224:227], v185 offset:4096
	ds_read_b128 v[228:231], v185 offset:5120
	ds_read_b128 v[232:235], v185 offset:6144
	ds_read_b128 v[236:239], v185 offset:7168
	global_load_lds_dwordx4 v156, s[14:15]
	s_add_i32 m0, s37, 0xe000
	s_nop 0
	global_load_lds_dwordx4 v158, s[14:15]
	s_waitcnt vmcnt(8)
	s_waitcnt lgkmcnt(0)
	s_barrier
	s_setprio 1
	v_mfma_f32_16x16x32_bf16 v[124:127], v[128:131], v[208:211], 0
	v_mfma_f32_16x16x32_bf16 v[120:123], v[136:139], v[208:211], 0
	v_mfma_f32_16x16x32_bf16 v[108:111], v[128:131], v[216:219], 0
	v_mfma_f32_16x16x32_bf16 v[104:107], v[136:139], v[216:219], 0
	v_mfma_f32_16x16x32_bf16 v[92:95], v[128:131], v[224:227], 0
	v_mfma_f32_16x16x32_bf16 v[88:91], v[136:139], v[224:227], 0
	v_mfma_f32_16x16x32_bf16 v[76:79], v[128:131], v[232:235], 0
	v_mfma_f32_16x16x32_bf16 v[72:75], v[136:139], v[232:235], 0
	v_mfma_f32_16x16x32_bf16 v[124:127], v[132:135], v[212:215], v[124:127]
	v_mfma_f32_16x16x32_bf16 v[120:123], v[164:167], v[212:215], v[120:123]
	v_mfma_f32_16x16x32_bf16 v[108:111], v[132:135], v[220:223], v[108:111]
	v_mfma_f32_16x16x32_bf16 v[104:107], v[164:167], v[220:223], v[104:107]
	v_mfma_f32_16x16x32_bf16 v[92:95], v[132:135], v[228:231], v[92:95]
	v_mfma_f32_16x16x32_bf16 v[88:91], v[164:167], v[228:231], v[88:91]
	v_mfma_f32_16x16x32_bf16 v[76:79], v[132:135], v[236:239], v[76:79]
	v_mfma_f32_16x16x32_bf16 v[72:75], v[164:167], v[236:239], v[72:75]
	v_mfma_f32_16x16x32_bf16 v[116:119], v[188:191], v[208:211], 0
	v_mfma_f32_16x16x32_bf16 v[112:115], v[200:203], v[208:211], 0
	v_mfma_f32_16x16x32_bf16 v[100:103], v[188:191], v[216:219], 0
	v_mfma_f32_16x16x32_bf16 v[96:99], v[200:203], v[216:219], 0
	v_mfma_f32_16x16x32_bf16 v[84:87], v[188:191], v[224:227], 0
	v_mfma_f32_16x16x32_bf16 v[80:83], v[200:203], v[224:227], 0
	v_mfma_f32_16x16x32_bf16 v[68:71], v[188:191], v[232:235], 0
	v_mfma_f32_16x16x32_bf16 v[64:67], v[200:203], v[232:235], 0
	v_mfma_f32_16x16x32_bf16 v[116:119], v[196:199], v[212:215], v[116:119]
	v_mfma_f32_16x16x32_bf16 v[112:115], v[204:207], v[212:215], v[112:115]
	v_mfma_f32_16x16x32_bf16 v[100:103], v[196:199], v[220:223], v[100:103]
	v_mfma_f32_16x16x32_bf16 v[96:99], v[204:207], v[220:223], v[96:99]
	v_mfma_f32_16x16x32_bf16 v[84:87], v[196:199], v[228:231], v[84:87]
	v_mfma_f32_16x16x32_bf16 v[80:83], v[204:207], v[228:231], v[80:83]
	v_mfma_f32_16x16x32_bf16 v[68:71], v[196:199], v[236:239], v[68:71]
	v_mfma_f32_16x16x32_bf16 v[64:67], v[204:207], v[236:239], v[64:67]
	s_barrier
	s_setprio 0
	s_add_i32 s68, s51, s36
	s_add_u32 s98, s2, s26
	s_addc_u32 s99, s3, s27
	s_mov_b32 m0, s68
	ds_read_b128 v[208:211], v185 offset:16384
	ds_read_b128 v[212:215], v185 offset:17408
	ds_read_b128 v[216:219], v185 offset:18432
	ds_read_b128 v[220:223], v185 offset:19456
	ds_read_b128 v[224:227], v185 offset:20480
	ds_read_b128 v[228:231], v185 offset:21504
	ds_read_b128 v[232:235], v185 offset:22528
	ds_read_b128 v[236:239], v185 offset:23552
	global_load_lds_dwordx4 v150, s[2:3]
	s_add_i32 m0, s68, 0x2000
	s_add_u32 s68, s2, 0xb0000
	s_addc_u32 s69, s3, 0
	s_add_i32 s70, s52, s36
	global_load_lds_dwordx4 v154, s[2:3]
	s_mov_b32 m0, s70
	s_nop 0
	global_load_lds_dwordx4 v150, s[68:69]
	s_add_i32 m0, s70, 0x2000
	s_nop 0
	global_load_lds_dwordx4 v154, s[68:69]
	s_add_u32 s100, s22, s26
	s_addc_u32 s101, s23, s27
	s_mov_b32 m0, s37
	s_nop 0
	global_load_lds_dwordx4 v148, s[22:23]
	s_mov_b32 m0, s38
	s_nop 0
	global_load_lds_dwordx4 v152, s[22:23]
	s_waitcnt vmcnt(8)
	s_waitcnt lgkmcnt(0)
	s_barrier
	s_setprio 1
	v_mfma_f32_16x16x32_bf16 v[60:63], v[128:131], v[208:211], 0
	v_mfma_f32_16x16x32_bf16 v[56:59], v[136:139], v[208:211], 0
	v_mfma_f32_16x16x32_bf16 v[44:47], v[128:131], v[216:219], 0
	v_mfma_f32_16x16x32_bf16 v[40:43], v[136:139], v[216:219], 0
	v_mfma_f32_16x16x32_bf16 v[28:31], v[128:131], v[224:227], 0
	v_mfma_f32_16x16x32_bf16 v[24:27], v[136:139], v[224:227], 0
	v_mfma_f32_16x16x32_bf16 v[12:15], v[128:131], v[232:235], 0
	v_mfma_f32_16x16x32_bf16 v[8:11], v[136:139], v[232:235], 0
	v_mfma_f32_16x16x32_bf16 v[60:63], v[132:135], v[212:215], v[60:63]
	v_mfma_f32_16x16x32_bf16 v[56:59], v[164:167], v[212:215], v[56:59]
	v_mfma_f32_16x16x32_bf16 v[44:47], v[132:135], v[220:223], v[44:47]
	v_mfma_f32_16x16x32_bf16 v[40:43], v[164:167], v[220:223], v[40:43]
	v_mfma_f32_16x16x32_bf16 v[28:31], v[132:135], v[228:231], v[28:31]
	v_mfma_f32_16x16x32_bf16 v[24:27], v[164:167], v[228:231], v[24:27]
	v_mfma_f32_16x16x32_bf16 v[12:15], v[132:135], v[236:239], v[12:15]
	v_mfma_f32_16x16x32_bf16 v[8:11], v[164:167], v[236:239], v[8:11]
	v_mfma_f32_16x16x32_bf16 v[52:55], v[188:191], v[208:211], 0
	v_mfma_f32_16x16x32_bf16 v[48:51], v[200:203], v[208:211], 0
	v_mfma_f32_16x16x32_bf16 v[36:39], v[188:191], v[216:219], 0
	v_mfma_f32_16x16x32_bf16 v[32:35], v[200:203], v[216:219], 0
	v_mfma_f32_16x16x32_bf16 v[20:23], v[188:191], v[224:227], 0
	v_mfma_f32_16x16x32_bf16 v[16:19], v[200:203], v[224:227], 0
	v_mfma_f32_16x16x32_bf16 v[4:7], v[188:191], v[232:235], 0
	v_mfma_f32_16x16x32_bf16 v[0:3], v[200:203], v[232:235], 0
	v_mfma_f32_16x16x32_bf16 v[52:55], v[196:199], v[212:215], v[52:55]
	v_mfma_f32_16x16x32_bf16 v[48:51], v[204:207], v[212:215], v[48:51]
	v_mfma_f32_16x16x32_bf16 v[36:39], v[196:199], v[220:223], v[36:39]
	v_mfma_f32_16x16x32_bf16 v[32:35], v[204:207], v[220:223], v[32:35]
	v_mfma_f32_16x16x32_bf16 v[20:23], v[196:199], v[228:231], v[20:23]
	v_mfma_f32_16x16x32_bf16 v[16:19], v[204:207], v[228:231], v[16:19]
	v_mfma_f32_16x16x32_bf16 v[4:7], v[196:199], v[236:239], v[4:7]
	v_mfma_f32_16x16x32_bf16 v[0:3], v[204:207], v[236:239], v[0:3]
	s_barrier
	s_setprio 0
	s_add_i32 s68, 0, 0x18000
	s_add_i32 s69, 0, 0x1c000
	v_add_u32_e32 v164, s68, v141
	v_add_u32_e32 v187, s69, v141
	ds_read_b128 v[128:131], v164
	ds_read_b128 v[132:135], v164 offset:1024
	ds_read_b128 v[136:139], v164 offset:2048
	ds_read_b128 v[164:167], v164 offset:3072
	ds_read_b128 v[188:191], v187
	ds_read_b128 v[196:199], v187 offset:1024
	ds_read_b128 v[200:203], v187 offset:2048
	ds_read_b128 v[204:207], v187 offset:3072
	s_add_u32 s22, s22, 0xb0000
	s_addc_u32 s23, s23, 0
	s_mov_b32 m0, s39
	ds_read_b128 v[208:211], v185 offset:32768
	ds_read_b128 v[212:215], v185 offset:33792
	ds_read_b128 v[216:219], v185 offset:34816
	ds_read_b128 v[220:223], v185 offset:35840
	ds_read_b128 v[224:227], v185 offset:36864
	ds_read_b128 v[228:231], v185 offset:37888
	ds_read_b128 v[232:235], v185 offset:38912
	ds_read_b128 v[236:239], v185 offset:39936
	global_load_lds_dwordx4 v148, s[22:23]
	s_mov_b32 m0, s40
	s_nop 0
	global_load_lds_dwordx4 v152, s[22:23]
	s_waitcnt vmcnt(8)
	s_waitcnt lgkmcnt(0)
	s_barrier
	s_setprio 1
	v_mfma_f32_16x16x32_bf16 v[124:127], v[128:131], v[208:211], v[124:127]
	v_mfma_f32_16x16x32_bf16 v[120:123], v[136:139], v[208:211], v[120:123]
	v_mfma_f32_16x16x32_bf16 v[108:111], v[128:131], v[216:219], v[108:111]
	v_mfma_f32_16x16x32_bf16 v[104:107], v[136:139], v[216:219], v[104:107]
	v_mfma_f32_16x16x32_bf16 v[92:95], v[128:131], v[224:227], v[92:95]
	v_mfma_f32_16x16x32_bf16 v[88:91], v[136:139], v[224:227], v[88:91]
	v_mfma_f32_16x16x32_bf16 v[76:79], v[128:131], v[232:235], v[76:79]
	v_mfma_f32_16x16x32_bf16 v[72:75], v[136:139], v[232:235], v[72:75]
	v_mfma_f32_16x16x32_bf16 v[124:127], v[132:135], v[212:215], v[124:127]
	v_mfma_f32_16x16x32_bf16 v[120:123], v[164:167], v[212:215], v[120:123]
	v_mfma_f32_16x16x32_bf16 v[108:111], v[132:135], v[220:223], v[108:111]
	v_mfma_f32_16x16x32_bf16 v[104:107], v[164:167], v[220:223], v[104:107]
	v_mfma_f32_16x16x32_bf16 v[92:95], v[132:135], v[228:231], v[92:95]
	v_mfma_f32_16x16x32_bf16 v[88:91], v[164:167], v[228:231], v[88:91]
	v_mfma_f32_16x16x32_bf16 v[76:79], v[132:135], v[236:239], v[76:79]
	v_mfma_f32_16x16x32_bf16 v[72:75], v[164:167], v[236:239], v[72:75]
	v_mfma_f32_16x16x32_bf16 v[116:119], v[188:191], v[208:211], v[116:119]
	v_mfma_f32_16x16x32_bf16 v[112:115], v[200:203], v[208:211], v[112:115]
	v_mfma_f32_16x16x32_bf16 v[100:103], v[188:191], v[216:219], v[100:103]
	v_mfma_f32_16x16x32_bf16 v[96:99], v[200:203], v[216:219], v[96:99]
	v_mfma_f32_16x16x32_bf16 v[84:87], v[188:191], v[224:227], v[84:87]
	v_mfma_f32_16x16x32_bf16 v[80:83], v[200:203], v[224:227], v[80:83]
	v_mfma_f32_16x16x32_bf16 v[68:71], v[188:191], v[232:235], v[68:71]
	v_mfma_f32_16x16x32_bf16 v[64:67], v[200:203], v[232:235], v[64:67]
	v_mfma_f32_16x16x32_bf16 v[116:119], v[196:199], v[212:215], v[116:119]
	v_mfma_f32_16x16x32_bf16 v[112:115], v[204:207], v[212:215], v[112:115]
	v_mfma_f32_16x16x32_bf16 v[100:103], v[196:199], v[220:223], v[100:103]
	v_mfma_f32_16x16x32_bf16 v[96:99], v[204:207], v[220:223], v[96:99]
	v_mfma_f32_16x16x32_bf16 v[84:87], v[196:199], v[228:231], v[84:87]
	v_mfma_f32_16x16x32_bf16 v[80:83], v[204:207], v[228:231], v[80:83]
	v_mfma_f32_16x16x32_bf16 v[68:71], v[196:199], v[236:239], v[68:71]
	v_mfma_f32_16x16x32_bf16 v[64:67], v[204:207], v[236:239], v[64:67]
	s_barrier
	s_setprio 0
	s_add_i32 s22, s68, s36
	s_mov_b32 m0, s22
	ds_read_b128 v[208:211], v185 offset:49152
	ds_read_b128 v[212:215], v185 offset:50176
	ds_read_b128 v[216:219], v185 offset:51200
	ds_read_b128 v[220:223], v185 offset:52224
	ds_read_b128 v[224:227], v185 offset:53248
	ds_read_b128 v[228:231], v185 offset:54272
	ds_read_b128 v[232:235], v185 offset:55296
	ds_read_b128 v[236:239], v185 offset:56320
	global_load_lds_dwordx4 v150, s[98:99]
	s_add_i32 m0, s22, 0x2000
	s_add_u32 s2, s2, 0xb0080
	s_addc_u32 s3, s3, 0
	s_add_i32 s22, s69, s36
	global_load_lds_dwordx4 v154, s[98:99]
	s_mov_b32 m0, s22
	s_nop 0
	global_load_lds_dwordx4 v150, s[2:3]
	s_add_i32 m0, s22, 0x2000
	s_nop 0
	global_load_lds_dwordx4 v154, s[2:3]
	s_mov_b32 m0, s44
	s_nop 0
	global_load_lds_dwordx4 v148, s[100:101]
	s_mov_b32 m0, s45
	s_nop 0
	global_load_lds_dwordx4 v152, s[100:101]
	s_waitcnt vmcnt(8)
	s_waitcnt lgkmcnt(0)
	s_barrier
	s_setprio 1
	v_mfma_f32_16x16x32_bf16 v[60:63], v[128:131], v[208:211], v[60:63]
	v_mfma_f32_16x16x32_bf16 v[56:59], v[136:139], v[208:211], v[56:59]
	v_mfma_f32_16x16x32_bf16 v[44:47], v[128:131], v[216:219], v[44:47]
	v_mfma_f32_16x16x32_bf16 v[40:43], v[136:139], v[216:219], v[40:43]
	v_mfma_f32_16x16x32_bf16 v[28:31], v[128:131], v[224:227], v[28:31]
	v_mfma_f32_16x16x32_bf16 v[24:27], v[136:139], v[224:227], v[24:27]
	v_mfma_f32_16x16x32_bf16 v[12:15], v[128:131], v[232:235], v[12:15]
	v_mfma_f32_16x16x32_bf16 v[8:11], v[136:139], v[232:235], v[8:11]
	v_mfma_f32_16x16x32_bf16 v[60:63], v[132:135], v[212:215], v[60:63]
	v_mfma_f32_16x16x32_bf16 v[56:59], v[164:167], v[212:215], v[56:59]
	v_mfma_f32_16x16x32_bf16 v[44:47], v[132:135], v[220:223], v[44:47]
	v_mfma_f32_16x16x32_bf16 v[40:43], v[164:167], v[220:223], v[40:43]
	v_mfma_f32_16x16x32_bf16 v[28:31], v[132:135], v[228:231], v[28:31]
	v_mfma_f32_16x16x32_bf16 v[24:27], v[164:167], v[228:231], v[24:27]
	v_mfma_f32_16x16x32_bf16 v[12:15], v[132:135], v[236:239], v[12:15]
	v_mfma_f32_16x16x32_bf16 v[8:11], v[164:167], v[236:239], v[8:11]
	v_mfma_f32_16x16x32_bf16 v[52:55], v[188:191], v[208:211], v[52:55]
	v_mfma_f32_16x16x32_bf16 v[48:51], v[200:203], v[208:211], v[48:51]
	v_mfma_f32_16x16x32_bf16 v[36:39], v[188:191], v[216:219], v[36:39]
	v_mfma_f32_16x16x32_bf16 v[32:35], v[200:203], v[216:219], v[32:35]
	v_mfma_f32_16x16x32_bf16 v[20:23], v[188:191], v[224:227], v[20:23]
	v_mfma_f32_16x16x32_bf16 v[16:19], v[200:203], v[224:227], v[16:19]
	v_mfma_f32_16x16x32_bf16 v[4:7], v[188:191], v[232:235], v[4:7]
	v_mfma_f32_16x16x32_bf16 v[0:3], v[200:203], v[232:235], v[0:3]
	v_mfma_f32_16x16x32_bf16 v[52:55], v[196:199], v[212:215], v[52:55]
	v_mfma_f32_16x16x32_bf16 v[48:51], v[204:207], v[212:215], v[48:51]
	v_mfma_f32_16x16x32_bf16 v[36:39], v[196:199], v[220:223], v[36:39]
	v_mfma_f32_16x16x32_bf16 v[32:35], v[204:207], v[220:223], v[32:35]
	v_mfma_f32_16x16x32_bf16 v[20:23], v[196:199], v[228:231], v[20:23]
	v_mfma_f32_16x16x32_bf16 v[16:19], v[204:207], v[228:231], v[16:19]
	v_mfma_f32_16x16x32_bf16 v[4:7], v[196:199], v[236:239], v[4:7]
	v_mfma_f32_16x16x32_bf16 v[0:3], v[204:207], v[236:239], v[0:3]
	s_barrier
	s_setprio 0
	s_add_i32 s67, s67, 2
	s_add_u32 s14, s14, 0x100
	s_addc_u32 s15, s15, 0
	s_add_u32 s65, s65, 0x100
	s_addc_u32 s66, s66, 0
	s_cmp_gt_u32 s67, 41
	s_cbranch_scc1 .Lgemm_kdone_2
.LBB0_455:
	ds_read_b128 v[128:131], v147
	ds_read_b128 v[132:135], v147 offset:1024
	ds_read_b128 v[136:139], v147 offset:2048
	ds_read_b128 v[164:167], v147 offset:3072
	ds_read_b128 v[188:191], v184
	ds_read_b128 v[196:199], v184 offset:1024
	ds_read_b128 v[200:203], v184 offset:2048
	ds_read_b128 v[204:207], v184 offset:3072
	s_add_u32 s2, s14, 0xfff50080
	s_addc_u32 s3, s15, -1
	s_cmp_eq_u32 s67, 40
	s_cselect_b32 s23, s1, s3
	s_cselect_b32 s22, s0, s2
	s_cselect_b32 s3, s31, s66
	s_cselect_b32 s2, s30, s65
	s_add_i32 m0, s37, 0xc000
	ds_read_b128 v[208:211], v185
	ds_read_b128 v[212:215], v185 offset:1024
	ds_read_b128 v[216:219], v185 offset:2048
	ds_read_b128 v[220:223], v185 offset:3072
	ds_read_b128 v[224:227], v185 offset:4096
	ds_read_b128 v[228:231], v185 offset:5120
	ds_read_b128 v[232:235], v185 offset:6144
	ds_read_b128 v[236:239], v185 offset:7168
	global_load_lds_dwordx4 v156, s[14:15]
	s_add_i32 m0, s37, 0xe000
	s_nop 0
	global_load_lds_dwordx4 v158, s[14:15]
	s_waitcnt vmcnt(8)
	s_waitcnt lgkmcnt(0)
	s_barrier
	s_setprio 1
	v_mfma_f32_16x16x32_bf16 v[124:127], v[128:131], v[208:211], v[124:127]
	v_mfma_f32_16x16x32_bf16 v[120:123], v[136:139], v[208:211], v[120:123]
	v_mfma_f32_16x16x32_bf16 v[108:111], v[128:131], v[216:219], v[108:111]
	v_mfma_f32_16x16x32_bf16 v[104:107], v[136:139], v[216:219], v[104:107]
	v_mfma_f32_16x16x32_bf16 v[92:95], v[128:131], v[224:227], v[92:95]
	v_mfma_f32_16x16x32_bf16 v[88:91], v[136:139], v[224:227], v[88:91]
	v_mfma_f32_16x16x32_bf16 v[76:79], v[128:131], v[232:235], v[76:79]
	v_mfma_f32_16x16x32_bf16 v[72:75], v[136:139], v[232:235], v[72:75]
	v_mfma_f32_16x16x32_bf16 v[124:127], v[132:135], v[212:215], v[124:127]
	v_mfma_f32_16x16x32_bf16 v[120:123], v[164:167], v[212:215], v[120:123]
	v_mfma_f32_16x16x32_bf16 v[108:111], v[132:135], v[220:223], v[108:111]
	v_mfma_f32_16x16x32_bf16 v[104:107], v[164:167], v[220:223], v[104:107]
	v_mfma_f32_16x16x32_bf16 v[92:95], v[132:135], v[228:231], v[92:95]
	v_mfma_f32_16x16x32_bf16 v[88:91], v[164:167], v[228:231], v[88:91]
	v_mfma_f32_16x16x32_bf16 v[76:79], v[132:135], v[236:239], v[76:79]
	v_mfma_f32_16x16x32_bf16 v[72:75], v[164:167], v[236:239], v[72:75]
	v_mfma_f32_16x16x32_bf16 v[116:119], v[188:191], v[208:211], v[116:119]
	v_mfma_f32_16x16x32_bf16 v[112:115], v[200:203], v[208:211], v[112:115]
	v_mfma_f32_16x16x32_bf16 v[100:103], v[188:191], v[216:219], v[100:103]
	v_mfma_f32_16x16x32_bf16 v[96:99], v[200:203], v[216:219], v[96:99]
	v_mfma_f32_16x16x32_bf16 v[84:87], v[188:191], v[224:227], v[84:87]
	v_mfma_f32_16x16x32_bf16 v[80:83], v[200:203], v[224:227], v[80:83]
	v_mfma_f32_16x16x32_bf16 v[68:71], v[188:191], v[232:235], v[68:71]
	v_mfma_f32_16x16x32_bf16 v[64:67], v[200:203], v[232:235], v[64:67]
	v_mfma_f32_16x16x32_bf16 v[116:119], v[196:199], v[212:215], v[116:119]
	v_mfma_f32_16x16x32_bf16 v[112:115], v[204:207], v[212:215], v[112:115]
	v_mfma_f32_16x16x32_bf16 v[100:103], v[196:199], v[220:223], v[100:103]
	v_mfma_f32_16x16x32_bf16 v[96:99], v[204:207], v[220:223], v[96:99]
	v_mfma_f32_16x16x32_bf16 v[84:87], v[196:199], v[228:231], v[84:87]
	v_mfma_f32_16x16x32_bf16 v[80:83], v[204:207], v[228:231], v[80:83]
	v_mfma_f32_16x16x32_bf16 v[68:71], v[196:199], v[236:239], v[68:71]
	v_mfma_f32_16x16x32_bf16 v[64:67], v[204:207], v[236:239], v[64:67]
	s_barrier
	s_setprio 0
	s_add_i32 s68, s51, s36
	s_add_u32 s98, s2, s26
	s_addc_u32 s99, s3, s27
	s_mov_b32 m0, s68
	ds_read_b128 v[208:211], v185 offset:16384
	ds_read_b128 v[212:215], v185 offset:17408
	ds_read_b128 v[216:219], v185 offset:18432
	ds_read_b128 v[220:223], v185 offset:19456
	ds_read_b128 v[224:227], v185 offset:20480
	ds_read_b128 v[228:231], v185 offset:21504
	ds_read_b128 v[232:235], v185 offset:22528
	ds_read_b128 v[236:239], v185 offset:23552
	global_load_lds_dwordx4 v150, s[2:3]
	s_add_i32 m0, s68, 0x2000
	s_add_u32 s68, s2, 0xb0000
	s_addc_u32 s69, s3, 0
	s_add_i32 s70, s52, s36
	global_load_lds_dwordx4 v154, s[2:3]
	s_mov_b32 m0, s70
	s_nop 0
	global_load_lds_dwordx4 v150, s[68:69]
	s_add_i32 m0, s70, 0x2000
	s_nop 0
	global_load_lds_dwordx4 v154, s[68:69]
	s_add_u32 s100, s22, s26
	s_addc_u32 s101, s23, s27
	s_mov_b32 m0, s37
	s_nop 0
	global_load_lds_dwordx4 v148, s[22:23]
	s_mov_b32 m0, s38
	s_nop 0
	global_load_lds_dwordx4 v152, s[22:23]
	s_waitcnt vmcnt(8)
	s_waitcnt lgkmcnt(0)
	s_barrier
	s_setprio 1
	v_mfma_f32_16x16x32_bf16 v[60:63], v[128:131], v[208:211], v[60:63]
	v_mfma_f32_16x16x32_bf16 v[56:59], v[136:139], v[208:211], v[56:59]
	v_mfma_f32_16x16x32_bf16 v[44:47], v[128:131], v[216:219], v[44:47]
	v_mfma_f32_16x16x32_bf16 v[40:43], v[136:139], v[216:219], v[40:43]
	v_mfma_f32_16x16x32_bf16 v[28:31], v[128:131], v[224:227], v[28:31]
	v_mfma_f32_16x16x32_bf16 v[24:27], v[136:139], v[224:227], v[24:27]
	v_mfma_f32_16x16x32_bf16 v[12:15], v[128:131], v[232:235], v[12:15]
	v_mfma_f32_16x16x32_bf16 v[8:11], v[136:139], v[232:235], v[8:11]
	v_mfma_f32_16x16x32_bf16 v[60:63], v[132:135], v[212:215], v[60:63]
	v_mfma_f32_16x16x32_bf16 v[56:59], v[164:167], v[212:215], v[56:59]
	v_mfma_f32_16x16x32_bf16 v[44:47], v[132:135], v[220:223], v[44:47]
	v_mfma_f32_16x16x32_bf16 v[40:43], v[164:167], v[220:223], v[40:43]
	v_mfma_f32_16x16x32_bf16 v[28:31], v[132:135], v[228:231], v[28:31]
	v_mfma_f32_16x16x32_bf16 v[24:27], v[164:167], v[228:231], v[24:27]
	v_mfma_f32_16x16x32_bf16 v[12:15], v[132:135], v[236:239], v[12:15]
	v_mfma_f32_16x16x32_bf16 v[8:11], v[164:167], v[236:239], v[8:11]
	v_mfma_f32_16x16x32_bf16 v[52:55], v[188:191], v[208:211], v[52:55]
	v_mfma_f32_16x16x32_bf16 v[48:51], v[200:203], v[208:211], v[48:51]
	v_mfma_f32_16x16x32_bf16 v[36:39], v[188:191], v[216:219], v[36:39]
	v_mfma_f32_16x16x32_bf16 v[32:35], v[200:203], v[216:219], v[32:35]
	v_mfma_f32_16x16x32_bf16 v[20:23], v[188:191], v[224:227], v[20:23]
	v_mfma_f32_16x16x32_bf16 v[16:19], v[200:203], v[224:227], v[16:19]
	v_mfma_f32_16x16x32_bf16 v[4:7], v[188:191], v[232:235], v[4:7]
	v_mfma_f32_16x16x32_bf16 v[0:3], v[200:203], v[232:235], v[0:3]
	v_mfma_f32_16x16x32_bf16 v[52:55], v[196:199], v[212:215], v[52:55]
	v_mfma_f32_16x16x32_bf16 v[48:51], v[204:207], v[212:215], v[48:51]
	v_mfma_f32_16x16x32_bf16 v[36:39], v[196:199], v[220:223], v[36:39]
	v_mfma_f32_16x16x32_bf16 v[32:35], v[204:207], v[220:223], v[32:35]
	v_mfma_f32_16x16x32_bf16 v[20:23], v[196:199], v[228:231], v[20:23]
	v_mfma_f32_16x16x32_bf16 v[16:19], v[204:207], v[228:231], v[16:19]
	v_mfma_f32_16x16x32_bf16 v[4:7], v[196:199], v[236:239], v[4:7]
	v_mfma_f32_16x16x32_bf16 v[0:3], v[204:207], v[236:239], v[0:3]
	s_barrier
	s_setprio 0
	s_add_i32 s68, 0, 0x18000
	s_add_i32 s69, 0, 0x1c000
	v_add_u32_e32 v164, s68, v141
	v_add_u32_e32 v187, s69, v141
	ds_read_b128 v[128:131], v164
	ds_read_b128 v[132:135], v164 offset:1024
	ds_read_b128 v[136:139], v164 offset:2048
	ds_read_b128 v[164:167], v164 offset:3072
	ds_read_b128 v[188:191], v187
	ds_read_b128 v[196:199], v187 offset:1024
	ds_read_b128 v[200:203], v187 offset:2048
	ds_read_b128 v[204:207], v187 offset:3072
	s_add_u32 s22, s22, 0xb0000
	s_addc_u32 s23, s23, 0
	s_mov_b32 m0, s39
	ds_read_b128 v[208:211], v185 offset:32768
	ds_read_b128 v[212:215], v185 offset:33792
	ds_read_b128 v[216:219], v185 offset:34816
	ds_read_b128 v[220:223], v185 offset:35840
	ds_read_b128 v[224:227], v185 offset:36864
	ds_read_b128 v[228:231], v185 offset:37888
	ds_read_b128 v[232:235], v185 offset:38912
	ds_read_b128 v[236:239], v185 offset:39936
	global_load_lds_dwordx4 v148, s[22:23]
	s_mov_b32 m0, s40
	s_nop 0
	global_load_lds_dwordx4 v152, s[22:23]
	s_waitcnt vmcnt(8)
	s_waitcnt lgkmcnt(0)
	s_barrier
	s_setprio 1
	v_mfma_f32_16x16x32_bf16 v[124:127], v[128:131], v[208:211], v[124:127]
	v_mfma_f32_16x16x32_bf16 v[120:123], v[136:139], v[208:211], v[120:123]
	v_mfma_f32_16x16x32_bf16 v[108:111], v[128:131], v[216:219], v[108:111]
	v_mfma_f32_16x16x32_bf16 v[104:107], v[136:139], v[216:219], v[104:107]
	v_mfma_f32_16x16x32_bf16 v[92:95], v[128:131], v[224:227], v[92:95]
	v_mfma_f32_16x16x32_bf16 v[88:91], v[136:139], v[224:227], v[88:91]
	v_mfma_f32_16x16x32_bf16 v[76:79], v[128:131], v[232:235], v[76:79]
	v_mfma_f32_16x16x32_bf16 v[72:75], v[136:139], v[232:235], v[72:75]
	v_mfma_f32_16x16x32_bf16 v[124:127], v[132:135], v[212:215], v[124:127]
	v_mfma_f32_16x16x32_bf16 v[120:123], v[164:167], v[212:215], v[120:123]
	v_mfma_f32_16x16x32_bf16 v[108:111], v[132:135], v[220:223], v[108:111]
	v_mfma_f32_16x16x32_bf16 v[104:107], v[164:167], v[220:223], v[104:107]
	v_mfma_f32_16x16x32_bf16 v[92:95], v[132:135], v[228:231], v[92:95]
	v_mfma_f32_16x16x32_bf16 v[88:91], v[164:167], v[228:231], v[88:91]
	v_mfma_f32_16x16x32_bf16 v[76:79], v[132:135], v[236:239], v[76:79]
	v_mfma_f32_16x16x32_bf16 v[72:75], v[164:167], v[236:239], v[72:75]
	v_mfma_f32_16x16x32_bf16 v[116:119], v[188:191], v[208:211], v[116:119]
	v_mfma_f32_16x16x32_bf16 v[112:115], v[200:203], v[208:211], v[112:115]
	v_mfma_f32_16x16x32_bf16 v[100:103], v[188:191], v[216:219], v[100:103]
	v_mfma_f32_16x16x32_bf16 v[96:99], v[200:203], v[216:219], v[96:99]
	v_mfma_f32_16x16x32_bf16 v[84:87], v[188:191], v[224:227], v[84:87]
	v_mfma_f32_16x16x32_bf16 v[80:83], v[200:203], v[224:227], v[80:83]
	v_mfma_f32_16x16x32_bf16 v[68:71], v[188:191], v[232:235], v[68:71]
	v_mfma_f32_16x16x32_bf16 v[64:67], v[200:203], v[232:235], v[64:67]
	v_mfma_f32_16x16x32_bf16 v[116:119], v[196:199], v[212:215], v[116:119]
	v_mfma_f32_16x16x32_bf16 v[112:115], v[204:207], v[212:215], v[112:115]
	v_mfma_f32_16x16x32_bf16 v[100:103], v[196:199], v[220:223], v[100:103]
	v_mfma_f32_16x16x32_bf16 v[96:99], v[204:207], v[220:223], v[96:99]
	v_mfma_f32_16x16x32_bf16 v[84:87], v[196:199], v[228:231], v[84:87]
	v_mfma_f32_16x16x32_bf16 v[80:83], v[204:207], v[228:231], v[80:83]
	v_mfma_f32_16x16x32_bf16 v[68:71], v[196:199], v[236:239], v[68:71]
	v_mfma_f32_16x16x32_bf16 v[64:67], v[204:207], v[236:239], v[64:67]
	s_barrier
	s_setprio 0
	s_add_i32 s22, s68, s36
	s_mov_b32 m0, s22
	ds_read_b128 v[208:211], v185 offset:49152
	ds_read_b128 v[212:215], v185 offset:50176
	ds_read_b128 v[216:219], v185 offset:51200
	ds_read_b128 v[220:223], v185 offset:52224
	ds_read_b128 v[224:227], v185 offset:53248
	ds_read_b128 v[228:231], v185 offset:54272
	ds_read_b128 v[232:235], v185 offset:55296
	ds_read_b128 v[236:239], v185 offset:56320
	global_load_lds_dwordx4 v150, s[98:99]
	s_add_i32 m0, s22, 0x2000
	s_add_u32 s2, s2, 0xb0080
	s_addc_u32 s3, s3, 0
	s_add_i32 s22, s69, s36
	global_load_lds_dwordx4 v154, s[98:99]
	s_mov_b32 m0, s22
	s_nop 0
	global_load_lds_dwordx4 v150, s[2:3]
	s_add_i32 m0, s22, 0x2000
	s_nop 0
	global_load_lds_dwordx4 v154, s[2:3]
	s_mov_b32 m0, s44
	s_nop 0
	global_load_lds_dwordx4 v148, s[100:101]
	s_mov_b32 m0, s45
	s_nop 0
	global_load_lds_dwordx4 v152, s[100:101]
	s_waitcnt vmcnt(8)
	s_waitcnt lgkmcnt(0)
	s_barrier
	s_setprio 1
	v_mfma_f32_16x16x32_bf16 v[60:63], v[128:131], v[208:211], v[60:63]
	v_mfma_f32_16x16x32_bf16 v[56:59], v[136:139], v[208:211], v[56:59]
	v_mfma_f32_16x16x32_bf16 v[44:47], v[128:131], v[216:219], v[44:47]
	v_mfma_f32_16x16x32_bf16 v[40:43], v[136:139], v[216:219], v[40:43]
	v_mfma_f32_16x16x32_bf16 v[28:31], v[128:131], v[224:227], v[28:31]
	v_mfma_f32_16x16x32_bf16 v[24:27], v[136:139], v[224:227], v[24:27]
	v_mfma_f32_16x16x32_bf16 v[12:15], v[128:131], v[232:235], v[12:15]
	v_mfma_f32_16x16x32_bf16 v[8:11], v[136:139], v[232:235], v[8:11]
	v_mfma_f32_16x16x32_bf16 v[60:63], v[132:135], v[212:215], v[60:63]
	v_mfma_f32_16x16x32_bf16 v[56:59], v[164:167], v[212:215], v[56:59]
	v_mfma_f32_16x16x32_bf16 v[44:47], v[132:135], v[220:223], v[44:47]
	v_mfma_f32_16x16x32_bf16 v[40:43], v[164:167], v[220:223], v[40:43]
	v_mfma_f32_16x16x32_bf16 v[28:31], v[132:135], v[228:231], v[28:31]
	v_mfma_f32_16x16x32_bf16 v[24:27], v[164:167], v[228:231], v[24:27]
	v_mfma_f32_16x16x32_bf16 v[12:15], v[132:135], v[236:239], v[12:15]
	v_mfma_f32_16x16x32_bf16 v[8:11], v[164:167], v[236:239], v[8:11]
	v_mfma_f32_16x16x32_bf16 v[52:55], v[188:191], v[208:211], v[52:55]
	v_mfma_f32_16x16x32_bf16 v[48:51], v[200:203], v[208:211], v[48:51]
	v_mfma_f32_16x16x32_bf16 v[36:39], v[188:191], v[216:219], v[36:39]
	v_mfma_f32_16x16x32_bf16 v[32:35], v[200:203], v[216:219], v[32:35]
	v_mfma_f32_16x16x32_bf16 v[20:23], v[188:191], v[224:227], v[20:23]
	v_mfma_f32_16x16x32_bf16 v[16:19], v[200:203], v[224:227], v[16:19]
	v_mfma_f32_16x16x32_bf16 v[4:7], v[188:191], v[232:235], v[4:7]
	v_mfma_f32_16x16x32_bf16 v[0:3], v[200:203], v[232:235], v[0:3]
	v_mfma_f32_16x16x32_bf16 v[52:55], v[196:199], v[212:215], v[52:55]
	v_mfma_f32_16x16x32_bf16 v[48:51], v[204:207], v[212:215], v[48:51]
	v_mfma_f32_16x16x32_bf16 v[36:39], v[196:199], v[220:223], v[36:39]
	v_mfma_f32_16x16x32_bf16 v[32:35], v[204:207], v[220:223], v[32:35]
	v_mfma_f32_16x16x32_bf16 v[20:23], v[196:199], v[228:231], v[20:23]
	v_mfma_f32_16x16x32_bf16 v[16:19], v[204:207], v[228:231], v[16:19]
	v_mfma_f32_16x16x32_bf16 v[4:7], v[196:199], v[236:239], v[4:7]
	v_mfma_f32_16x16x32_bf16 v[0:3], v[204:207], v[236:239], v[0:3]
	s_barrier
	s_setprio 0
	s_add_i32 s67, s67, 2
	s_add_u32 s14, s14, 0x100
	s_addc_u32 s15, s15, 0
	s_add_u32 s65, s65, 0x100
	s_addc_u32 s66, s66, 0
	s_cmp_gt_u32 s67, 41
	s_cbranch_scc0 .LBB0_455

.LBB0_551:
	s_ashr_i32 s41, s40, 31
	s_lshl_b64 s[22:23], s[40:41], 19
	s_add_u32 s42, s84, s22
	s_addc_u32 s43, s85, s23
	s_and_b64 s[22:23], s[4:5], exec
	s_cselect_b32 s41, s43, s15
	s_cselect_b32 s69, s42, s14
	s_ashr_i32 s39, s38, 31
	s_lshl_b64 s[22:23], s[38:39], 19
	s_add_u32 s44, s34, s22
	s_addc_u32 s45, s35, s23
	s_and_b64 s[22:23], s[4:5], exec
	s_cselect_b32 s39, s45, s3
	s_cselect_b32 s70, s44, s2
	s_add_u32 s14, s14, 0x40080
	s_addc_u32 s15, s15, 0
	s_add_u32 s71, s2, 0x100
	s_addc_u32 s72, s3, 0
	s_mov_b32 s73, -2
	s_waitcnt vmcnt(0)
	ds_read_b128 v[156:159], v155
	ds_read_b128 v[160:163], v155 offset:1024
	ds_read_b128 v[184:187], v155 offset:2048
	ds_read_b128 v[188:191], v155 offset:3072
	ds_read_b128 v[196:199], v166
	ds_read_b128 v[200:203], v166 offset:1024
	ds_read_b128 v[204:207], v166 offset:2048
	ds_read_b128 v[208:211], v166 offset:3072
	s_add_u32 s2, s14, 0xfffc0080
	s_addc_u32 s3, s15, -1
	s_cmp_eq_u32 s73, 12
	s_cselect_b32 s23, s41, s3
	s_cselect_b32 s22, s69, s2
	s_cselect_b32 s3, s39, s72
	s_cselect_b32 s2, s70, s71
	s_add_i32 m0, s49, 0xc000
	ds_read_b128 v[212:215], v167
	ds_read_b128 v[216:219], v167 offset:1024
	ds_read_b128 v[220:223], v167 offset:2048
	ds_read_b128 v[224:227], v167 offset:3072
	ds_read_b128 v[228:231], v167 offset:4096
	ds_read_b128 v[232:235], v167 offset:5120
	ds_read_b128 v[236:239], v167 offset:6144
	ds_read_b128 v[240:243], v167 offset:7168
	global_load_lds_dwordx4 v130, s[14:15]
	s_add_i32 m0, s49, 0xe000
	s_nop 0
	global_load_lds_dwordx4 v132, s[14:15]
	s_waitcnt vmcnt(8)
	s_waitcnt lgkmcnt(0)
	s_barrier
	s_setprio 1
	v_mfma_f32_16x16x32_bf16 v[124:127], v[156:159], v[212:215], 0
	v_mfma_f32_16x16x32_bf16 v[120:123], v[184:187], v[212:215], 0
	v_mfma_f32_16x16x32_bf16 v[116:119], v[156:159], v[220:223], 0
	v_mfma_f32_16x16x32_bf16 v[112:115], v[184:187], v[220:223], 0
	v_mfma_f32_16x16x32_bf16 v[92:95], v[156:159], v[228:231], 0
	v_mfma_f32_16x16x32_bf16 v[88:91], v[184:187], v[228:231], 0
	v_mfma_f32_16x16x32_bf16 v[76:79], v[156:159], v[236:239], 0
	v_mfma_f32_16x16x32_bf16 v[72:75], v[184:187], v[236:239], 0
	v_mfma_f32_16x16x32_bf16 v[124:127], v[160:163], v[216:219], v[124:127]
	v_mfma_f32_16x16x32_bf16 v[120:123], v[188:191], v[216:219], v[120:123]
	v_mfma_f32_16x16x32_bf16 v[116:119], v[160:163], v[224:227], v[116:119]
	v_mfma_f32_16x16x32_bf16 v[112:115], v[188:191], v[224:227], v[112:115]
	v_mfma_f32_16x16x32_bf16 v[92:95], v[160:163], v[232:235], v[92:95]
	v_mfma_f32_16x16x32_bf16 v[88:91], v[188:191], v[232:235], v[88:91]
	v_mfma_f32_16x16x32_bf16 v[76:79], v[160:163], v[240:243], v[76:79]
	v_mfma_f32_16x16x32_bf16 v[72:75], v[188:191], v[240:243], v[72:75]
	v_mfma_f32_16x16x32_bf16 v[108:111], v[196:199], v[212:215], 0
	v_mfma_f32_16x16x32_bf16 v[104:107], v[204:207], v[212:215], 0
	v_mfma_f32_16x16x32_bf16 v[100:103], v[196:199], v[220:223], 0
	v_mfma_f32_16x16x32_bf16 v[96:99], v[204:207], v[220:223], 0
	v_mfma_f32_16x16x32_bf16 v[84:87], v[196:199], v[228:231], 0
	v_mfma_f32_16x16x32_bf16 v[80:83], v[204:207], v[228:231], 0
	v_mfma_f32_16x16x32_bf16 v[68:71], v[196:199], v[236:239], 0
	v_mfma_f32_16x16x32_bf16 v[64:67], v[204:207], v[236:239], 0
	v_mfma_f32_16x16x32_bf16 v[108:111], v[200:203], v[216:219], v[108:111]
	v_mfma_f32_16x16x32_bf16 v[104:107], v[208:211], v[216:219], v[104:107]
	v_mfma_f32_16x16x32_bf16 v[100:103], v[200:203], v[224:227], v[100:103]
	v_mfma_f32_16x16x32_bf16 v[96:99], v[208:211], v[224:227], v[96:99]
	v_mfma_f32_16x16x32_bf16 v[84:87], v[200:203], v[232:235], v[84:87]
	v_mfma_f32_16x16x32_bf16 v[80:83], v[208:211], v[232:235], v[80:83]
	v_mfma_f32_16x16x32_bf16 v[68:71], v[200:203], v[240:243], v[68:71]
	v_mfma_f32_16x16x32_bf16 v[64:67], v[208:211], v[240:243], v[64:67]
	s_barrier
	s_setprio 0
	s_add_i32 s74, s58, s46
	s_add_u32 s98, s2, s24
	s_addc_u32 s99, s3, s25
	s_mov_b32 m0, s74
	ds_read_b128 v[212:215], v167 offset:16384
	ds_read_b128 v[216:219], v167 offset:17408
	ds_read_b128 v[220:223], v167 offset:18432
	ds_read_b128 v[224:227], v167 offset:19456
	ds_read_b128 v[228:231], v167 offset:20480
	ds_read_b128 v[232:235], v167 offset:21504
	ds_read_b128 v[236:239], v167 offset:22528
	ds_read_b128 v[240:243], v167 offset:23552
	global_load_lds_dwordx4 v142, s[2:3]
	s_add_i32 m0, s74, 0x2000
	s_add_u32 s74, s2, 0x40000
	s_addc_u32 s75, s3, 0
	s_add_i32 s76, s59, s46
	global_load_lds_dwordx4 v146, s[2:3]
	s_mov_b32 m0, s76
	s_nop 0
	global_load_lds_dwordx4 v142, s[74:75]
	s_add_i32 m0, s76, 0x2000
	s_nop 0
	global_load_lds_dwordx4 v146, s[74:75]
	s_add_u32 s100, s22, s24
	s_addc_u32 s101, s23, s25
	s_mov_b32 m0, s49
	s_nop 0
	global_load_lds_dwordx4 v140, s[22:23]
	s_mov_b32 m0, s50
	s_nop 0
	global_load_lds_dwordx4 v144, s[22:23]
	s_waitcnt vmcnt(8)
	s_waitcnt lgkmcnt(0)
	s_barrier
	s_setprio 1
	v_mfma_f32_16x16x32_bf16 v[60:63], v[156:159], v[212:215], 0
	v_mfma_f32_16x16x32_bf16 v[56:59], v[184:187], v[212:215], 0
	v_mfma_f32_16x16x32_bf16 v[44:47], v[156:159], v[220:223], 0
	v_mfma_f32_16x16x32_bf16 v[40:43], v[184:187], v[220:223], 0
	v_mfma_f32_16x16x32_bf16 v[28:31], v[156:159], v[228:231], 0
	v_mfma_f32_16x16x32_bf16 v[24:27], v[184:187], v[228:231], 0
	v_mfma_f32_16x16x32_bf16 v[12:15], v[156:159], v[236:239], 0
	v_mfma_f32_16x16x32_bf16 v[8:11], v[184:187], v[236:239], 0
	v_mfma_f32_16x16x32_bf16 v[60:63], v[160:163], v[216:219], v[60:63]
	v_mfma_f32_16x16x32_bf16 v[56:59], v[188:191], v[216:219], v[56:59]
	v_mfma_f32_16x16x32_bf16 v[44:47], v[160:163], v[224:227], v[44:47]
	v_mfma_f32_16x16x32_bf16 v[40:43], v[188:191], v[224:227], v[40:43]
	v_mfma_f32_16x16x32_bf16 v[28:31], v[160:163], v[232:235], v[28:31]
	v_mfma_f32_16x16x32_bf16 v[24:27], v[188:191], v[232:235], v[24:27]
	v_mfma_f32_16x16x32_bf16 v[12:15], v[160:163], v[240:243], v[12:15]
	v_mfma_f32_16x16x32_bf16 v[8:11], v[188:191], v[240:243], v[8:11]
	v_mfma_f32_16x16x32_bf16 v[52:55], v[196:199], v[212:215], 0
	v_mfma_f32_16x16x32_bf16 v[48:51], v[204:207], v[212:215], 0
	v_mfma_f32_16x16x32_bf16 v[36:39], v[196:199], v[220:223], 0
	v_mfma_f32_16x16x32_bf16 v[32:35], v[204:207], v[220:223], 0
	v_mfma_f32_16x16x32_bf16 v[20:23], v[196:199], v[228:231], 0
	v_mfma_f32_16x16x32_bf16 v[16:19], v[204:207], v[228:231], 0
	v_mfma_f32_16x16x32_bf16 v[4:7], v[196:199], v[236:239], 0
	v_mfma_f32_16x16x32_bf16 v[0:3], v[204:207], v[236:239], 0
	v_mfma_f32_16x16x32_bf16 v[52:55], v[200:203], v[216:219], v[52:55]
	v_mfma_f32_16x16x32_bf16 v[48:51], v[208:211], v[216:219], v[48:51]
	v_mfma_f32_16x16x32_bf16 v[36:39], v[200:203], v[224:227], v[36:39]
	v_mfma_f32_16x16x32_bf16 v[32:35], v[208:211], v[224:227], v[32:35]
	v_mfma_f32_16x16x32_bf16 v[20:23], v[200:203], v[232:235], v[20:23]
	v_mfma_f32_16x16x32_bf16 v[16:19], v[208:211], v[232:235], v[16:19]
	v_mfma_f32_16x16x32_bf16 v[4:7], v[200:203], v[240:243], v[4:7]
	v_mfma_f32_16x16x32_bf16 v[0:3], v[208:211], v[240:243], v[0:3]
	s_barrier
	s_setprio 0
	s_add_i32 s74, 0, 0x18000
	v_add_u32_e32 v128, s74, v151
	s_add_i32 s75, 0, 0x1c000
	ds_read_b128 v[156:159], v128
	ds_read_b128 v[160:163], v128 offset:1024
	ds_read_b128 v[184:187], v128 offset:2048
	ds_read_b128 v[188:191], v128 offset:3072
	v_add_u32_e32 v128, s75, v151
	ds_read_b128 v[196:199], v128
	ds_read_b128 v[200:203], v128 offset:1024
	ds_read_b128 v[204:207], v128 offset:2048
	ds_read_b128 v[208:211], v128 offset:3072
	s_add_u32 s22, s22, 0x40000
	s_addc_u32 s23, s23, 0
	s_mov_b32 m0, s51
	ds_read_b128 v[212:215], v167 offset:32768
	ds_read_b128 v[216:219], v167 offset:33792
	ds_read_b128 v[220:223], v167 offset:34816
	ds_read_b128 v[224:227], v167 offset:35840
	ds_read_b128 v[228:231], v167 offset:36864
	ds_read_b128 v[232:235], v167 offset:37888
	ds_read_b128 v[236:239], v167 offset:38912
	ds_read_b128 v[240:243], v167 offset:39936
	global_load_lds_dwordx4 v140, s[22:23]
	s_mov_b32 m0, s52
	s_nop 0
	global_load_lds_dwordx4 v144, s[22:23]
	s_waitcnt vmcnt(8)
	s_waitcnt lgkmcnt(0)
	s_barrier
	s_setprio 1
	v_mfma_f32_16x16x32_bf16 v[124:127], v[156:159], v[212:215], v[124:127]
	v_mfma_f32_16x16x32_bf16 v[120:123], v[184:187], v[212:215], v[120:123]
	v_mfma_f32_16x16x32_bf16 v[116:119], v[156:159], v[220:223], v[116:119]
	v_mfma_f32_16x16x32_bf16 v[112:115], v[184:187], v[220:223], v[112:115]
	v_mfma_f32_16x16x32_bf16 v[92:95], v[156:159], v[228:231], v[92:95]
	v_mfma_f32_16x16x32_bf16 v[88:91], v[184:187], v[228:231], v[88:91]
	v_mfma_f32_16x16x32_bf16 v[76:79], v[156:159], v[236:239], v[76:79]
	v_mfma_f32_16x16x32_bf16 v[72:75], v[184:187], v[236:239], v[72:75]
	v_mfma_f32_16x16x32_bf16 v[124:127], v[160:163], v[216:219], v[124:127]
	v_mfma_f32_16x16x32_bf16 v[120:123], v[188:191], v[216:219], v[120:123]
	v_mfma_f32_16x16x32_bf16 v[116:119], v[160:163], v[224:227], v[116:119]
	v_mfma_f32_16x16x32_bf16 v[112:115], v[188:191], v[224:227], v[112:115]
	v_mfma_f32_16x16x32_bf16 v[92:95], v[160:163], v[232:235], v[92:95]
	v_mfma_f32_16x16x32_bf16 v[88:91], v[188:191], v[232:235], v[88:91]
	v_mfma_f32_16x16x32_bf16 v[76:79], v[160:163], v[240:243], v[76:79]
	v_mfma_f32_16x16x32_bf16 v[72:75], v[188:191], v[240:243], v[72:75]
	v_mfma_f32_16x16x32_bf16 v[108:111], v[196:199], v[212:215], v[108:111]
	v_mfma_f32_16x16x32_bf16 v[104:107], v[204:207], v[212:215], v[104:107]
	v_mfma_f32_16x16x32_bf16 v[100:103], v[196:199], v[220:223], v[100:103]
	v_mfma_f32_16x16x32_bf16 v[96:99], v[204:207], v[220:223], v[96:99]
	v_mfma_f32_16x16x32_bf16 v[84:87], v[196:199], v[228:231], v[84:87]
	v_mfma_f32_16x16x32_bf16 v[80:83], v[204:207], v[228:231], v[80:83]
	v_mfma_f32_16x16x32_bf16 v[68:71], v[196:199], v[236:239], v[68:71]
	v_mfma_f32_16x16x32_bf16 v[64:67], v[204:207], v[236:239], v[64:67]
	v_mfma_f32_16x16x32_bf16 v[108:111], v[200:203], v[216:219], v[108:111]
	v_mfma_f32_16x16x32_bf16 v[104:107], v[208:211], v[216:219], v[104:107]
	v_mfma_f32_16x16x32_bf16 v[100:103], v[200:203], v[224:227], v[100:103]
	v_mfma_f32_16x16x32_bf16 v[96:99], v[208:211], v[224:227], v[96:99]
	v_mfma_f32_16x16x32_bf16 v[84:87], v[200:203], v[232:235], v[84:87]
	v_mfma_f32_16x16x32_bf16 v[80:83], v[208:211], v[232:235], v[80:83]
	v_mfma_f32_16x16x32_bf16 v[68:71], v[200:203], v[240:243], v[68:71]
	v_mfma_f32_16x16x32_bf16 v[64:67], v[208:211], v[240:243], v[64:67]
	s_barrier
	s_setprio 0
	s_add_i32 s22, s74, s46
	s_mov_b32 m0, s22
	ds_read_b128 v[212:215], v167 offset:49152
	ds_read_b128 v[216:219], v167 offset:50176
	ds_read_b128 v[220:223], v167 offset:51200
	ds_read_b128 v[224:227], v167 offset:52224
	ds_read_b128 v[228:231], v167 offset:53248
	ds_read_b128 v[232:235], v167 offset:54272
	ds_read_b128 v[236:239], v167 offset:55296
	ds_read_b128 v[240:243], v167 offset:56320
	global_load_lds_dwordx4 v142, s[98:99]
	s_add_i32 m0, s22, 0x2000
	s_add_u32 s2, s2, 0x40080
	s_addc_u32 s3, s3, 0
	s_add_i32 s22, s75, s46
	global_load_lds_dwordx4 v146, s[98:99]
	s_mov_b32 m0, s22
	s_nop 0
	global_load_lds_dwordx4 v142, s[2:3]
	s_add_i32 m0, s22, 0x2000
	s_nop 0
	global_load_lds_dwordx4 v146, s[2:3]
	s_mov_b32 m0, s54
	s_nop 0
	global_load_lds_dwordx4 v140, s[100:101]
	s_mov_b32 m0, s55
	s_nop 0
	global_load_lds_dwordx4 v144, s[100:101]
	s_waitcnt vmcnt(8)
	s_waitcnt lgkmcnt(0)
	s_barrier
	s_setprio 1
	v_mfma_f32_16x16x32_bf16 v[60:63], v[156:159], v[212:215], v[60:63]
	v_mfma_f32_16x16x32_bf16 v[56:59], v[184:187], v[212:215], v[56:59]
	v_mfma_f32_16x16x32_bf16 v[44:47], v[156:159], v[220:223], v[44:47]
	v_mfma_f32_16x16x32_bf16 v[40:43], v[184:187], v[220:223], v[40:43]
	v_mfma_f32_16x16x32_bf16 v[28:31], v[156:159], v[228:231], v[28:31]
	v_mfma_f32_16x16x32_bf16 v[24:27], v[184:187], v[228:231], v[24:27]
	v_mfma_f32_16x16x32_bf16 v[12:15], v[156:159], v[236:239], v[12:15]
	v_mfma_f32_16x16x32_bf16 v[8:11], v[184:187], v[236:239], v[8:11]
	v_mfma_f32_16x16x32_bf16 v[60:63], v[160:163], v[216:219], v[60:63]
	v_mfma_f32_16x16x32_bf16 v[56:59], v[188:191], v[216:219], v[56:59]
	v_mfma_f32_16x16x32_bf16 v[44:47], v[160:163], v[224:227], v[44:47]
	v_mfma_f32_16x16x32_bf16 v[40:43], v[188:191], v[224:227], v[40:43]
	v_mfma_f32_16x16x32_bf16 v[28:31], v[160:163], v[232:235], v[28:31]
	v_mfma_f32_16x16x32_bf16 v[24:27], v[188:191], v[232:235], v[24:27]
	v_mfma_f32_16x16x32_bf16 v[12:15], v[160:163], v[240:243], v[12:15]
	v_mfma_f32_16x16x32_bf16 v[8:11], v[188:191], v[240:243], v[8:11]
	v_mfma_f32_16x16x32_bf16 v[52:55], v[196:199], v[212:215], v[52:55]
	v_mfma_f32_16x16x32_bf16 v[48:51], v[204:207], v[212:215], v[48:51]
	v_mfma_f32_16x16x32_bf16 v[36:39], v[196:199], v[220:223], v[36:39]
	v_mfma_f32_16x16x32_bf16 v[32:35], v[204:207], v[220:223], v[32:35]
	v_mfma_f32_16x16x32_bf16 v[20:23], v[196:199], v[228:231], v[20:23]
	v_mfma_f32_16x16x32_bf16 v[16:19], v[204:207], v[228:231], v[16:19]
	v_mfma_f32_16x16x32_bf16 v[4:7], v[196:199], v[236:239], v[4:7]
	v_mfma_f32_16x16x32_bf16 v[0:3], v[204:207], v[236:239], v[0:3]
	v_mfma_f32_16x16x32_bf16 v[52:55], v[200:203], v[216:219], v[52:55]
	v_mfma_f32_16x16x32_bf16 v[48:51], v[208:211], v[216:219], v[48:51]
	v_mfma_f32_16x16x32_bf16 v[36:39], v[200:203], v[224:227], v[36:39]
	v_mfma_f32_16x16x32_bf16 v[32:35], v[208:211], v[224:227], v[32:35]
	v_mfma_f32_16x16x32_bf16 v[20:23], v[200:203], v[232:235], v[20:23]
	v_mfma_f32_16x16x32_bf16 v[16:19], v[208:211], v[232:235], v[16:19]
	v_mfma_f32_16x16x32_bf16 v[4:7], v[200:203], v[240:243], v[4:7]
	v_mfma_f32_16x16x32_bf16 v[0:3], v[208:211], v[240:243], v[0:3]
	s_barrier
	s_setprio 0
	s_add_i32 s73, s73, 2
	s_add_u32 s14, s14, 0x100
	s_addc_u32 s15, s15, 0
	s_add_u32 s71, s71, 0x100
	s_addc_u32 s72, s72, 0
	s_cmp_gt_u32 s73, 13
	s_cbranch_scc1 .Lgemm_kdone_3
.LBB0_552:
	ds_read_b128 v[156:159], v155
	ds_read_b128 v[160:163], v155 offset:1024
	ds_read_b128 v[184:187], v155 offset:2048
	ds_read_b128 v[188:191], v155 offset:3072
	ds_read_b128 v[196:199], v166
	ds_read_b128 v[200:203], v166 offset:1024
	ds_read_b128 v[204:207], v166 offset:2048
	ds_read_b128 v[208:211], v166 offset:3072
	s_add_u32 s2, s14, 0xfffc0080
	s_addc_u32 s3, s15, -1
	s_cmp_eq_u32 s73, 12
	s_cselect_b32 s23, s41, s3
	s_cselect_b32 s22, s69, s2
	s_cselect_b32 s3, s39, s72
	s_cselect_b32 s2, s70, s71
	s_add_i32 m0, s49, 0xc000
	ds_read_b128 v[212:215], v167
	ds_read_b128 v[216:219], v167 offset:1024
	ds_read_b128 v[220:223], v167 offset:2048
	ds_read_b128 v[224:227], v167 offset:3072
	ds_read_b128 v[228:231], v167 offset:4096
	ds_read_b128 v[232:235], v167 offset:5120
	ds_read_b128 v[236:239], v167 offset:6144
	ds_read_b128 v[240:243], v167 offset:7168
	global_load_lds_dwordx4 v130, s[14:15]
	s_add_i32 m0, s49, 0xe000
	s_nop 0
	global_load_lds_dwordx4 v132, s[14:15]
	s_waitcnt vmcnt(8)
	s_waitcnt lgkmcnt(0)
	s_barrier
	s_setprio 1
	v_mfma_f32_16x16x32_bf16 v[124:127], v[156:159], v[212:215], v[124:127]
	v_mfma_f32_16x16x32_bf16 v[120:123], v[184:187], v[212:215], v[120:123]
	v_mfma_f32_16x16x32_bf16 v[116:119], v[156:159], v[220:223], v[116:119]
	v_mfma_f32_16x16x32_bf16 v[112:115], v[184:187], v[220:223], v[112:115]
	v_mfma_f32_16x16x32_bf16 v[92:95], v[156:159], v[228:231], v[92:95]
	v_mfma_f32_16x16x32_bf16 v[88:91], v[184:187], v[228:231], v[88:91]
	v_mfma_f32_16x16x32_bf16 v[76:79], v[156:159], v[236:239], v[76:79]
	v_mfma_f32_16x16x32_bf16 v[72:75], v[184:187], v[236:239], v[72:75]
	v_mfma_f32_16x16x32_bf16 v[124:127], v[160:163], v[216:219], v[124:127]
	v_mfma_f32_16x16x32_bf16 v[120:123], v[188:191], v[216:219], v[120:123]
	v_mfma_f32_16x16x32_bf16 v[116:119], v[160:163], v[224:227], v[116:119]
	v_mfma_f32_16x16x32_bf16 v[112:115], v[188:191], v[224:227], v[112:115]
	v_mfma_f32_16x16x32_bf16 v[92:95], v[160:163], v[232:235], v[92:95]
	v_mfma_f32_16x16x32_bf16 v[88:91], v[188:191], v[232:235], v[88:91]
	v_mfma_f32_16x16x32_bf16 v[76:79], v[160:163], v[240:243], v[76:79]
	v_mfma_f32_16x16x32_bf16 v[72:75], v[188:191], v[240:243], v[72:75]
	v_mfma_f32_16x16x32_bf16 v[108:111], v[196:199], v[212:215], v[108:111]
	v_mfma_f32_16x16x32_bf16 v[104:107], v[204:207], v[212:215], v[104:107]
	v_mfma_f32_16x16x32_bf16 v[100:103], v[196:199], v[220:223], v[100:103]
	v_mfma_f32_16x16x32_bf16 v[96:99], v[204:207], v[220:223], v[96:99]
	v_mfma_f32_16x16x32_bf16 v[84:87], v[196:199], v[228:231], v[84:87]
	v_mfma_f32_16x16x32_bf16 v[80:83], v[204:207], v[228:231], v[80:83]
	v_mfma_f32_16x16x32_bf16 v[68:71], v[196:199], v[236:239], v[68:71]
	v_mfma_f32_16x16x32_bf16 v[64:67], v[204:207], v[236:239], v[64:67]
	v_mfma_f32_16x16x32_bf16 v[108:111], v[200:203], v[216:219], v[108:111]
	v_mfma_f32_16x16x32_bf16 v[104:107], v[208:211], v[216:219], v[104:107]
	v_mfma_f32_16x16x32_bf16 v[100:103], v[200:203], v[224:227], v[100:103]
	v_mfma_f32_16x16x32_bf16 v[96:99], v[208:211], v[224:227], v[96:99]
	v_mfma_f32_16x16x32_bf16 v[84:87], v[200:203], v[232:235], v[84:87]
	v_mfma_f32_16x16x32_bf16 v[80:83], v[208:211], v[232:235], v[80:83]
	v_mfma_f32_16x16x32_bf16 v[68:71], v[200:203], v[240:243], v[68:71]
	v_mfma_f32_16x16x32_bf16 v[64:67], v[208:211], v[240:243], v[64:67]
	s_barrier
	s_setprio 0
	s_add_i32 s74, s58, s46
	s_add_u32 s98, s2, s24
	s_addc_u32 s99, s3, s25
	s_mov_b32 m0, s74
	ds_read_b128 v[212:215], v167 offset:16384
	ds_read_b128 v[216:219], v167 offset:17408
	ds_read_b128 v[220:223], v167 offset:18432
	ds_read_b128 v[224:227], v167 offset:19456
	ds_read_b128 v[228:231], v167 offset:20480
	ds_read_b128 v[232:235], v167 offset:21504
	ds_read_b128 v[236:239], v167 offset:22528
	ds_read_b128 v[240:243], v167 offset:23552
	global_load_lds_dwordx4 v142, s[2:3]
	s_add_i32 m0, s74, 0x2000
	s_add_u32 s74, s2, 0x40000
	s_addc_u32 s75, s3, 0
	s_add_i32 s76, s59, s46
	global_load_lds_dwordx4 v146, s[2:3]
	s_mov_b32 m0, s76
	s_nop 0
	global_load_lds_dwordx4 v142, s[74:75]
	s_add_i32 m0, s76, 0x2000
	s_nop 0
	global_load_lds_dwordx4 v146, s[74:75]
	s_add_u32 s100, s22, s24
	s_addc_u32 s101, s23, s25
	s_mov_b32 m0, s49
	s_nop 0
	global_load_lds_dwordx4 v140, s[22:23]
	s_mov_b32 m0, s50
	s_nop 0
	global_load_lds_dwordx4 v144, s[22:23]
	s_waitcnt vmcnt(8)
	s_waitcnt lgkmcnt(0)
	s_barrier
	s_setprio 1
	v_mfma_f32_16x16x32_bf16 v[60:63], v[156:159], v[212:215], v[60:63]
	v_mfma_f32_16x16x32_bf16 v[56:59], v[184:187], v[212:215], v[56:59]
	v_mfma_f32_16x16x32_bf16 v[44:47], v[156:159], v[220:223], v[44:47]
	v_mfma_f32_16x16x32_bf16 v[40:43], v[184:187], v[220:223], v[40:43]
	v_mfma_f32_16x16x32_bf16 v[28:31], v[156:159], v[228:231], v[28:31]
	v_mfma_f32_16x16x32_bf16 v[24:27], v[184:187], v[228:231], v[24:27]
	v_mfma_f32_16x16x32_bf16 v[12:15], v[156:159], v[236:239], v[12:15]
	v_mfma_f32_16x16x32_bf16 v[8:11], v[184:187], v[236:239], v[8:11]
	v_mfma_f32_16x16x32_bf16 v[60:63], v[160:163], v[216:219], v[60:63]
	v_mfma_f32_16x16x32_bf16 v[56:59], v[188:191], v[216:219], v[56:59]
	v_mfma_f32_16x16x32_bf16 v[44:47], v[160:163], v[224:227], v[44:47]
	v_mfma_f32_16x16x32_bf16 v[40:43], v[188:191], v[224:227], v[40:43]
	v_mfma_f32_16x16x32_bf16 v[28:31], v[160:163], v[232:235], v[28:31]
	v_mfma_f32_16x16x32_bf16 v[24:27], v[188:191], v[232:235], v[24:27]
	v_mfma_f32_16x16x32_bf16 v[12:15], v[160:163], v[240:243], v[12:15]
	v_mfma_f32_16x16x32_bf16 v[8:11], v[188:191], v[240:243], v[8:11]
	v_mfma_f32_16x16x32_bf16 v[52:55], v[196:199], v[212:215], v[52:55]
	v_mfma_f32_16x16x32_bf16 v[48:51], v[204:207], v[212:215], v[48:51]
	v_mfma_f32_16x16x32_bf16 v[36:39], v[196:199], v[220:223], v[36:39]
	v_mfma_f32_16x16x32_bf16 v[32:35], v[204:207], v[220:223], v[32:35]
	v_mfma_f32_16x16x32_bf16 v[20:23], v[196:199], v[228:231], v[20:23]
	v_mfma_f32_16x16x32_bf16 v[16:19], v[204:207], v[228:231], v[16:19]
	v_mfma_f32_16x16x32_bf16 v[4:7], v[196:199], v[236:239], v[4:7]
	v_mfma_f32_16x16x32_bf16 v[0:3], v[204:207], v[236:239], v[0:3]
	v_mfma_f32_16x16x32_bf16 v[52:55], v[200:203], v[216:219], v[52:55]
	v_mfma_f32_16x16x32_bf16 v[48:51], v[208:211], v[216:219], v[48:51]
	v_mfma_f32_16x16x32_bf16 v[36:39], v[200:203], v[224:227], v[36:39]
	v_mfma_f32_16x16x32_bf16 v[32:35], v[208:211], v[224:227], v[32:35]
	v_mfma_f32_16x16x32_bf16 v[20:23], v[200:203], v[232:235], v[20:23]
	v_mfma_f32_16x16x32_bf16 v[16:19], v[208:211], v[232:235], v[16:19]
	v_mfma_f32_16x16x32_bf16 v[4:7], v[200:203], v[240:243], v[4:7]
	v_mfma_f32_16x16x32_bf16 v[0:3], v[208:211], v[240:243], v[0:3]
	s_barrier
	s_setprio 0
	s_add_i32 s74, 0, 0x18000
	v_add_u32_e32 v128, s74, v151
	s_add_i32 s75, 0, 0x1c000
	ds_read_b128 v[156:159], v128
	ds_read_b128 v[160:163], v128 offset:1024
	ds_read_b128 v[184:187], v128 offset:2048
	ds_read_b128 v[188:191], v128 offset:3072
	v_add_u32_e32 v128, s75, v151
	ds_read_b128 v[196:199], v128
	ds_read_b128 v[200:203], v128 offset:1024
	ds_read_b128 v[204:207], v128 offset:2048
	ds_read_b128 v[208:211], v128 offset:3072
	s_add_u32 s22, s22, 0x40000
	s_addc_u32 s23, s23, 0
	s_mov_b32 m0, s51
	ds_read_b128 v[212:215], v167 offset:32768
	ds_read_b128 v[216:219], v167 offset:33792
	ds_read_b128 v[220:223], v167 offset:34816
	ds_read_b128 v[224:227], v167 offset:35840
	ds_read_b128 v[228:231], v167 offset:36864
	ds_read_b128 v[232:235], v167 offset:37888
	ds_read_b128 v[236:239], v167 offset:38912
	ds_read_b128 v[240:243], v167 offset:39936
	global_load_lds_dwordx4 v140, s[22:23]
	s_mov_b32 m0, s52
	s_nop 0
	global_load_lds_dwordx4 v144, s[22:23]
	s_waitcnt vmcnt(8)
	s_waitcnt lgkmcnt(0)
	s_barrier
	s_setprio 1
	v_mfma_f32_16x16x32_bf16 v[124:127], v[156:159], v[212:215], v[124:127]
	v_mfma_f32_16x16x32_bf16 v[120:123], v[184:187], v[212:215], v[120:123]
	v_mfma_f32_16x16x32_bf16 v[116:119], v[156:159], v[220:223], v[116:119]
	v_mfma_f32_16x16x32_bf16 v[112:115], v[184:187], v[220:223], v[112:115]
	v_mfma_f32_16x16x32_bf16 v[92:95], v[156:159], v[228:231], v[92:95]
	v_mfma_f32_16x16x32_bf16 v[88:91], v[184:187], v[228:231], v[88:91]
	v_mfma_f32_16x16x32_bf16 v[76:79], v[156:159], v[236:239], v[76:79]
	v_mfma_f32_16x16x32_bf16 v[72:75], v[184:187], v[236:239], v[72:75]
	v_mfma_f32_16x16x32_bf16 v[124:127], v[160:163], v[216:219], v[124:127]
	v_mfma_f32_16x16x32_bf16 v[120:123], v[188:191], v[216:219], v[120:123]
	v_mfma_f32_16x16x32_bf16 v[116:119], v[160:163], v[224:227], v[116:119]
	v_mfma_f32_16x16x32_bf16 v[112:115], v[188:191], v[224:227], v[112:115]
	v_mfma_f32_16x16x32_bf16 v[92:95], v[160:163], v[232:235], v[92:95]
	v_mfma_f32_16x16x32_bf16 v[88:91], v[188:191], v[232:235], v[88:91]
	v_mfma_f32_16x16x32_bf16 v[76:79], v[160:163], v[240:243], v[76:79]
	v_mfma_f32_16x16x32_bf16 v[72:75], v[188:191], v[240:243], v[72:75]
	v_mfma_f32_16x16x32_bf16 v[108:111], v[196:199], v[212:215], v[108:111]
	v_mfma_f32_16x16x32_bf16 v[104:107], v[204:207], v[212:215], v[104:107]
	v_mfma_f32_16x16x32_bf16 v[100:103], v[196:199], v[220:223], v[100:103]
	v_mfma_f32_16x16x32_bf16 v[96:99], v[204:207], v[220:223], v[96:99]
	v_mfma_f32_16x16x32_bf16 v[84:87], v[196:199], v[228:231], v[84:87]
	v_mfma_f32_16x16x32_bf16 v[80:83], v[204:207], v[228:231], v[80:83]
	v_mfma_f32_16x16x32_bf16 v[68:71], v[196:199], v[236:239], v[68:71]
	v_mfma_f32_16x16x32_bf16 v[64:67], v[204:207], v[236:239], v[64:67]
	v_mfma_f32_16x16x32_bf16 v[108:111], v[200:203], v[216:219], v[108:111]
	v_mfma_f32_16x16x32_bf16 v[104:107], v[208:211], v[216:219], v[104:107]
	v_mfma_f32_16x16x32_bf16 v[100:103], v[200:203], v[224:227], v[100:103]
	v_mfma_f32_16x16x32_bf16 v[96:99], v[208:211], v[224:227], v[96:99]
	v_mfma_f32_16x16x32_bf16 v[84:87], v[200:203], v[232:235], v[84:87]
	v_mfma_f32_16x16x32_bf16 v[80:83], v[208:211], v[232:235], v[80:83]
	v_mfma_f32_16x16x32_bf16 v[68:71], v[200:203], v[240:243], v[68:71]
	v_mfma_f32_16x16x32_bf16 v[64:67], v[208:211], v[240:243], v[64:67]
	s_barrier
	s_setprio 0
	s_add_i32 s22, s74, s46
	s_mov_b32 m0, s22
	ds_read_b128 v[212:215], v167 offset:49152
	ds_read_b128 v[216:219], v167 offset:50176
	ds_read_b128 v[220:223], v167 offset:51200
	ds_read_b128 v[224:227], v167 offset:52224
	ds_read_b128 v[228:231], v167 offset:53248
	ds_read_b128 v[232:235], v167 offset:54272
	ds_read_b128 v[236:239], v167 offset:55296
	ds_read_b128 v[240:243], v167 offset:56320
	global_load_lds_dwordx4 v142, s[98:99]
	s_add_i32 m0, s22, 0x2000
	s_add_u32 s2, s2, 0x40080
	s_addc_u32 s3, s3, 0
	s_add_i32 s22, s75, s46
	global_load_lds_dwordx4 v146, s[98:99]
	s_mov_b32 m0, s22
	s_nop 0
	global_load_lds_dwordx4 v142, s[2:3]
	s_add_i32 m0, s22, 0x2000
	s_nop 0
	global_load_lds_dwordx4 v146, s[2:3]
	s_mov_b32 m0, s54
	s_nop 0
	global_load_lds_dwordx4 v140, s[100:101]
	s_mov_b32 m0, s55
	s_nop 0
	global_load_lds_dwordx4 v144, s[100:101]
	s_waitcnt vmcnt(8)
	s_waitcnt lgkmcnt(0)
	s_barrier
	s_setprio 1
	v_mfma_f32_16x16x32_bf16 v[60:63], v[156:159], v[212:215], v[60:63]
	v_mfma_f32_16x16x32_bf16 v[56:59], v[184:187], v[212:215], v[56:59]
	v_mfma_f32_16x16x32_bf16 v[44:47], v[156:159], v[220:223], v[44:47]
	v_mfma_f32_16x16x32_bf16 v[40:43], v[184:187], v[220:223], v[40:43]
	v_mfma_f32_16x16x32_bf16 v[28:31], v[156:159], v[228:231], v[28:31]
	v_mfma_f32_16x16x32_bf16 v[24:27], v[184:187], v[228:231], v[24:27]
	v_mfma_f32_16x16x32_bf16 v[12:15], v[156:159], v[236:239], v[12:15]
	v_mfma_f32_16x16x32_bf16 v[8:11], v[184:187], v[236:239], v[8:11]
	v_mfma_f32_16x16x32_bf16 v[60:63], v[160:163], v[216:219], v[60:63]
	v_mfma_f32_16x16x32_bf16 v[56:59], v[188:191], v[216:219], v[56:59]
	v_mfma_f32_16x16x32_bf16 v[44:47], v[160:163], v[224:227], v[44:47]
	v_mfma_f32_16x16x32_bf16 v[40:43], v[188:191], v[224:227], v[40:43]
	v_mfma_f32_16x16x32_bf16 v[28:31], v[160:163], v[232:235], v[28:31]
	v_mfma_f32_16x16x32_bf16 v[24:27], v[188:191], v[232:235], v[24:27]
	v_mfma_f32_16x16x32_bf16 v[12:15], v[160:163], v[240:243], v[12:15]
	v_mfma_f32_16x16x32_bf16 v[8:11], v[188:191], v[240:243], v[8:11]
	v_mfma_f32_16x16x32_bf16 v[52:55], v[196:199], v[212:215], v[52:55]
	v_mfma_f32_16x16x32_bf16 v[48:51], v[204:207], v[212:215], v[48:51]
	v_mfma_f32_16x16x32_bf16 v[36:39], v[196:199], v[220:223], v[36:39]
	v_mfma_f32_16x16x32_bf16 v[32:35], v[204:207], v[220:223], v[32:35]
	v_mfma_f32_16x16x32_bf16 v[20:23], v[196:199], v[228:231], v[20:23]
	v_mfma_f32_16x16x32_bf16 v[16:19], v[204:207], v[228:231], v[16:19]
	v_mfma_f32_16x16x32_bf16 v[4:7], v[196:199], v[236:239], v[4:7]
	v_mfma_f32_16x16x32_bf16 v[0:3], v[204:207], v[236:239], v[0:3]
	v_mfma_f32_16x16x32_bf16 v[52:55], v[200:203], v[216:219], v[52:55]
	v_mfma_f32_16x16x32_bf16 v[48:51], v[208:211], v[216:219], v[48:51]
	v_mfma_f32_16x16x32_bf16 v[36:39], v[200:203], v[224:227], v[36:39]
	v_mfma_f32_16x16x32_bf16 v[32:35], v[208:211], v[224:227], v[32:35]
	v_mfma_f32_16x16x32_bf16 v[20:23], v[200:203], v[232:235], v[20:23]
	v_mfma_f32_16x16x32_bf16 v[16:19], v[208:211], v[232:235], v[16:19]
	v_mfma_f32_16x16x32_bf16 v[4:7], v[200:203], v[240:243], v[4:7]
	v_mfma_f32_16x16x32_bf16 v[0:3], v[208:211], v[240:243], v[0:3]
	s_barrier
	s_setprio 0
	s_add_i32 s73, s73, 2
	s_add_u32 s14, s14, 0x100
	s_addc_u32 s15, s15, 0
	s_add_u32 s71, s71, 0x100
	s_addc_u32 s72, s72, 0
	s_cmp_gt_u32 s73, 13
	s_cbranch_scc0 .LBB0_552

.LBB0_724:
	s_ashr_i32 s27, s26, 31
	s_lshl_b64 s[22:23], s[26:27], 19
	s_add_u32 s28, s16, s22
	s_addc_u32 s29, s17, s23
	s_and_b64 s[22:23], s[6:7], exec
	s_cselect_b32 s27, s29, s15
	s_cselect_b32 s59, s28, s14
	s_ashr_i32 s25, s24, 31
	s_lshl_b64 s[22:23], s[24:25], 19
	s_add_u32 s30, s35, s22
	s_addc_u32 s31, s38, s23
	s_and_b64 s[22:23], s[6:7], exec
	s_cselect_b32 s25, s31, s3
	s_cselect_b32 s64, s30, s2
	s_add_u32 s14, s14, 0x40080
	s_addc_u32 s15, s15, 0
	s_add_u32 s65, s2, 0x100
	s_addc_u32 s66, s3, 0
	s_mov_b32 s67, -2
	s_waitcnt lgkmcnt(0)
	s_waitcnt vmcnt(0)
	ds_read_b128 v[128:131], v155
	ds_read_b128 v[132:135], v155 offset:1024
	ds_read_b128 v[136:139], v155 offset:2048
	ds_read_b128 v[164:167], v155 offset:3072
	ds_read_b128 v[188:191], v184
	ds_read_b128 v[196:199], v184 offset:1024
	ds_read_b128 v[200:203], v184 offset:2048
	ds_read_b128 v[204:207], v184 offset:3072
	s_add_u32 s2, s14, 0xfffc0080
	s_addc_u32 s3, s15, -1
	s_cmp_eq_u32 s67, 12
	s_cselect_b32 s23, s27, s3
	s_cselect_b32 s22, s59, s2
	s_cselect_b32 s3, s25, s66
	s_cselect_b32 s2, s64, s65
	s_add_i32 m0, s37, 0xc000
	ds_read_b128 v[208:211], v185
	ds_read_b128 v[212:215], v185 offset:1024
	ds_read_b128 v[216:219], v185 offset:2048
	ds_read_b128 v[220:223], v185 offset:3072
	ds_read_b128 v[224:227], v185 offset:4096
	ds_read_b128 v[228:231], v185 offset:5120
	ds_read_b128 v[232:235], v185 offset:6144
	ds_read_b128 v[236:239], v185 offset:7168
	global_load_lds_dwordx4 v156, s[14:15]
	s_add_i32 m0, s37, 0xe000
	s_nop 0
	global_load_lds_dwordx4 v158, s[14:15]
	s_waitcnt vmcnt(8)
	s_waitcnt lgkmcnt(0)
	s_barrier
	s_setprio 1
	v_mfma_f32_16x16x32_bf16 v[124:127], v[128:131], v[208:211], 0
	v_mfma_f32_16x16x32_bf16 v[120:123], v[136:139], v[208:211], 0
	v_mfma_f32_16x16x32_bf16 v[108:111], v[128:131], v[216:219], 0
	v_mfma_f32_16x16x32_bf16 v[104:107], v[136:139], v[216:219], 0
	v_mfma_f32_16x16x32_bf16 v[92:95], v[128:131], v[224:227], 0
	v_mfma_f32_16x16x32_bf16 v[88:91], v[136:139], v[224:227], 0
	v_mfma_f32_16x16x32_bf16 v[76:79], v[128:131], v[232:235], 0
	v_mfma_f32_16x16x32_bf16 v[72:75], v[136:139], v[232:235], 0
	v_mfma_f32_16x16x32_bf16 v[124:127], v[132:135], v[212:215], v[124:127]
	v_mfma_f32_16x16x32_bf16 v[120:123], v[164:167], v[212:215], v[120:123]
	v_mfma_f32_16x16x32_bf16 v[108:111], v[132:135], v[220:223], v[108:111]
	v_mfma_f32_16x16x32_bf16 v[104:107], v[164:167], v[220:223], v[104:107]
	v_mfma_f32_16x16x32_bf16 v[92:95], v[132:135], v[228:231], v[92:95]
	v_mfma_f32_16x16x32_bf16 v[88:91], v[164:167], v[228:231], v[88:91]
	v_mfma_f32_16x16x32_bf16 v[76:79], v[132:135], v[236:239], v[76:79]
	v_mfma_f32_16x16x32_bf16 v[72:75], v[164:167], v[236:239], v[72:75]
	v_mfma_f32_16x16x32_bf16 v[116:119], v[188:191], v[208:211], 0
	v_mfma_f32_16x16x32_bf16 v[112:115], v[200:203], v[208:211], 0
	v_mfma_f32_16x16x32_bf16 v[100:103], v[188:191], v[216:219], 0
	v_mfma_f32_16x16x32_bf16 v[96:99], v[200:203], v[216:219], 0
	v_mfma_f32_16x16x32_bf16 v[84:87], v[188:191], v[224:227], 0
	v_mfma_f32_16x16x32_bf16 v[80:83], v[200:203], v[224:227], 0
	v_mfma_f32_16x16x32_bf16 v[68:71], v[188:191], v[232:235], 0
	v_mfma_f32_16x16x32_bf16 v[64:67], v[200:203], v[232:235], 0
	v_mfma_f32_16x16x32_bf16 v[116:119], v[196:199], v[212:215], v[116:119]
	v_mfma_f32_16x16x32_bf16 v[112:115], v[204:207], v[212:215], v[112:115]
	v_mfma_f32_16x16x32_bf16 v[100:103], v[196:199], v[220:223], v[100:103]
	v_mfma_f32_16x16x32_bf16 v[96:99], v[204:207], v[220:223], v[96:99]
	v_mfma_f32_16x16x32_bf16 v[84:87], v[196:199], v[228:231], v[84:87]
	v_mfma_f32_16x16x32_bf16 v[80:83], v[204:207], v[228:231], v[80:83]
	v_mfma_f32_16x16x32_bf16 v[68:71], v[196:199], v[236:239], v[68:71]
	v_mfma_f32_16x16x32_bf16 v[64:67], v[204:207], v[236:239], v[64:67]
	s_barrier
	s_setprio 0
	s_add_i32 s68, s52, s39
	s_add_u32 s98, s2, s18
	s_addc_u32 s99, s3, s19
	s_mov_b32 m0, s68
	ds_read_b128 v[208:211], v185 offset:16384
	ds_read_b128 v[212:215], v185 offset:17408
	ds_read_b128 v[216:219], v185 offset:18432
	ds_read_b128 v[220:223], v185 offset:19456
	ds_read_b128 v[224:227], v185 offset:20480
	ds_read_b128 v[228:231], v185 offset:21504
	ds_read_b128 v[232:235], v185 offset:22528
	ds_read_b128 v[236:239], v185 offset:23552
	global_load_lds_dwordx4 v142, s[2:3]
	s_add_i32 m0, s68, 0x2000
	s_add_u32 s68, s2, 0x40000
	s_addc_u32 s69, s3, 0
	s_add_i32 s70, s53, s39
	global_load_lds_dwordx4 v146, s[2:3]
	s_mov_b32 m0, s70
	s_nop 0
	global_load_lds_dwordx4 v142, s[68:69]
	s_add_i32 m0, s70, 0x2000
	s_nop 0
	global_load_lds_dwordx4 v146, s[68:69]
	s_add_u32 s100, s22, s18
	s_addc_u32 s101, s23, s19
	s_mov_b32 m0, s37
	s_nop 0
	global_load_lds_dwordx4 v140, s[22:23]
	s_mov_b32 m0, s40
	s_nop 0
	global_load_lds_dwordx4 v144, s[22:23]
	s_waitcnt vmcnt(8)
	s_waitcnt lgkmcnt(0)
	s_barrier
	s_setprio 1
	v_mfma_f32_16x16x32_bf16 v[60:63], v[128:131], v[208:211], 0
	v_mfma_f32_16x16x32_bf16 v[56:59], v[136:139], v[208:211], 0
	v_mfma_f32_16x16x32_bf16 v[44:47], v[128:131], v[216:219], 0
	v_mfma_f32_16x16x32_bf16 v[40:43], v[136:139], v[216:219], 0
	v_mfma_f32_16x16x32_bf16 v[28:31], v[128:131], v[224:227], 0
	v_mfma_f32_16x16x32_bf16 v[24:27], v[136:139], v[224:227], 0
	v_mfma_f32_16x16x32_bf16 v[12:15], v[128:131], v[232:235], 0
	v_mfma_f32_16x16x32_bf16 v[8:11], v[136:139], v[232:235], 0
	v_mfma_f32_16x16x32_bf16 v[60:63], v[132:135], v[212:215], v[60:63]
	v_mfma_f32_16x16x32_bf16 v[56:59], v[164:167], v[212:215], v[56:59]
	v_mfma_f32_16x16x32_bf16 v[44:47], v[132:135], v[220:223], v[44:47]
	v_mfma_f32_16x16x32_bf16 v[40:43], v[164:167], v[220:223], v[40:43]
	v_mfma_f32_16x16x32_bf16 v[28:31], v[132:135], v[228:231], v[28:31]
	v_mfma_f32_16x16x32_bf16 v[24:27], v[164:167], v[228:231], v[24:27]
	v_mfma_f32_16x16x32_bf16 v[12:15], v[132:135], v[236:239], v[12:15]
	v_mfma_f32_16x16x32_bf16 v[8:11], v[164:167], v[236:239], v[8:11]
	v_mfma_f32_16x16x32_bf16 v[52:55], v[188:191], v[208:211], 0
	v_mfma_f32_16x16x32_bf16 v[48:51], v[200:203], v[208:211], 0
	v_mfma_f32_16x16x32_bf16 v[36:39], v[188:191], v[216:219], 0
	v_mfma_f32_16x16x32_bf16 v[32:35], v[200:203], v[216:219], 0
	v_mfma_f32_16x16x32_bf16 v[20:23], v[188:191], v[224:227], 0
	v_mfma_f32_16x16x32_bf16 v[16:19], v[200:203], v[224:227], 0
	v_mfma_f32_16x16x32_bf16 v[4:7], v[188:191], v[232:235], 0
	v_mfma_f32_16x16x32_bf16 v[0:3], v[200:203], v[232:235], 0
	v_mfma_f32_16x16x32_bf16 v[52:55], v[196:199], v[212:215], v[52:55]
	v_mfma_f32_16x16x32_bf16 v[48:51], v[204:207], v[212:215], v[48:51]
	v_mfma_f32_16x16x32_bf16 v[36:39], v[196:199], v[220:223], v[36:39]
	v_mfma_f32_16x16x32_bf16 v[32:35], v[204:207], v[220:223], v[32:35]
	v_mfma_f32_16x16x32_bf16 v[20:23], v[196:199], v[228:231], v[20:23]
	v_mfma_f32_16x16x32_bf16 v[16:19], v[204:207], v[228:231], v[16:19]
	v_mfma_f32_16x16x32_bf16 v[4:7], v[196:199], v[236:239], v[4:7]
	v_mfma_f32_16x16x32_bf16 v[0:3], v[204:207], v[236:239], v[0:3]
	s_barrier
	s_setprio 0
	s_add_i32 s68, 0, 0x18000
	s_add_i32 s69, 0, 0x1c000
	v_add_u32_e32 v164, s68, v149
	v_add_u32_e32 v187, s69, v149
	ds_read_b128 v[128:131], v164
	ds_read_b128 v[132:135], v164 offset:1024
	ds_read_b128 v[136:139], v164 offset:2048
	ds_read_b128 v[164:167], v164 offset:3072
	ds_read_b128 v[188:191], v187
	ds_read_b128 v[196:199], v187 offset:1024
	ds_read_b128 v[200:203], v187 offset:2048
	ds_read_b128 v[204:207], v187 offset:3072
	s_add_u32 s22, s22, 0x40000
	s_addc_u32 s23, s23, 0
	s_mov_b32 m0, s41
	ds_read_b128 v[208:211], v185 offset:32768
	ds_read_b128 v[212:215], v185 offset:33792
	ds_read_b128 v[216:219], v185 offset:34816
	ds_read_b128 v[220:223], v185 offset:35840
	ds_read_b128 v[224:227], v185 offset:36864
	ds_read_b128 v[228:231], v185 offset:37888
	ds_read_b128 v[232:235], v185 offset:38912
	ds_read_b128 v[236:239], v185 offset:39936
	global_load_lds_dwordx4 v140, s[22:23]
	s_mov_b32 m0, s42
	s_nop 0
	global_load_lds_dwordx4 v144, s[22:23]
	s_waitcnt vmcnt(8)
	s_waitcnt lgkmcnt(0)
	s_barrier
	s_setprio 1
	v_mfma_f32_16x16x32_bf16 v[124:127], v[128:131], v[208:211], v[124:127]
	v_mfma_f32_16x16x32_bf16 v[120:123], v[136:139], v[208:211], v[120:123]
	v_mfma_f32_16x16x32_bf16 v[108:111], v[128:131], v[216:219], v[108:111]
	v_mfma_f32_16x16x32_bf16 v[104:107], v[136:139], v[216:219], v[104:107]
	v_mfma_f32_16x16x32_bf16 v[92:95], v[128:131], v[224:227], v[92:95]
	v_mfma_f32_16x16x32_bf16 v[88:91], v[136:139], v[224:227], v[88:91]
	v_mfma_f32_16x16x32_bf16 v[76:79], v[128:131], v[232:235], v[76:79]
	v_mfma_f32_16x16x32_bf16 v[72:75], v[136:139], v[232:235], v[72:75]
	v_mfma_f32_16x16x32_bf16 v[124:127], v[132:135], v[212:215], v[124:127]
	v_mfma_f32_16x16x32_bf16 v[120:123], v[164:167], v[212:215], v[120:123]
	v_mfma_f32_16x16x32_bf16 v[108:111], v[132:135], v[220:223], v[108:111]
	v_mfma_f32_16x16x32_bf16 v[104:107], v[164:167], v[220:223], v[104:107]
	v_mfma_f32_16x16x32_bf16 v[92:95], v[132:135], v[228:231], v[92:95]
	v_mfma_f32_16x16x32_bf16 v[88:91], v[164:167], v[228:231], v[88:91]
	v_mfma_f32_16x16x32_bf16 v[76:79], v[132:135], v[236:239], v[76:79]
	v_mfma_f32_16x16x32_bf16 v[72:75], v[164:167], v[236:239], v[72:75]
	v_mfma_f32_16x16x32_bf16 v[116:119], v[188:191], v[208:211], v[116:119]
	v_mfma_f32_16x16x32_bf16 v[112:115], v[200:203], v[208:211], v[112:115]
	v_mfma_f32_16x16x32_bf16 v[100:103], v[188:191], v[216:219], v[100:103]
	v_mfma_f32_16x16x32_bf16 v[96:99], v[200:203], v[216:219], v[96:99]
	v_mfma_f32_16x16x32_bf16 v[84:87], v[188:191], v[224:227], v[84:87]
	v_mfma_f32_16x16x32_bf16 v[80:83], v[200:203], v[224:227], v[80:83]
	v_mfma_f32_16x16x32_bf16 v[68:71], v[188:191], v[232:235], v[68:71]
	v_mfma_f32_16x16x32_bf16 v[64:67], v[200:203], v[232:235], v[64:67]
	v_mfma_f32_16x16x32_bf16 v[116:119], v[196:199], v[212:215], v[116:119]
	v_mfma_f32_16x16x32_bf16 v[112:115], v[204:207], v[212:215], v[112:115]
	v_mfma_f32_16x16x32_bf16 v[100:103], v[196:199], v[220:223], v[100:103]
	v_mfma_f32_16x16x32_bf16 v[96:99], v[204:207], v[220:223], v[96:99]
	v_mfma_f32_16x16x32_bf16 v[84:87], v[196:199], v[228:231], v[84:87]
	v_mfma_f32_16x16x32_bf16 v[80:83], v[204:207], v[228:231], v[80:83]
	v_mfma_f32_16x16x32_bf16 v[68:71], v[196:199], v[236:239], v[68:71]
	v_mfma_f32_16x16x32_bf16 v[64:67], v[204:207], v[236:239], v[64:67]
	s_barrier
	s_setprio 0
	s_add_i32 s22, s68, s39
	s_mov_b32 m0, s22
	ds_read_b128 v[208:211], v185 offset:49152
	ds_read_b128 v[212:215], v185 offset:50176
	ds_read_b128 v[216:219], v185 offset:51200
	ds_read_b128 v[220:223], v185 offset:52224
	ds_read_b128 v[224:227], v185 offset:53248
	ds_read_b128 v[228:231], v185 offset:54272
	ds_read_b128 v[232:235], v185 offset:55296
	ds_read_b128 v[236:239], v185 offset:56320
	global_load_lds_dwordx4 v142, s[98:99]
	s_add_i32 m0, s22, 0x2000
	s_add_u32 s2, s2, 0x40080
	s_addc_u32 s3, s3, 0
	s_add_i32 s22, s69, s39
	global_load_lds_dwordx4 v146, s[98:99]
	s_mov_b32 m0, s22
	s_nop 0
	global_load_lds_dwordx4 v142, s[2:3]
	s_add_i32 m0, s22, 0x2000
	s_nop 0
	global_load_lds_dwordx4 v146, s[2:3]
	s_mov_b32 m0, s46
	s_nop 0
	global_load_lds_dwordx4 v140, s[100:101]
	s_mov_b32 m0, s47
	s_nop 0
	global_load_lds_dwordx4 v144, s[100:101]
	s_waitcnt vmcnt(8)
	s_waitcnt lgkmcnt(0)
	s_barrier
	s_setprio 1
	v_mfma_f32_16x16x32_bf16 v[60:63], v[128:131], v[208:211], v[60:63]
	v_mfma_f32_16x16x32_bf16 v[56:59], v[136:139], v[208:211], v[56:59]
	v_mfma_f32_16x16x32_bf16 v[44:47], v[128:131], v[216:219], v[44:47]
	v_mfma_f32_16x16x32_bf16 v[40:43], v[136:139], v[216:219], v[40:43]
	v_mfma_f32_16x16x32_bf16 v[28:31], v[128:131], v[224:227], v[28:31]
	v_mfma_f32_16x16x32_bf16 v[24:27], v[136:139], v[224:227], v[24:27]
	v_mfma_f32_16x16x32_bf16 v[12:15], v[128:131], v[232:235], v[12:15]
	v_mfma_f32_16x16x32_bf16 v[8:11], v[136:139], v[232:235], v[8:11]
	v_mfma_f32_16x16x32_bf16 v[60:63], v[132:135], v[212:215], v[60:63]
	v_mfma_f32_16x16x32_bf16 v[56:59], v[164:167], v[212:215], v[56:59]
	v_mfma_f32_16x16x32_bf16 v[44:47], v[132:135], v[220:223], v[44:47]
	v_mfma_f32_16x16x32_bf16 v[40:43], v[164:167], v[220:223], v[40:43]
	v_mfma_f32_16x16x32_bf16 v[28:31], v[132:135], v[228:231], v[28:31]
	v_mfma_f32_16x16x32_bf16 v[24:27], v[164:167], v[228:231], v[24:27]
	v_mfma_f32_16x16x32_bf16 v[12:15], v[132:135], v[236:239], v[12:15]
	v_mfma_f32_16x16x32_bf16 v[8:11], v[164:167], v[236:239], v[8:11]
	v_mfma_f32_16x16x32_bf16 v[52:55], v[188:191], v[208:211], v[52:55]
	v_mfma_f32_16x16x32_bf16 v[48:51], v[200:203], v[208:211], v[48:51]
	v_mfma_f32_16x16x32_bf16 v[36:39], v[188:191], v[216:219], v[36:39]
	v_mfma_f32_16x16x32_bf16 v[32:35], v[200:203], v[216:219], v[32:35]
	v_mfma_f32_16x16x32_bf16 v[20:23], v[188:191], v[224:227], v[20:23]
	v_mfma_f32_16x16x32_bf16 v[16:19], v[200:203], v[224:227], v[16:19]
	v_mfma_f32_16x16x32_bf16 v[4:7], v[188:191], v[232:235], v[4:7]
	v_mfma_f32_16x16x32_bf16 v[0:3], v[200:203], v[232:235], v[0:3]
	v_mfma_f32_16x16x32_bf16 v[52:55], v[196:199], v[212:215], v[52:55]
	v_mfma_f32_16x16x32_bf16 v[48:51], v[204:207], v[212:215], v[48:51]
	v_mfma_f32_16x16x32_bf16 v[36:39], v[196:199], v[220:223], v[36:39]
	v_mfma_f32_16x16x32_bf16 v[32:35], v[204:207], v[220:223], v[32:35]
	v_mfma_f32_16x16x32_bf16 v[20:23], v[196:199], v[228:231], v[20:23]
	v_mfma_f32_16x16x32_bf16 v[16:19], v[204:207], v[228:231], v[16:19]
	v_mfma_f32_16x16x32_bf16 v[4:7], v[196:199], v[236:239], v[4:7]
	v_mfma_f32_16x16x32_bf16 v[0:3], v[204:207], v[236:239], v[0:3]
	s_barrier
	s_setprio 0
	s_add_i32 s67, s67, 2
	s_add_u32 s14, s14, 0x100
	s_addc_u32 s15, s15, 0
	s_add_u32 s65, s65, 0x100
	s_addc_u32 s66, s66, 0
	s_cmp_gt_u32 s67, 13
	s_cbranch_scc1 .Lgemm_kdone_4
.LBB0_725:
	ds_read_b128 v[128:131], v155
	ds_read_b128 v[132:135], v155 offset:1024
	ds_read_b128 v[136:139], v155 offset:2048
	ds_read_b128 v[164:167], v155 offset:3072
	ds_read_b128 v[188:191], v184
	ds_read_b128 v[196:199], v184 offset:1024
	ds_read_b128 v[200:203], v184 offset:2048
	ds_read_b128 v[204:207], v184 offset:3072
	s_add_u32 s2, s14, 0xfffc0080
	s_addc_u32 s3, s15, -1
	s_cmp_eq_u32 s67, 12
	s_cselect_b32 s23, s27, s3
	s_cselect_b32 s22, s59, s2
	s_cselect_b32 s3, s25, s66
	s_cselect_b32 s2, s64, s65
	s_add_i32 m0, s37, 0xc000
	ds_read_b128 v[208:211], v185
	ds_read_b128 v[212:215], v185 offset:1024
	ds_read_b128 v[216:219], v185 offset:2048
	ds_read_b128 v[220:223], v185 offset:3072
	ds_read_b128 v[224:227], v185 offset:4096
	ds_read_b128 v[228:231], v185 offset:5120
	ds_read_b128 v[232:235], v185 offset:6144
	ds_read_b128 v[236:239], v185 offset:7168
	global_load_lds_dwordx4 v156, s[14:15]
	s_add_i32 m0, s37, 0xe000
	s_nop 0
	global_load_lds_dwordx4 v158, s[14:15]
	s_waitcnt vmcnt(8)
	s_waitcnt lgkmcnt(0)
	s_barrier
	s_setprio 1
	v_mfma_f32_16x16x32_bf16 v[124:127], v[128:131], v[208:211], v[124:127]
	v_mfma_f32_16x16x32_bf16 v[120:123], v[136:139], v[208:211], v[120:123]
	v_mfma_f32_16x16x32_bf16 v[108:111], v[128:131], v[216:219], v[108:111]
	v_mfma_f32_16x16x32_bf16 v[104:107], v[136:139], v[216:219], v[104:107]
	v_mfma_f32_16x16x32_bf16 v[92:95], v[128:131], v[224:227], v[92:95]
	v_mfma_f32_16x16x32_bf16 v[88:91], v[136:139], v[224:227], v[88:91]
	v_mfma_f32_16x16x32_bf16 v[76:79], v[128:131], v[232:235], v[76:79]
	v_mfma_f32_16x16x32_bf16 v[72:75], v[136:139], v[232:235], v[72:75]
	v_mfma_f32_16x16x32_bf16 v[124:127], v[132:135], v[212:215], v[124:127]
	v_mfma_f32_16x16x32_bf16 v[120:123], v[164:167], v[212:215], v[120:123]
	v_mfma_f32_16x16x32_bf16 v[108:111], v[132:135], v[220:223], v[108:111]
	v_mfma_f32_16x16x32_bf16 v[104:107], v[164:167], v[220:223], v[104:107]
	v_mfma_f32_16x16x32_bf16 v[92:95], v[132:135], v[228:231], v[92:95]
	v_mfma_f32_16x16x32_bf16 v[88:91], v[164:167], v[228:231], v[88:91]
	v_mfma_f32_16x16x32_bf16 v[76:79], v[132:135], v[236:239], v[76:79]
	v_mfma_f32_16x16x32_bf16 v[72:75], v[164:167], v[236:239], v[72:75]
	v_mfma_f32_16x16x32_bf16 v[116:119], v[188:191], v[208:211], v[116:119]
	v_mfma_f32_16x16x32_bf16 v[112:115], v[200:203], v[208:211], v[112:115]
	v_mfma_f32_16x16x32_bf16 v[100:103], v[188:191], v[216:219], v[100:103]
	v_mfma_f32_16x16x32_bf16 v[96:99], v[200:203], v[216:219], v[96:99]
	v_mfma_f32_16x16x32_bf16 v[84:87], v[188:191], v[224:227], v[84:87]
	v_mfma_f32_16x16x32_bf16 v[80:83], v[200:203], v[224:227], v[80:83]
	v_mfma_f32_16x16x32_bf16 v[68:71], v[188:191], v[232:235], v[68:71]
	v_mfma_f32_16x16x32_bf16 v[64:67], v[200:203], v[232:235], v[64:67]
	v_mfma_f32_16x16x32_bf16 v[116:119], v[196:199], v[212:215], v[116:119]
	v_mfma_f32_16x16x32_bf16 v[112:115], v[204:207], v[212:215], v[112:115]
	v_mfma_f32_16x16x32_bf16 v[100:103], v[196:199], v[220:223], v[100:103]
	v_mfma_f32_16x16x32_bf16 v[96:99], v[204:207], v[220:223], v[96:99]
	v_mfma_f32_16x16x32_bf16 v[84:87], v[196:199], v[228:231], v[84:87]
	v_mfma_f32_16x16x32_bf16 v[80:83], v[204:207], v[228:231], v[80:83]
	v_mfma_f32_16x16x32_bf16 v[68:71], v[196:199], v[236:239], v[68:71]
	v_mfma_f32_16x16x32_bf16 v[64:67], v[204:207], v[236:239], v[64:67]
	s_barrier
	s_setprio 0
	s_add_i32 s68, s52, s39
	s_add_u32 s98, s2, s18
	s_addc_u32 s99, s3, s19
	s_mov_b32 m0, s68
	ds_read_b128 v[208:211], v185 offset:16384
	ds_read_b128 v[212:215], v185 offset:17408
	ds_read_b128 v[216:219], v185 offset:18432
	ds_read_b128 v[220:223], v185 offset:19456
	ds_read_b128 v[224:227], v185 offset:20480
	ds_read_b128 v[228:231], v185 offset:21504
	ds_read_b128 v[232:235], v185 offset:22528
	ds_read_b128 v[236:239], v185 offset:23552
	global_load_lds_dwordx4 v142, s[2:3]
	s_add_i32 m0, s68, 0x2000
	s_add_u32 s68, s2, 0x40000
	s_addc_u32 s69, s3, 0
	s_add_i32 s70, s53, s39
	global_load_lds_dwordx4 v146, s[2:3]
	s_mov_b32 m0, s70
	s_nop 0
	global_load_lds_dwordx4 v142, s[68:69]
	s_add_i32 m0, s70, 0x2000
	s_nop 0
	global_load_lds_dwordx4 v146, s[68:69]
	s_add_u32 s100, s22, s18
	s_addc_u32 s101, s23, s19
	s_mov_b32 m0, s37
	s_nop 0
	global_load_lds_dwordx4 v140, s[22:23]
	s_mov_b32 m0, s40
	s_nop 0
	global_load_lds_dwordx4 v144, s[22:23]
	s_waitcnt vmcnt(8)
	s_waitcnt lgkmcnt(0)
	s_barrier
	s_setprio 1
	v_mfma_f32_16x16x32_bf16 v[60:63], v[128:131], v[208:211], v[60:63]
	v_mfma_f32_16x16x32_bf16 v[56:59], v[136:139], v[208:211], v[56:59]
	v_mfma_f32_16x16x32_bf16 v[44:47], v[128:131], v[216:219], v[44:47]
	v_mfma_f32_16x16x32_bf16 v[40:43], v[136:139], v[216:219], v[40:43]
	v_mfma_f32_16x16x32_bf16 v[28:31], v[128:131], v[224:227], v[28:31]
	v_mfma_f32_16x16x32_bf16 v[24:27], v[136:139], v[224:227], v[24:27]
	v_mfma_f32_16x16x32_bf16 v[12:15], v[128:131], v[232:235], v[12:15]
	v_mfma_f32_16x16x32_bf16 v[8:11], v[136:139], v[232:235], v[8:11]
	v_mfma_f32_16x16x32_bf16 v[60:63], v[132:135], v[212:215], v[60:63]
	v_mfma_f32_16x16x32_bf16 v[56:59], v[164:167], v[212:215], v[56:59]
	v_mfma_f32_16x16x32_bf16 v[44:47], v[132:135], v[220:223], v[44:47]
	v_mfma_f32_16x16x32_bf16 v[40:43], v[164:167], v[220:223], v[40:43]
	v_mfma_f32_16x16x32_bf16 v[28:31], v[132:135], v[228:231], v[28:31]
	v_mfma_f32_16x16x32_bf16 v[24:27], v[164:167], v[228:231], v[24:27]
	v_mfma_f32_16x16x32_bf16 v[12:15], v[132:135], v[236:239], v[12:15]
	v_mfma_f32_16x16x32_bf16 v[8:11], v[164:167], v[236:239], v[8:11]
	v_mfma_f32_16x16x32_bf16 v[52:55], v[188:191], v[208:211], v[52:55]
	v_mfma_f32_16x16x32_bf16 v[48:51], v[200:203], v[208:211], v[48:51]
	v_mfma_f32_16x16x32_bf16 v[36:39], v[188:191], v[216:219], v[36:39]
	v_mfma_f32_16x16x32_bf16 v[32:35], v[200:203], v[216:219], v[32:35]
	v_mfma_f32_16x16x32_bf16 v[20:23], v[188:191], v[224:227], v[20:23]
	v_mfma_f32_16x16x32_bf16 v[16:19], v[200:203], v[224:227], v[16:19]
	v_mfma_f32_16x16x32_bf16 v[4:7], v[188:191], v[232:235], v[4:7]
	v_mfma_f32_16x16x32_bf16 v[0:3], v[200:203], v[232:235], v[0:3]
	v_mfma_f32_16x16x32_bf16 v[52:55], v[196:199], v[212:215], v[52:55]
	v_mfma_f32_16x16x32_bf16 v[48:51], v[204:207], v[212:215], v[48:51]
	v_mfma_f32_16x16x32_bf16 v[36:39], v[196:199], v[220:223], v[36:39]
	v_mfma_f32_16x16x32_bf16 v[32:35], v[204:207], v[220:223], v[32:35]
	v_mfma_f32_16x16x32_bf16 v[20:23], v[196:199], v[228:231], v[20:23]
	v_mfma_f32_16x16x32_bf16 v[16:19], v[204:207], v[228:231], v[16:19]
	v_mfma_f32_16x16x32_bf16 v[4:7], v[196:199], v[236:239], v[4:7]
	v_mfma_f32_16x16x32_bf16 v[0:3], v[204:207], v[236:239], v[0:3]
	s_barrier
	s_setprio 0
	s_add_i32 s68, 0, 0x18000
	s_add_i32 s69, 0, 0x1c000
	v_add_u32_e32 v164, s68, v149
	v_add_u32_e32 v187, s69, v149
	ds_read_b128 v[128:131], v164
	ds_read_b128 v[132:135], v164 offset:1024
	ds_read_b128 v[136:139], v164 offset:2048
	ds_read_b128 v[164:167], v164 offset:3072
	ds_read_b128 v[188:191], v187
	ds_read_b128 v[196:199], v187 offset:1024
	ds_read_b128 v[200:203], v187 offset:2048
	ds_read_b128 v[204:207], v187 offset:3072
	s_add_u32 s22, s22, 0x40000
	s_addc_u32 s23, s23, 0
	s_mov_b32 m0, s41
	ds_read_b128 v[208:211], v185 offset:32768
	ds_read_b128 v[212:215], v185 offset:33792
	ds_read_b128 v[216:219], v185 offset:34816
	ds_read_b128 v[220:223], v185 offset:35840
	ds_read_b128 v[224:227], v185 offset:36864
	ds_read_b128 v[228:231], v185 offset:37888
	ds_read_b128 v[232:235], v185 offset:38912
	ds_read_b128 v[236:239], v185 offset:39936
	global_load_lds_dwordx4 v140, s[22:23]
	s_mov_b32 m0, s42
	s_nop 0
	global_load_lds_dwordx4 v144, s[22:23]
	s_waitcnt vmcnt(8)
	s_waitcnt lgkmcnt(0)
	s_barrier
	s_setprio 1
	v_mfma_f32_16x16x32_bf16 v[124:127], v[128:131], v[208:211], v[124:127]
	v_mfma_f32_16x16x32_bf16 v[120:123], v[136:139], v[208:211], v[120:123]
	v_mfma_f32_16x16x32_bf16 v[108:111], v[128:131], v[216:219], v[108:111]
	v_mfma_f32_16x16x32_bf16 v[104:107], v[136:139], v[216:219], v[104:107]
	v_mfma_f32_16x16x32_bf16 v[92:95], v[128:131], v[224:227], v[92:95]
	v_mfma_f32_16x16x32_bf16 v[88:91], v[136:139], v[224:227], v[88:91]
	v_mfma_f32_16x16x32_bf16 v[76:79], v[128:131], v[232:235], v[76:79]
	v_mfma_f32_16x16x32_bf16 v[72:75], v[136:139], v[232:235], v[72:75]
	v_mfma_f32_16x16x32_bf16 v[124:127], v[132:135], v[212:215], v[124:127]
	v_mfma_f32_16x16x32_bf16 v[120:123], v[164:167], v[212:215], v[120:123]
	v_mfma_f32_16x16x32_bf16 v[108:111], v[132:135], v[220:223], v[108:111]
	v_mfma_f32_16x16x32_bf16 v[104:107], v[164:167], v[220:223], v[104:107]
	v_mfma_f32_16x16x32_bf16 v[92:95], v[132:135], v[228:231], v[92:95]
	v_mfma_f32_16x16x32_bf16 v[88:91], v[164:167], v[228:231], v[88:91]
	v_mfma_f32_16x16x32_bf16 v[76:79], v[132:135], v[236:239], v[76:79]
	v_mfma_f32_16x16x32_bf16 v[72:75], v[164:167], v[236:239], v[72:75]
	v_mfma_f32_16x16x32_bf16 v[116:119], v[188:191], v[208:211], v[116:119]
	v_mfma_f32_16x16x32_bf16 v[112:115], v[200:203], v[208:211], v[112:115]
	v_mfma_f32_16x16x32_bf16 v[100:103], v[188:191], v[216:219], v[100:103]
	v_mfma_f32_16x16x32_bf16 v[96:99], v[200:203], v[216:219], v[96:99]
	v_mfma_f32_16x16x32_bf16 v[84:87], v[188:191], v[224:227], v[84:87]
	v_mfma_f32_16x16x32_bf16 v[80:83], v[200:203], v[224:227], v[80:83]
	v_mfma_f32_16x16x32_bf16 v[68:71], v[188:191], v[232:235], v[68:71]
	v_mfma_f32_16x16x32_bf16 v[64:67], v[200:203], v[232:235], v[64:67]
	v_mfma_f32_16x16x32_bf16 v[116:119], v[196:199], v[212:215], v[116:119]
	v_mfma_f32_16x16x32_bf16 v[112:115], v[204:207], v[212:215], v[112:115]
	v_mfma_f32_16x16x32_bf16 v[100:103], v[196:199], v[220:223], v[100:103]
	v_mfma_f32_16x16x32_bf16 v[96:99], v[204:207], v[220:223], v[96:99]
	v_mfma_f32_16x16x32_bf16 v[84:87], v[196:199], v[228:231], v[84:87]
	v_mfma_f32_16x16x32_bf16 v[80:83], v[204:207], v[228:231], v[80:83]
	v_mfma_f32_16x16x32_bf16 v[68:71], v[196:199], v[236:239], v[68:71]
	v_mfma_f32_16x16x32_bf16 v[64:67], v[204:207], v[236:239], v[64:67]
	s_barrier
	s_setprio 0
	s_add_i32 s22, s68, s39
	s_mov_b32 m0, s22
	ds_read_b128 v[208:211], v185 offset:49152
	ds_read_b128 v[212:215], v185 offset:50176
	ds_read_b128 v[216:219], v185 offset:51200
	ds_read_b128 v[220:223], v185 offset:52224
	ds_read_b128 v[224:227], v185 offset:53248
	ds_read_b128 v[228:231], v185 offset:54272
	ds_read_b128 v[232:235], v185 offset:55296
	ds_read_b128 v[236:239], v185 offset:56320
	global_load_lds_dwordx4 v142, s[98:99]
	s_add_i32 m0, s22, 0x2000
	s_add_u32 s2, s2, 0x40080
	s_addc_u32 s3, s3, 0
	s_add_i32 s22, s69, s39
	global_load_lds_dwordx4 v146, s[98:99]
	s_mov_b32 m0, s22
	s_nop 0
	global_load_lds_dwordx4 v142, s[2:3]
	s_add_i32 m0, s22, 0x2000
	s_nop 0
	global_load_lds_dwordx4 v146, s[2:3]
	s_mov_b32 m0, s46
	s_nop 0
	global_load_lds_dwordx4 v140, s[100:101]
	s_mov_b32 m0, s47
	s_nop 0
	global_load_lds_dwordx4 v144, s[100:101]
	s_waitcnt vmcnt(8)
	s_waitcnt lgkmcnt(0)
	s_barrier
	s_setprio 1
	v_mfma_f32_16x16x32_bf16 v[60:63], v[128:131], v[208:211], v[60:63]
	v_mfma_f32_16x16x32_bf16 v[56:59], v[136:139], v[208:211], v[56:59]
	v_mfma_f32_16x16x32_bf16 v[44:47], v[128:131], v[216:219], v[44:47]
	v_mfma_f32_16x16x32_bf16 v[40:43], v[136:139], v[216:219], v[40:43]
	v_mfma_f32_16x16x32_bf16 v[28:31], v[128:131], v[224:227], v[28:31]
	v_mfma_f32_16x16x32_bf16 v[24:27], v[136:139], v[224:227], v[24:27]
	v_mfma_f32_16x16x32_bf16 v[12:15], v[128:131], v[232:235], v[12:15]
	v_mfma_f32_16x16x32_bf16 v[8:11], v[136:139], v[232:235], v[8:11]
	v_mfma_f32_16x16x32_bf16 v[60:63], v[132:135], v[212:215], v[60:63]
	v_mfma_f32_16x16x32_bf16 v[56:59], v[164:167], v[212:215], v[56:59]
	v_mfma_f32_16x16x32_bf16 v[44:47], v[132:135], v[220:223], v[44:47]
	v_mfma_f32_16x16x32_bf16 v[40:43], v[164:167], v[220:223], v[40:43]
	v_mfma_f32_16x16x32_bf16 v[28:31], v[132:135], v[228:231], v[28:31]
	v_mfma_f32_16x16x32_bf16 v[24:27], v[164:167], v[228:231], v[24:27]
	v_mfma_f32_16x16x32_bf16 v[12:15], v[132:135], v[236:239], v[12:15]
	v_mfma_f32_16x16x32_bf16 v[8:11], v[164:167], v[236:239], v[8:11]
	v_mfma_f32_16x16x32_bf16 v[52:55], v[188:191], v[208:211], v[52:55]
	v_mfma_f32_16x16x32_bf16 v[48:51], v[200:203], v[208:211], v[48:51]
	v_mfma_f32_16x16x32_bf16 v[36:39], v[188:191], v[216:219], v[36:39]
	v_mfma_f32_16x16x32_bf16 v[32:35], v[200:203], v[216:219], v[32:35]
	v_mfma_f32_16x16x32_bf16 v[20:23], v[188:191], v[224:227], v[20:23]
	v_mfma_f32_16x16x32_bf16 v[16:19], v[200:203], v[224:227], v[16:19]
	v_mfma_f32_16x16x32_bf16 v[4:7], v[188:191], v[232:235], v[4:7]
	v_mfma_f32_16x16x32_bf16 v[0:3], v[200:203], v[232:235], v[0:3]
	v_mfma_f32_16x16x32_bf16 v[52:55], v[196:199], v[212:215], v[52:55]
	v_mfma_f32_16x16x32_bf16 v[48:51], v[204:207], v[212:215], v[48:51]
	v_mfma_f32_16x16x32_bf16 v[36:39], v[196:199], v[220:223], v[36:39]
	v_mfma_f32_16x16x32_bf16 v[32:35], v[204:207], v[220:223], v[32:35]
	v_mfma_f32_16x16x32_bf16 v[20:23], v[196:199], v[228:231], v[20:23]
	v_mfma_f32_16x16x32_bf16 v[16:19], v[204:207], v[228:231], v[16:19]
	v_mfma_f32_16x16x32_bf16 v[4:7], v[196:199], v[236:239], v[4:7]
	v_mfma_f32_16x16x32_bf16 v[0:3], v[204:207], v[236:239], v[0:3]
	s_barrier
	s_setprio 0
	s_add_i32 s67, s67, 2
	s_add_u32 s14, s14, 0x100
	s_addc_u32 s15, s15, 0
	s_add_u32 s65, s65, 0x100
	s_addc_u32 s66, s66, 0
	s_cmp_gt_u32 s67, 13
	s_cbranch_scc0 .LBB0_725

.LBB0_808:
	s_ashr_i32 s25, s24, 31
	s_lshl_b64 s[22:23], s[24:25], 19
	s_add_u32 s26, s84, s22
	s_addc_u32 s27, s85, s23
	s_and_b64 s[22:23], s[4:5], exec
	s_cselect_b32 s25, s27, s15
	s_cselect_b32 s50, s26, s14
	s_ashr_i32 s21, s20, 31
	s_lshl_b64 s[22:23], s[20:21], 19
	s_add_u32 s28, s30, s22
	s_addc_u32 s29, s31, s23
	s_and_b64 s[22:23], s[4:5], exec
	s_cselect_b32 s21, s29, s3
	s_cselect_b32 s51, s28, s2
	s_add_u32 s14, s14, 0x40080
	s_addc_u32 s15, s15, 0
	s_add_u32 s52, s2, 0x100
	s_addc_u32 s53, s3, 0
	s_mov_b32 s54, -2
	s_waitcnt vmcnt(0)
	ds_read_b128 v[136:139], v155
	ds_read_b128 v[162:165], v155 offset:1024
	ds_read_b128 v[166:169], v155 offset:2048
	ds_read_b128 v[178:181], v155 offset:3072
	ds_read_b128 v[184:187], v158
	ds_read_b128 v[188:191], v158 offset:1024
	ds_read_b128 v[196:199], v158 offset:2048
	ds_read_b128 v[200:203], v158 offset:3072
	s_add_u32 s2, s14, 0xfffc0080
	s_addc_u32 s3, s15, -1
	s_cmp_eq_u32 s54, 12
	s_cselect_b32 s23, s25, s3
	s_cselect_b32 s22, s50, s2
	s_cselect_b32 s3, s21, s53
	s_cselect_b32 s2, s51, s52
	s_add_i32 m0, s37, 0xc000
	ds_read_b128 v[204:207], v159
	ds_read_b128 v[208:211], v159 offset:1024
	ds_read_b128 v[212:215], v159 offset:2048
	ds_read_b128 v[216:219], v159 offset:3072
	ds_read_b128 v[220:223], v159 offset:4096
	ds_read_b128 v[224:227], v159 offset:5120
	ds_read_b128 v[228:231], v159 offset:6144
	ds_read_b128 v[232:235], v159 offset:7168
	global_load_lds_dwordx4 v128, s[14:15]
	s_add_i32 m0, s37, 0xe000
	s_nop 0
	global_load_lds_dwordx4 v130, s[14:15]
	s_waitcnt vmcnt(8)
	s_waitcnt lgkmcnt(0)
	s_barrier
	s_setprio 1
	v_mfma_f32_16x16x32_bf16 v[112:115], v[136:139], v[204:207], 0
	v_mfma_f32_16x16x32_bf16 v[108:111], v[166:169], v[204:207], 0
	v_mfma_f32_16x16x32_bf16 v[104:107], v[136:139], v[212:215], 0
	v_mfma_f32_16x16x32_bf16 v[100:103], v[166:169], v[212:215], 0
	v_mfma_f32_16x16x32_bf16 v[92:95], v[136:139], v[220:223], 0
	v_mfma_f32_16x16x32_bf16 v[84:87], v[166:169], v[220:223], 0
	v_mfma_f32_16x16x32_bf16 v[76:79], v[136:139], v[228:231], 0
	v_mfma_f32_16x16x32_bf16 v[68:71], v[166:169], v[228:231], 0
	v_mfma_f32_16x16x32_bf16 v[112:115], v[162:165], v[208:211], v[112:115]
	v_mfma_f32_16x16x32_bf16 v[108:111], v[178:181], v[208:211], v[108:111]
	v_mfma_f32_16x16x32_bf16 v[104:107], v[162:165], v[216:219], v[104:107]
	v_mfma_f32_16x16x32_bf16 v[100:103], v[178:181], v[216:219], v[100:103]
	v_mfma_f32_16x16x32_bf16 v[92:95], v[162:165], v[224:227], v[92:95]
	v_mfma_f32_16x16x32_bf16 v[84:87], v[178:181], v[224:227], v[84:87]
	v_mfma_f32_16x16x32_bf16 v[76:79], v[162:165], v[232:235], v[76:79]
	v_mfma_f32_16x16x32_bf16 v[68:71], v[178:181], v[232:235], v[68:71]
	v_mfma_f32_16x16x32_bf16 v[124:127], v[184:187], v[204:207], 0
	v_mfma_f32_16x16x32_bf16 v[120:123], v[196:199], v[204:207], 0
	v_mfma_f32_16x16x32_bf16 v[116:119], v[184:187], v[212:215], 0
	v_mfma_f32_16x16x32_bf16 v[96:99], v[196:199], v[212:215], 0
	v_mfma_f32_16x16x32_bf16 v[88:91], v[184:187], v[220:223], 0
	v_mfma_f32_16x16x32_bf16 v[80:83], v[196:199], v[220:223], 0
	v_mfma_f32_16x16x32_bf16 v[72:75], v[184:187], v[228:231], 0
	v_mfma_f32_16x16x32_bf16 v[64:67], v[196:199], v[228:231], 0
	v_mfma_f32_16x16x32_bf16 v[124:127], v[188:191], v[208:211], v[124:127]
	v_mfma_f32_16x16x32_bf16 v[120:123], v[200:203], v[208:211], v[120:123]
	v_mfma_f32_16x16x32_bf16 v[116:119], v[188:191], v[216:219], v[116:119]
	v_mfma_f32_16x16x32_bf16 v[96:99], v[200:203], v[216:219], v[96:99]
	v_mfma_f32_16x16x32_bf16 v[88:91], v[188:191], v[224:227], v[88:91]
	v_mfma_f32_16x16x32_bf16 v[80:83], v[200:203], v[224:227], v[80:83]
	v_mfma_f32_16x16x32_bf16 v[72:75], v[188:191], v[232:235], v[72:75]
	v_mfma_f32_16x16x32_bf16 v[64:67], v[200:203], v[232:235], v[64:67]
	s_barrier
	s_setprio 0
	s_add_i32 s55, s46, s34
	s_add_u32 s98, s2, s12
	s_addc_u32 s99, s3, s13
	s_mov_b32 m0, s55
	ds_read_b128 v[204:207], v159 offset:16384
	ds_read_b128 v[208:211], v159 offset:17408
	ds_read_b128 v[212:215], v159 offset:18432
	ds_read_b128 v[216:219], v159 offset:19456
	ds_read_b128 v[220:223], v159 offset:20480
	ds_read_b128 v[224:227], v159 offset:21504
	ds_read_b128 v[228:231], v159 offset:22528
	ds_read_b128 v[232:235], v159 offset:23552
	global_load_lds_dwordx4 v142, s[2:3]
	s_add_i32 m0, s55, 0x2000
	s_add_u32 s56, s2, 0x40000
	s_addc_u32 s57, s3, 0
	s_add_i32 s55, s47, s34
	global_load_lds_dwordx4 v146, s[2:3]
	s_mov_b32 m0, s55
	s_nop 0
	global_load_lds_dwordx4 v142, s[56:57]
	s_add_i32 m0, s55, 0x2000
	s_nop 0
	global_load_lds_dwordx4 v146, s[56:57]
	s_add_u32 s100, s22, s12
	s_addc_u32 s101, s23, s13
	s_mov_b32 m0, s37
	s_nop 0
	global_load_lds_dwordx4 v140, s[22:23]
	s_mov_b32 m0, s38
	s_nop 0
	global_load_lds_dwordx4 v144, s[22:23]
	s_waitcnt vmcnt(8)
	s_waitcnt lgkmcnt(0)
	s_barrier
	s_setprio 1
	v_mfma_f32_16x16x32_bf16 v[60:63], v[136:139], v[204:207], 0
	v_mfma_f32_16x16x32_bf16 v[52:55], v[166:169], v[204:207], 0
	v_mfma_f32_16x16x32_bf16 v[44:47], v[136:139], v[212:215], 0
	v_mfma_f32_16x16x32_bf16 v[36:39], v[166:169], v[212:215], 0
	v_mfma_f32_16x16x32_bf16 v[28:31], v[136:139], v[220:223], 0
	v_mfma_f32_16x16x32_bf16 v[20:23], v[166:169], v[220:223], 0
	v_mfma_f32_16x16x32_bf16 v[12:15], v[136:139], v[228:231], 0
	v_mfma_f32_16x16x32_bf16 v[4:7], v[166:169], v[228:231], 0
	v_mfma_f32_16x16x32_bf16 v[60:63], v[162:165], v[208:211], v[60:63]
	v_mfma_f32_16x16x32_bf16 v[52:55], v[178:181], v[208:211], v[52:55]
	v_mfma_f32_16x16x32_bf16 v[44:47], v[162:165], v[216:219], v[44:47]
	v_mfma_f32_16x16x32_bf16 v[36:39], v[178:181], v[216:219], v[36:39]
	v_mfma_f32_16x16x32_bf16 v[28:31], v[162:165], v[224:227], v[28:31]
	v_mfma_f32_16x16x32_bf16 v[20:23], v[178:181], v[224:227], v[20:23]
	v_mfma_f32_16x16x32_bf16 v[12:15], v[162:165], v[232:235], v[12:15]
	v_mfma_f32_16x16x32_bf16 v[4:7], v[178:181], v[232:235], v[4:7]
	v_mfma_f32_16x16x32_bf16 v[56:59], v[184:187], v[204:207], 0
	v_mfma_f32_16x16x32_bf16 v[48:51], v[196:199], v[204:207], 0
	v_mfma_f32_16x16x32_bf16 v[40:43], v[184:187], v[212:215], 0
	v_mfma_f32_16x16x32_bf16 v[32:35], v[196:199], v[212:215], 0
	v_mfma_f32_16x16x32_bf16 v[24:27], v[184:187], v[220:223], 0
	v_mfma_f32_16x16x32_bf16 v[16:19], v[196:199], v[220:223], 0
	v_mfma_f32_16x16x32_bf16 v[8:11], v[184:187], v[228:231], 0
	v_mfma_f32_16x16x32_bf16 v[0:3], v[196:199], v[228:231], 0
	v_mfma_f32_16x16x32_bf16 v[56:59], v[188:191], v[208:211], v[56:59]
	v_mfma_f32_16x16x32_bf16 v[48:51], v[200:203], v[208:211], v[48:51]
	v_mfma_f32_16x16x32_bf16 v[40:43], v[188:191], v[216:219], v[40:43]
	v_mfma_f32_16x16x32_bf16 v[32:35], v[200:203], v[216:219], v[32:35]
	v_mfma_f32_16x16x32_bf16 v[24:27], v[188:191], v[224:227], v[24:27]
	v_mfma_f32_16x16x32_bf16 v[16:19], v[200:203], v[224:227], v[16:19]
	v_mfma_f32_16x16x32_bf16 v[8:11], v[188:191], v[232:235], v[8:11]
	v_mfma_f32_16x16x32_bf16 v[0:3], v[200:203], v[232:235], v[0:3]
	s_barrier
	s_setprio 0
	s_add_i32 s55, 0, 0x18000
	v_add_u32_e32 v161, s55, v151
	s_add_i32 s56, 0, 0x1c000
	ds_read_b128 v[136:139], v161
	ds_read_b128 v[162:165], v161 offset:1024
	ds_read_b128 v[166:169], v161 offset:2048
	ds_read_b128 v[178:181], v161 offset:3072
	v_add_u32_e32 v161, s56, v151
	ds_read_b128 v[184:187], v161
	ds_read_b128 v[188:191], v161 offset:1024
	ds_read_b128 v[196:199], v161 offset:2048
	ds_read_b128 v[200:203], v161 offset:3072
	s_add_u32 s22, s22, 0x40000
	s_addc_u32 s23, s23, 0
	s_mov_b32 m0, s39
	ds_read_b128 v[204:207], v159 offset:32768
	ds_read_b128 v[208:211], v159 offset:33792
	ds_read_b128 v[212:215], v159 offset:34816
	ds_read_b128 v[216:219], v159 offset:35840
	ds_read_b128 v[220:223], v159 offset:36864
	ds_read_b128 v[224:227], v159 offset:37888
	ds_read_b128 v[228:231], v159 offset:38912
	ds_read_b128 v[232:235], v159 offset:39936
	global_load_lds_dwordx4 v140, s[22:23]
	s_mov_b32 m0, s40
	s_nop 0
	global_load_lds_dwordx4 v144, s[22:23]
	s_waitcnt vmcnt(8)
	s_waitcnt lgkmcnt(0)
	s_barrier
	s_setprio 1
	v_mfma_f32_16x16x32_bf16 v[112:115], v[136:139], v[204:207], v[112:115]
	v_mfma_f32_16x16x32_bf16 v[108:111], v[166:169], v[204:207], v[108:111]
	v_mfma_f32_16x16x32_bf16 v[104:107], v[136:139], v[212:215], v[104:107]
	v_mfma_f32_16x16x32_bf16 v[100:103], v[166:169], v[212:215], v[100:103]
	v_mfma_f32_16x16x32_bf16 v[92:95], v[136:139], v[220:223], v[92:95]
	v_mfma_f32_16x16x32_bf16 v[84:87], v[166:169], v[220:223], v[84:87]
	v_mfma_f32_16x16x32_bf16 v[76:79], v[136:139], v[228:231], v[76:79]
	v_mfma_f32_16x16x32_bf16 v[68:71], v[166:169], v[228:231], v[68:71]
	v_mfma_f32_16x16x32_bf16 v[112:115], v[162:165], v[208:211], v[112:115]
	v_mfma_f32_16x16x32_bf16 v[108:111], v[178:181], v[208:211], v[108:111]
	v_mfma_f32_16x16x32_bf16 v[104:107], v[162:165], v[216:219], v[104:107]
	v_mfma_f32_16x16x32_bf16 v[100:103], v[178:181], v[216:219], v[100:103]
	v_mfma_f32_16x16x32_bf16 v[92:95], v[162:165], v[224:227], v[92:95]
	v_mfma_f32_16x16x32_bf16 v[84:87], v[178:181], v[224:227], v[84:87]
	v_mfma_f32_16x16x32_bf16 v[76:79], v[162:165], v[232:235], v[76:79]
	v_mfma_f32_16x16x32_bf16 v[68:71], v[178:181], v[232:235], v[68:71]
	v_mfma_f32_16x16x32_bf16 v[124:127], v[184:187], v[204:207], v[124:127]
	v_mfma_f32_16x16x32_bf16 v[120:123], v[196:199], v[204:207], v[120:123]
	v_mfma_f32_16x16x32_bf16 v[116:119], v[184:187], v[212:215], v[116:119]
	v_mfma_f32_16x16x32_bf16 v[96:99], v[196:199], v[212:215], v[96:99]
	v_mfma_f32_16x16x32_bf16 v[88:91], v[184:187], v[220:223], v[88:91]
	v_mfma_f32_16x16x32_bf16 v[80:83], v[196:199], v[220:223], v[80:83]
	v_mfma_f32_16x16x32_bf16 v[72:75], v[184:187], v[228:231], v[72:75]
	v_mfma_f32_16x16x32_bf16 v[64:67], v[196:199], v[228:231], v[64:67]
	v_mfma_f32_16x16x32_bf16 v[124:127], v[188:191], v[208:211], v[124:127]
	v_mfma_f32_16x16x32_bf16 v[120:123], v[200:203], v[208:211], v[120:123]
	v_mfma_f32_16x16x32_bf16 v[116:119], v[188:191], v[216:219], v[116:119]
	v_mfma_f32_16x16x32_bf16 v[96:99], v[200:203], v[216:219], v[96:99]
	v_mfma_f32_16x16x32_bf16 v[88:91], v[188:191], v[224:227], v[88:91]
	v_mfma_f32_16x16x32_bf16 v[80:83], v[200:203], v[224:227], v[80:83]
	v_mfma_f32_16x16x32_bf16 v[72:75], v[188:191], v[232:235], v[72:75]
	v_mfma_f32_16x16x32_bf16 v[64:67], v[200:203], v[232:235], v[64:67]
	s_barrier
	s_setprio 0
	s_add_i32 s22, s55, s34
	s_mov_b32 m0, s22
	ds_read_b128 v[204:207], v159 offset:49152
	ds_read_b128 v[208:211], v159 offset:50176
	ds_read_b128 v[212:215], v159 offset:51200
	ds_read_b128 v[216:219], v159 offset:52224
	ds_read_b128 v[220:223], v159 offset:53248
	ds_read_b128 v[224:227], v159 offset:54272
	ds_read_b128 v[228:231], v159 offset:55296
	ds_read_b128 v[232:235], v159 offset:56320
	global_load_lds_dwordx4 v142, s[98:99]
	s_add_i32 m0, s22, 0x2000
	s_add_u32 s2, s2, 0x40080
	s_addc_u32 s3, s3, 0
	s_add_i32 s22, s56, s34
	global_load_lds_dwordx4 v146, s[98:99]
	s_mov_b32 m0, s22
	s_nop 0
	global_load_lds_dwordx4 v142, s[2:3]
	s_add_i32 m0, s22, 0x2000
	s_nop 0
	global_load_lds_dwordx4 v146, s[2:3]
	s_mov_b32 m0, s42
	s_nop 0
	global_load_lds_dwordx4 v140, s[100:101]
	s_mov_b32 m0, s43
	s_nop 0
	global_load_lds_dwordx4 v144, s[100:101]
	s_waitcnt vmcnt(8)
	s_waitcnt lgkmcnt(0)
	s_barrier
	s_setprio 1
	v_mfma_f32_16x16x32_bf16 v[60:63], v[136:139], v[204:207], v[60:63]
	v_mfma_f32_16x16x32_bf16 v[52:55], v[166:169], v[204:207], v[52:55]
	v_mfma_f32_16x16x32_bf16 v[44:47], v[136:139], v[212:215], v[44:47]
	v_mfma_f32_16x16x32_bf16 v[36:39], v[166:169], v[212:215], v[36:39]
	v_mfma_f32_16x16x32_bf16 v[28:31], v[136:139], v[220:223], v[28:31]
	v_mfma_f32_16x16x32_bf16 v[20:23], v[166:169], v[220:223], v[20:23]
	v_mfma_f32_16x16x32_bf16 v[12:15], v[136:139], v[228:231], v[12:15]
	v_mfma_f32_16x16x32_bf16 v[4:7], v[166:169], v[228:231], v[4:7]
	v_mfma_f32_16x16x32_bf16 v[60:63], v[162:165], v[208:211], v[60:63]
	v_mfma_f32_16x16x32_bf16 v[52:55], v[178:181], v[208:211], v[52:55]
	v_mfma_f32_16x16x32_bf16 v[44:47], v[162:165], v[216:219], v[44:47]
	v_mfma_f32_16x16x32_bf16 v[36:39], v[178:181], v[216:219], v[36:39]
	v_mfma_f32_16x16x32_bf16 v[28:31], v[162:165], v[224:227], v[28:31]
	v_mfma_f32_16x16x32_bf16 v[20:23], v[178:181], v[224:227], v[20:23]
	v_mfma_f32_16x16x32_bf16 v[12:15], v[162:165], v[232:235], v[12:15]
	v_mfma_f32_16x16x32_bf16 v[4:7], v[178:181], v[232:235], v[4:7]
	v_mfma_f32_16x16x32_bf16 v[56:59], v[184:187], v[204:207], v[56:59]
	v_mfma_f32_16x16x32_bf16 v[48:51], v[196:199], v[204:207], v[48:51]
	v_mfma_f32_16x16x32_bf16 v[40:43], v[184:187], v[212:215], v[40:43]
	v_mfma_f32_16x16x32_bf16 v[32:35], v[196:199], v[212:215], v[32:35]
	v_mfma_f32_16x16x32_bf16 v[24:27], v[184:187], v[220:223], v[24:27]
	v_mfma_f32_16x16x32_bf16 v[16:19], v[196:199], v[220:223], v[16:19]
	v_mfma_f32_16x16x32_bf16 v[8:11], v[184:187], v[228:231], v[8:11]
	v_mfma_f32_16x16x32_bf16 v[0:3], v[196:199], v[228:231], v[0:3]
	v_mfma_f32_16x16x32_bf16 v[56:59], v[188:191], v[208:211], v[56:59]
	v_mfma_f32_16x16x32_bf16 v[48:51], v[200:203], v[208:211], v[48:51]
	v_mfma_f32_16x16x32_bf16 v[40:43], v[188:191], v[216:219], v[40:43]
	v_mfma_f32_16x16x32_bf16 v[32:35], v[200:203], v[216:219], v[32:35]
	v_mfma_f32_16x16x32_bf16 v[24:27], v[188:191], v[224:227], v[24:27]
	v_mfma_f32_16x16x32_bf16 v[16:19], v[200:203], v[224:227], v[16:19]
	v_mfma_f32_16x16x32_bf16 v[8:11], v[188:191], v[232:235], v[8:11]
	v_mfma_f32_16x16x32_bf16 v[0:3], v[200:203], v[232:235], v[0:3]
	s_barrier
	s_setprio 0
	s_add_i32 s54, s54, 2
	s_add_u32 s14, s14, 0x100
	s_addc_u32 s15, s15, 0
	s_add_u32 s52, s52, 0x100
	s_addc_u32 s53, s53, 0
	s_cmp_gt_u32 s54, 13
	s_cbranch_scc1 .Lgemm_kdone_5
.LBB0_809:
	ds_read_b128 v[136:139], v155
	ds_read_b128 v[162:165], v155 offset:1024
	ds_read_b128 v[166:169], v155 offset:2048
	ds_read_b128 v[178:181], v155 offset:3072
	ds_read_b128 v[184:187], v158
	ds_read_b128 v[188:191], v158 offset:1024
	ds_read_b128 v[196:199], v158 offset:2048
	ds_read_b128 v[200:203], v158 offset:3072
	s_add_u32 s2, s14, 0xfffc0080
	s_addc_u32 s3, s15, -1
	s_cmp_eq_u32 s54, 12
	s_cselect_b32 s23, s25, s3
	s_cselect_b32 s22, s50, s2
	s_cselect_b32 s3, s21, s53
	s_cselect_b32 s2, s51, s52
	s_add_i32 m0, s37, 0xc000
	ds_read_b128 v[204:207], v159
	ds_read_b128 v[208:211], v159 offset:1024
	ds_read_b128 v[212:215], v159 offset:2048
	ds_read_b128 v[216:219], v159 offset:3072
	ds_read_b128 v[220:223], v159 offset:4096
	ds_read_b128 v[224:227], v159 offset:5120
	ds_read_b128 v[228:231], v159 offset:6144
	ds_read_b128 v[232:235], v159 offset:7168
	global_load_lds_dwordx4 v128, s[14:15]
	s_add_i32 m0, s37, 0xe000
	s_nop 0
	global_load_lds_dwordx4 v130, s[14:15]
	s_waitcnt vmcnt(8)
	s_waitcnt lgkmcnt(0)
	s_barrier
	s_setprio 1
	v_mfma_f32_16x16x32_bf16 v[112:115], v[136:139], v[204:207], v[112:115]
	v_mfma_f32_16x16x32_bf16 v[108:111], v[166:169], v[204:207], v[108:111]
	v_mfma_f32_16x16x32_bf16 v[104:107], v[136:139], v[212:215], v[104:107]
	v_mfma_f32_16x16x32_bf16 v[100:103], v[166:169], v[212:215], v[100:103]
	v_mfma_f32_16x16x32_bf16 v[92:95], v[136:139], v[220:223], v[92:95]
	v_mfma_f32_16x16x32_bf16 v[84:87], v[166:169], v[220:223], v[84:87]
	v_mfma_f32_16x16x32_bf16 v[76:79], v[136:139], v[228:231], v[76:79]
	v_mfma_f32_16x16x32_bf16 v[68:71], v[166:169], v[228:231], v[68:71]
	v_mfma_f32_16x16x32_bf16 v[112:115], v[162:165], v[208:211], v[112:115]
	v_mfma_f32_16x16x32_bf16 v[108:111], v[178:181], v[208:211], v[108:111]
	v_mfma_f32_16x16x32_bf16 v[104:107], v[162:165], v[216:219], v[104:107]
	v_mfma_f32_16x16x32_bf16 v[100:103], v[178:181], v[216:219], v[100:103]
	v_mfma_f32_16x16x32_bf16 v[92:95], v[162:165], v[224:227], v[92:95]
	v_mfma_f32_16x16x32_bf16 v[84:87], v[178:181], v[224:227], v[84:87]
	v_mfma_f32_16x16x32_bf16 v[76:79], v[162:165], v[232:235], v[76:79]
	v_mfma_f32_16x16x32_bf16 v[68:71], v[178:181], v[232:235], v[68:71]
	v_mfma_f32_16x16x32_bf16 v[124:127], v[184:187], v[204:207], v[124:127]
	v_mfma_f32_16x16x32_bf16 v[120:123], v[196:199], v[204:207], v[120:123]
	v_mfma_f32_16x16x32_bf16 v[116:119], v[184:187], v[212:215], v[116:119]
	v_mfma_f32_16x16x32_bf16 v[96:99], v[196:199], v[212:215], v[96:99]
	v_mfma_f32_16x16x32_bf16 v[88:91], v[184:187], v[220:223], v[88:91]
	v_mfma_f32_16x16x32_bf16 v[80:83], v[196:199], v[220:223], v[80:83]
	v_mfma_f32_16x16x32_bf16 v[72:75], v[184:187], v[228:231], v[72:75]
	v_mfma_f32_16x16x32_bf16 v[64:67], v[196:199], v[228:231], v[64:67]
	v_mfma_f32_16x16x32_bf16 v[124:127], v[188:191], v[208:211], v[124:127]
	v_mfma_f32_16x16x32_bf16 v[120:123], v[200:203], v[208:211], v[120:123]
	v_mfma_f32_16x16x32_bf16 v[116:119], v[188:191], v[216:219], v[116:119]
	v_mfma_f32_16x16x32_bf16 v[96:99], v[200:203], v[216:219], v[96:99]
	v_mfma_f32_16x16x32_bf16 v[88:91], v[188:191], v[224:227], v[88:91]
	v_mfma_f32_16x16x32_bf16 v[80:83], v[200:203], v[224:227], v[80:83]
	v_mfma_f32_16x16x32_bf16 v[72:75], v[188:191], v[232:235], v[72:75]
	v_mfma_f32_16x16x32_bf16 v[64:67], v[200:203], v[232:235], v[64:67]
	s_barrier
	s_setprio 0
	s_add_i32 s55, s46, s34
	s_add_u32 s98, s2, s12
	s_addc_u32 s99, s3, s13
	s_mov_b32 m0, s55
	ds_read_b128 v[204:207], v159 offset:16384
	ds_read_b128 v[208:211], v159 offset:17408
	ds_read_b128 v[212:215], v159 offset:18432
	ds_read_b128 v[216:219], v159 offset:19456
	ds_read_b128 v[220:223], v159 offset:20480
	ds_read_b128 v[224:227], v159 offset:21504
	ds_read_b128 v[228:231], v159 offset:22528
	ds_read_b128 v[232:235], v159 offset:23552
	global_load_lds_dwordx4 v142, s[2:3]
	s_add_i32 m0, s55, 0x2000
	s_add_u32 s56, s2, 0x40000
	s_addc_u32 s57, s3, 0
	s_add_i32 s55, s47, s34
	global_load_lds_dwordx4 v146, s[2:3]
	s_mov_b32 m0, s55
	s_nop 0
	global_load_lds_dwordx4 v142, s[56:57]
	s_add_i32 m0, s55, 0x2000
	s_nop 0
	global_load_lds_dwordx4 v146, s[56:57]
	s_add_u32 s100, s22, s12
	s_addc_u32 s101, s23, s13
	s_mov_b32 m0, s37
	s_nop 0
	global_load_lds_dwordx4 v140, s[22:23]
	s_mov_b32 m0, s38
	s_nop 0
	global_load_lds_dwordx4 v144, s[22:23]
	s_waitcnt vmcnt(8)
	s_waitcnt lgkmcnt(0)
	s_barrier
	s_setprio 1
	v_mfma_f32_16x16x32_bf16 v[60:63], v[136:139], v[204:207], v[60:63]
	v_mfma_f32_16x16x32_bf16 v[52:55], v[166:169], v[204:207], v[52:55]
	v_mfma_f32_16x16x32_bf16 v[44:47], v[136:139], v[212:215], v[44:47]
	v_mfma_f32_16x16x32_bf16 v[36:39], v[166:169], v[212:215], v[36:39]
	v_mfma_f32_16x16x32_bf16 v[28:31], v[136:139], v[220:223], v[28:31]
	v_mfma_f32_16x16x32_bf16 v[20:23], v[166:169], v[220:223], v[20:23]
	v_mfma_f32_16x16x32_bf16 v[12:15], v[136:139], v[228:231], v[12:15]
	v_mfma_f32_16x16x32_bf16 v[4:7], v[166:169], v[228:231], v[4:7]
	v_mfma_f32_16x16x32_bf16 v[60:63], v[162:165], v[208:211], v[60:63]
	v_mfma_f32_16x16x32_bf16 v[52:55], v[178:181], v[208:211], v[52:55]
	v_mfma_f32_16x16x32_bf16 v[44:47], v[162:165], v[216:219], v[44:47]
	v_mfma_f32_16x16x32_bf16 v[36:39], v[178:181], v[216:219], v[36:39]
	v_mfma_f32_16x16x32_bf16 v[28:31], v[162:165], v[224:227], v[28:31]
	v_mfma_f32_16x16x32_bf16 v[20:23], v[178:181], v[224:227], v[20:23]
	v_mfma_f32_16x16x32_bf16 v[12:15], v[162:165], v[232:235], v[12:15]
	v_mfma_f32_16x16x32_bf16 v[4:7], v[178:181], v[232:235], v[4:7]
	v_mfma_f32_16x16x32_bf16 v[56:59], v[184:187], v[204:207], v[56:59]
	v_mfma_f32_16x16x32_bf16 v[48:51], v[196:199], v[204:207], v[48:51]
	v_mfma_f32_16x16x32_bf16 v[40:43], v[184:187], v[212:215], v[40:43]
	v_mfma_f32_16x16x32_bf16 v[32:35], v[196:199], v[212:215], v[32:35]
	v_mfma_f32_16x16x32_bf16 v[24:27], v[184:187], v[220:223], v[24:27]
	v_mfma_f32_16x16x32_bf16 v[16:19], v[196:199], v[220:223], v[16:19]
	v_mfma_f32_16x16x32_bf16 v[8:11], v[184:187], v[228:231], v[8:11]
	v_mfma_f32_16x16x32_bf16 v[0:3], v[196:199], v[228:231], v[0:3]
	v_mfma_f32_16x16x32_bf16 v[56:59], v[188:191], v[208:211], v[56:59]
	v_mfma_f32_16x16x32_bf16 v[48:51], v[200:203], v[208:211], v[48:51]
	v_mfma_f32_16x16x32_bf16 v[40:43], v[188:191], v[216:219], v[40:43]
	v_mfma_f32_16x16x32_bf16 v[32:35], v[200:203], v[216:219], v[32:35]
	v_mfma_f32_16x16x32_bf16 v[24:27], v[188:191], v[224:227], v[24:27]
	v_mfma_f32_16x16x32_bf16 v[16:19], v[200:203], v[224:227], v[16:19]
	v_mfma_f32_16x16x32_bf16 v[8:11], v[188:191], v[232:235], v[8:11]
	v_mfma_f32_16x16x32_bf16 v[0:3], v[200:203], v[232:235], v[0:3]
	s_barrier
	s_setprio 0
	s_add_i32 s55, 0, 0x18000
	v_add_u32_e32 v161, s55, v151
	s_add_i32 s56, 0, 0x1c000
	ds_read_b128 v[136:139], v161
	ds_read_b128 v[162:165], v161 offset:1024
	ds_read_b128 v[166:169], v161 offset:2048
	ds_read_b128 v[178:181], v161 offset:3072
	v_add_u32_e32 v161, s56, v151
	ds_read_b128 v[184:187], v161
	ds_read_b128 v[188:191], v161 offset:1024
	ds_read_b128 v[196:199], v161 offset:2048
	ds_read_b128 v[200:203], v161 offset:3072
	s_add_u32 s22, s22, 0x40000
	s_addc_u32 s23, s23, 0
	s_mov_b32 m0, s39
	ds_read_b128 v[204:207], v159 offset:32768
	ds_read_b128 v[208:211], v159 offset:33792
	ds_read_b128 v[212:215], v159 offset:34816
	ds_read_b128 v[216:219], v159 offset:35840
	ds_read_b128 v[220:223], v159 offset:36864
	ds_read_b128 v[224:227], v159 offset:37888
	ds_read_b128 v[228:231], v159 offset:38912
	ds_read_b128 v[232:235], v159 offset:39936
	global_load_lds_dwordx4 v140, s[22:23]
	s_mov_b32 m0, s40
	s_nop 0
	global_load_lds_dwordx4 v144, s[22:23]
	s_waitcnt vmcnt(8)
	s_waitcnt lgkmcnt(0)
	s_barrier
	s_setprio 1
	v_mfma_f32_16x16x32_bf16 v[112:115], v[136:139], v[204:207], v[112:115]
	v_mfma_f32_16x16x32_bf16 v[108:111], v[166:169], v[204:207], v[108:111]
	v_mfma_f32_16x16x32_bf16 v[104:107], v[136:139], v[212:215], v[104:107]
	v_mfma_f32_16x16x32_bf16 v[100:103], v[166:169], v[212:215], v[100:103]
	v_mfma_f32_16x16x32_bf16 v[92:95], v[136:139], v[220:223], v[92:95]
	v_mfma_f32_16x16x32_bf16 v[84:87], v[166:169], v[220:223], v[84:87]
	v_mfma_f32_16x16x32_bf16 v[76:79], v[136:139], v[228:231], v[76:79]
	v_mfma_f32_16x16x32_bf16 v[68:71], v[166:169], v[228:231], v[68:71]
	v_mfma_f32_16x16x32_bf16 v[112:115], v[162:165], v[208:211], v[112:115]
	v_mfma_f32_16x16x32_bf16 v[108:111], v[178:181], v[208:211], v[108:111]
	v_mfma_f32_16x16x32_bf16 v[104:107], v[162:165], v[216:219], v[104:107]
	v_mfma_f32_16x16x32_bf16 v[100:103], v[178:181], v[216:219], v[100:103]
	v_mfma_f32_16x16x32_bf16 v[92:95], v[162:165], v[224:227], v[92:95]
	v_mfma_f32_16x16x32_bf16 v[84:87], v[178:181], v[224:227], v[84:87]
	v_mfma_f32_16x16x32_bf16 v[76:79], v[162:165], v[232:235], v[76:79]
	v_mfma_f32_16x16x32_bf16 v[68:71], v[178:181], v[232:235], v[68:71]
	v_mfma_f32_16x16x32_bf16 v[124:127], v[184:187], v[204:207], v[124:127]
	v_mfma_f32_16x16x32_bf16 v[120:123], v[196:199], v[204:207], v[120:123]
	v_mfma_f32_16x16x32_bf16 v[116:119], v[184:187], v[212:215], v[116:119]
	v_mfma_f32_16x16x32_bf16 v[96:99], v[196:199], v[212:215], v[96:99]
	v_mfma_f32_16x16x32_bf16 v[88:91], v[184:187], v[220:223], v[88:91]
	v_mfma_f32_16x16x32_bf16 v[80:83], v[196:199], v[220:223], v[80:83]
	v_mfma_f32_16x16x32_bf16 v[72:75], v[184:187], v[228:231], v[72:75]
	v_mfma_f32_16x16x32_bf16 v[64:67], v[196:199], v[228:231], v[64:67]
	v_mfma_f32_16x16x32_bf16 v[124:127], v[188:191], v[208:211], v[124:127]
	v_mfma_f32_16x16x32_bf16 v[120:123], v[200:203], v[208:211], v[120:123]
	v_mfma_f32_16x16x32_bf16 v[116:119], v[188:191], v[216:219], v[116:119]
	v_mfma_f32_16x16x32_bf16 v[96:99], v[200:203], v[216:219], v[96:99]
	v_mfma_f32_16x16x32_bf16 v[88:91], v[188:191], v[224:227], v[88:91]
	v_mfma_f32_16x16x32_bf16 v[80:83], v[200:203], v[224:227], v[80:83]
	v_mfma_f32_16x16x32_bf16 v[72:75], v[188:191], v[232:235], v[72:75]
	v_mfma_f32_16x16x32_bf16 v[64:67], v[200:203], v[232:235], v[64:67]
	s_barrier
	s_setprio 0
	s_add_i32 s22, s55, s34
	s_mov_b32 m0, s22
	ds_read_b128 v[204:207], v159 offset:49152
	ds_read_b128 v[208:211], v159 offset:50176
	ds_read_b128 v[212:215], v159 offset:51200
	ds_read_b128 v[216:219], v159 offset:52224
	ds_read_b128 v[220:223], v159 offset:53248
	ds_read_b128 v[224:227], v159 offset:54272
	ds_read_b128 v[228:231], v159 offset:55296
	ds_read_b128 v[232:235], v159 offset:56320
	global_load_lds_dwordx4 v142, s[98:99]
	s_add_i32 m0, s22, 0x2000
	s_add_u32 s2, s2, 0x40080
	s_addc_u32 s3, s3, 0
	s_add_i32 s22, s56, s34
	global_load_lds_dwordx4 v146, s[98:99]
	s_mov_b32 m0, s22
	s_nop 0
	global_load_lds_dwordx4 v142, s[2:3]
	s_add_i32 m0, s22, 0x2000
	s_nop 0
	global_load_lds_dwordx4 v146, s[2:3]
	s_mov_b32 m0, s42
	s_nop 0
	global_load_lds_dwordx4 v140, s[100:101]
	s_mov_b32 m0, s43
	s_nop 0
	global_load_lds_dwordx4 v144, s[100:101]
	s_waitcnt vmcnt(8)
	s_waitcnt lgkmcnt(0)
	s_barrier
	s_setprio 1
	v_mfma_f32_16x16x32_bf16 v[60:63], v[136:139], v[204:207], v[60:63]
	v_mfma_f32_16x16x32_bf16 v[52:55], v[166:169], v[204:207], v[52:55]
	v_mfma_f32_16x16x32_bf16 v[44:47], v[136:139], v[212:215], v[44:47]
	v_mfma_f32_16x16x32_bf16 v[36:39], v[166:169], v[212:215], v[36:39]
	v_mfma_f32_16x16x32_bf16 v[28:31], v[136:139], v[220:223], v[28:31]
	v_mfma_f32_16x16x32_bf16 v[20:23], v[166:169], v[220:223], v[20:23]
	v_mfma_f32_16x16x32_bf16 v[12:15], v[136:139], v[228:231], v[12:15]
	v_mfma_f32_16x16x32_bf16 v[4:7], v[166:169], v[228:231], v[4:7]
	v_mfma_f32_16x16x32_bf16 v[60:63], v[162:165], v[208:211], v[60:63]
	v_mfma_f32_16x16x32_bf16 v[52:55], v[178:181], v[208:211], v[52:55]
	v_mfma_f32_16x16x32_bf16 v[44:47], v[162:165], v[216:219], v[44:47]
	v_mfma_f32_16x16x32_bf16 v[36:39], v[178:181], v[216:219], v[36:39]
	v_mfma_f32_16x16x32_bf16 v[28:31], v[162:165], v[224:227], v[28:31]
	v_mfma_f32_16x16x32_bf16 v[20:23], v[178:181], v[224:227], v[20:23]
	v_mfma_f32_16x16x32_bf16 v[12:15], v[162:165], v[232:235], v[12:15]
	v_mfma_f32_16x16x32_bf16 v[4:7], v[178:181], v[232:235], v[4:7]
	v_mfma_f32_16x16x32_bf16 v[56:59], v[184:187], v[204:207], v[56:59]
	v_mfma_f32_16x16x32_bf16 v[48:51], v[196:199], v[204:207], v[48:51]
	v_mfma_f32_16x16x32_bf16 v[40:43], v[184:187], v[212:215], v[40:43]
	v_mfma_f32_16x16x32_bf16 v[32:35], v[196:199], v[212:215], v[32:35]
	v_mfma_f32_16x16x32_bf16 v[24:27], v[184:187], v[220:223], v[24:27]
	v_mfma_f32_16x16x32_bf16 v[16:19], v[196:199], v[220:223], v[16:19]
	v_mfma_f32_16x16x32_bf16 v[8:11], v[184:187], v[228:231], v[8:11]
	v_mfma_f32_16x16x32_bf16 v[0:3], v[196:199], v[228:231], v[0:3]
	v_mfma_f32_16x16x32_bf16 v[56:59], v[188:191], v[208:211], v[56:59]
	v_mfma_f32_16x16x32_bf16 v[48:51], v[200:203], v[208:211], v[48:51]
	v_mfma_f32_16x16x32_bf16 v[40:43], v[188:191], v[216:219], v[40:43]
	v_mfma_f32_16x16x32_bf16 v[32:35], v[200:203], v[216:219], v[32:35]
	v_mfma_f32_16x16x32_bf16 v[24:27], v[188:191], v[224:227], v[24:27]
	v_mfma_f32_16x16x32_bf16 v[16:19], v[200:203], v[224:227], v[16:19]
	v_mfma_f32_16x16x32_bf16 v[8:11], v[188:191], v[232:235], v[8:11]
	v_mfma_f32_16x16x32_bf16 v[0:3], v[200:203], v[232:235], v[0:3]
	s_barrier
	s_setprio 0
	s_add_i32 s54, s54, 2
	s_add_u32 s14, s14, 0x100
	s_addc_u32 s15, s15, 0
	s_add_u32 s52, s52, 0x100
	s_addc_u32 s53, s53, 0
	s_cmp_gt_u32 s54, 13
	s_cbranch_scc0 .LBB0_809

.LBB0_890:
	s_add_u32 s14, s14, 0xb0080
	s_addc_u32 s15, s15, 0
	s_add_u32 s53, s2, 0x100
	s_addc_u32 s54, s3, 0
	s_mov_b32 s55, -2
	s_waitcnt lgkmcnt(0)
	s_waitcnt vmcnt(0)
	ds_read_b128 v[128:131], v165
	ds_read_b128 v[132:135], v165 offset:1024
	ds_read_b128 v[136:139], v165 offset:2048
	ds_read_b128 v[156:159], v165 offset:3072
	ds_read_b128 v[172:175], v166
	ds_read_b128 v[176:179], v166 offset:1024
	ds_read_b128 v[180:183], v166 offset:2048
	ds_read_b128 v[184:187], v166 offset:3072
	s_add_u32 s2, s14, 0xfff50080
	s_addc_u32 s3, s15, -1
	s_cmp_eq_u32 s55, 40
	s_cselect_b32 s23, s1, s3
	s_cselect_b32 s22, s0, s2
	s_cselect_b32 s3, s21, s54
	s_cselect_b32 s2, s20, s53
	s_add_i32 m0, s27, 0xc000
	ds_read_b128 v[188:191], v167
	ds_read_b128 v[196:199], v167 offset:1024
	ds_read_b128 v[200:203], v167 offset:2048
	ds_read_b128 v[204:207], v167 offset:3072
	ds_read_b128 v[208:211], v167 offset:4096
	ds_read_b128 v[212:215], v167 offset:5120
	ds_read_b128 v[216:219], v167 offset:6144
	ds_read_b128 v[220:223], v167 offset:7168
	global_load_lds_dwordx4 v140, s[14:15]
	s_add_i32 m0, s27, 0xe000
	s_nop 0
	global_load_lds_dwordx4 v142, s[14:15]
	s_waitcnt vmcnt(8)
	s_waitcnt lgkmcnt(0)
	s_barrier
	s_setprio 1
	v_mfma_f32_16x16x32_bf16 v[124:127], v[128:131], v[188:191], 0
	v_mfma_f32_16x16x32_bf16 v[120:123], v[136:139], v[188:191], 0
	v_mfma_f32_16x16x32_bf16 v[108:111], v[128:131], v[200:203], 0
	v_mfma_f32_16x16x32_bf16 v[104:107], v[136:139], v[200:203], 0
	v_mfma_f32_16x16x32_bf16 v[92:95], v[128:131], v[208:211], 0
	v_mfma_f32_16x16x32_bf16 v[88:91], v[136:139], v[208:211], 0
	v_mfma_f32_16x16x32_bf16 v[76:79], v[128:131], v[216:219], 0
	v_mfma_f32_16x16x32_bf16 v[72:75], v[136:139], v[216:219], 0
	v_mfma_f32_16x16x32_bf16 v[124:127], v[132:135], v[196:199], v[124:127]
	v_mfma_f32_16x16x32_bf16 v[120:123], v[156:159], v[196:199], v[120:123]
	v_mfma_f32_16x16x32_bf16 v[108:111], v[132:135], v[204:207], v[108:111]
	v_mfma_f32_16x16x32_bf16 v[104:107], v[156:159], v[204:207], v[104:107]
	v_mfma_f32_16x16x32_bf16 v[92:95], v[132:135], v[212:215], v[92:95]
	v_mfma_f32_16x16x32_bf16 v[88:91], v[156:159], v[212:215], v[88:91]
	v_mfma_f32_16x16x32_bf16 v[76:79], v[132:135], v[220:223], v[76:79]
	v_mfma_f32_16x16x32_bf16 v[72:75], v[156:159], v[220:223], v[72:75]
	v_mfma_f32_16x16x32_bf16 v[116:119], v[172:175], v[188:191], 0
	v_mfma_f32_16x16x32_bf16 v[112:115], v[180:183], v[188:191], 0
	v_mfma_f32_16x16x32_bf16 v[100:103], v[172:175], v[200:203], 0
	v_mfma_f32_16x16x32_bf16 v[96:99], v[180:183], v[200:203], 0
	v_mfma_f32_16x16x32_bf16 v[84:87], v[172:175], v[208:211], 0
	v_mfma_f32_16x16x32_bf16 v[80:83], v[180:183], v[208:211], 0
	v_mfma_f32_16x16x32_bf16 v[68:71], v[172:175], v[216:219], 0
	v_mfma_f32_16x16x32_bf16 v[64:67], v[180:183], v[216:219], 0
	v_mfma_f32_16x16x32_bf16 v[116:119], v[176:179], v[196:199], v[116:119]
	v_mfma_f32_16x16x32_bf16 v[112:115], v[184:187], v[196:199], v[112:115]
	v_mfma_f32_16x16x32_bf16 v[100:103], v[176:179], v[204:207], v[100:103]
	v_mfma_f32_16x16x32_bf16 v[96:99], v[184:187], v[204:207], v[96:99]
	v_mfma_f32_16x16x32_bf16 v[84:87], v[176:179], v[212:215], v[84:87]
	v_mfma_f32_16x16x32_bf16 v[80:83], v[184:187], v[212:215], v[80:83]
	v_mfma_f32_16x16x32_bf16 v[68:71], v[176:179], v[220:223], v[68:71]
	v_mfma_f32_16x16x32_bf16 v[64:67], v[184:187], v[220:223], v[64:67]
	s_barrier
	s_setprio 0
	s_add_i32 s56, s43, s26
	s_add_u32 s98, s2, s12
	s_addc_u32 s99, s3, s13
	s_mov_b32 m0, s56
	ds_read_b128 v[188:191], v167 offset:16384
	ds_read_b128 v[196:199], v167 offset:17408
	ds_read_b128 v[200:203], v167 offset:18432
	ds_read_b128 v[204:207], v167 offset:19456
	ds_read_b128 v[208:211], v167 offset:20480
	ds_read_b128 v[212:215], v167 offset:21504
	ds_read_b128 v[216:219], v167 offset:22528
	ds_read_b128 v[220:223], v167 offset:23552
	global_load_lds_dwordx4 v150, s[2:3]
	s_add_i32 m0, s56, 0x2000
	s_add_u32 s56, s2, 0xb0000
	s_addc_u32 s57, s3, 0
	s_add_i32 s58, s44, s26
	global_load_lds_dwordx4 v154, s[2:3]
	s_mov_b32 m0, s58
	s_nop 0
	global_load_lds_dwordx4 v150, s[56:57]
	s_add_i32 m0, s58, 0x2000
	s_nop 0
	global_load_lds_dwordx4 v154, s[56:57]
	s_add_u32 s100, s22, s12
	s_addc_u32 s101, s23, s13
	s_mov_b32 m0, s27
	s_nop 0
	global_load_lds_dwordx4 v148, s[22:23]
	s_mov_b32 m0, s28
	s_nop 0
	global_load_lds_dwordx4 v152, s[22:23]
	s_waitcnt vmcnt(8)
	s_waitcnt lgkmcnt(0)
	s_barrier
	s_setprio 1
	v_mfma_f32_16x16x32_bf16 v[60:63], v[128:131], v[188:191], 0
	v_mfma_f32_16x16x32_bf16 v[56:59], v[136:139], v[188:191], 0
	v_mfma_f32_16x16x32_bf16 v[44:47], v[128:131], v[200:203], 0
	v_mfma_f32_16x16x32_bf16 v[40:43], v[136:139], v[200:203], 0
	v_mfma_f32_16x16x32_bf16 v[28:31], v[128:131], v[208:211], 0
	v_mfma_f32_16x16x32_bf16 v[24:27], v[136:139], v[208:211], 0
	v_mfma_f32_16x16x32_bf16 v[12:15], v[128:131], v[216:219], 0
	v_mfma_f32_16x16x32_bf16 v[8:11], v[136:139], v[216:219], 0
	v_mfma_f32_16x16x32_bf16 v[60:63], v[132:135], v[196:199], v[60:63]
	v_mfma_f32_16x16x32_bf16 v[56:59], v[156:159], v[196:199], v[56:59]
	v_mfma_f32_16x16x32_bf16 v[44:47], v[132:135], v[204:207], v[44:47]
	v_mfma_f32_16x16x32_bf16 v[40:43], v[156:159], v[204:207], v[40:43]
	v_mfma_f32_16x16x32_bf16 v[28:31], v[132:135], v[212:215], v[28:31]
	v_mfma_f32_16x16x32_bf16 v[24:27], v[156:159], v[212:215], v[24:27]
	v_mfma_f32_16x16x32_bf16 v[12:15], v[132:135], v[220:223], v[12:15]
	v_mfma_f32_16x16x32_bf16 v[8:11], v[156:159], v[220:223], v[8:11]
	v_mfma_f32_16x16x32_bf16 v[52:55], v[172:175], v[188:191], 0
	v_mfma_f32_16x16x32_bf16 v[48:51], v[180:183], v[188:191], 0
	v_mfma_f32_16x16x32_bf16 v[36:39], v[172:175], v[200:203], 0
	v_mfma_f32_16x16x32_bf16 v[32:35], v[180:183], v[200:203], 0
	v_mfma_f32_16x16x32_bf16 v[20:23], v[172:175], v[208:211], 0
	v_mfma_f32_16x16x32_bf16 v[16:19], v[180:183], v[208:211], 0
	v_mfma_f32_16x16x32_bf16 v[4:7], v[172:175], v[216:219], 0
	v_mfma_f32_16x16x32_bf16 v[0:3], v[180:183], v[216:219], 0
	v_mfma_f32_16x16x32_bf16 v[52:55], v[176:179], v[196:199], v[52:55]
	v_mfma_f32_16x16x32_bf16 v[48:51], v[184:187], v[196:199], v[48:51]
	v_mfma_f32_16x16x32_bf16 v[36:39], v[176:179], v[204:207], v[36:39]
	v_mfma_f32_16x16x32_bf16 v[32:35], v[184:187], v[204:207], v[32:35]
	v_mfma_f32_16x16x32_bf16 v[20:23], v[176:179], v[212:215], v[20:23]
	v_mfma_f32_16x16x32_bf16 v[16:19], v[184:187], v[212:215], v[16:19]
	v_mfma_f32_16x16x32_bf16 v[4:7], v[176:179], v[220:223], v[4:7]
	v_mfma_f32_16x16x32_bf16 v[0:3], v[184:187], v[220:223], v[0:3]
	s_barrier
	s_setprio 0
	s_add_i32 s56, 0, 0x18000
	s_add_i32 s57, 0, 0x1c000
	v_add_u32_e32 v156, s56, v162
	v_add_u32_e32 v169, s57, v162
	ds_read_b128 v[128:131], v156
	ds_read_b128 v[132:135], v156 offset:1024
	ds_read_b128 v[136:139], v156 offset:2048
	ds_read_b128 v[156:159], v156 offset:3072
	ds_read_b128 v[172:175], v169
	ds_read_b128 v[176:179], v169 offset:1024
	ds_read_b128 v[180:183], v169 offset:2048
	ds_read_b128 v[184:187], v169 offset:3072
	s_add_u32 s22, s22, 0xb0000
	s_addc_u32 s23, s23, 0
	s_mov_b32 m0, s29
	ds_read_b128 v[188:191], v167 offset:32768
	ds_read_b128 v[196:199], v167 offset:33792
	ds_read_b128 v[200:203], v167 offset:34816
	ds_read_b128 v[204:207], v167 offset:35840
	ds_read_b128 v[208:211], v167 offset:36864
	ds_read_b128 v[212:215], v167 offset:37888
	ds_read_b128 v[216:219], v167 offset:38912
	ds_read_b128 v[220:223], v167 offset:39936
	global_load_lds_dwordx4 v148, s[22:23]
	s_mov_b32 m0, s30
	s_nop 0
	global_load_lds_dwordx4 v152, s[22:23]
	s_waitcnt vmcnt(8)
	s_waitcnt lgkmcnt(0)
	s_barrier
	s_setprio 1
	v_mfma_f32_16x16x32_bf16 v[124:127], v[128:131], v[188:191], v[124:127]
	v_mfma_f32_16x16x32_bf16 v[120:123], v[136:139], v[188:191], v[120:123]
	v_mfma_f32_16x16x32_bf16 v[108:111], v[128:131], v[200:203], v[108:111]
	v_mfma_f32_16x16x32_bf16 v[104:107], v[136:139], v[200:203], v[104:107]
	v_mfma_f32_16x16x32_bf16 v[92:95], v[128:131], v[208:211], v[92:95]
	v_mfma_f32_16x16x32_bf16 v[88:91], v[136:139], v[208:211], v[88:91]
	v_mfma_f32_16x16x32_bf16 v[76:79], v[128:131], v[216:219], v[76:79]
	v_mfma_f32_16x16x32_bf16 v[72:75], v[136:139], v[216:219], v[72:75]
	v_mfma_f32_16x16x32_bf16 v[124:127], v[132:135], v[196:199], v[124:127]
	v_mfma_f32_16x16x32_bf16 v[120:123], v[156:159], v[196:199], v[120:123]
	v_mfma_f32_16x16x32_bf16 v[108:111], v[132:135], v[204:207], v[108:111]
	v_mfma_f32_16x16x32_bf16 v[104:107], v[156:159], v[204:207], v[104:107]
	v_mfma_f32_16x16x32_bf16 v[92:95], v[132:135], v[212:215], v[92:95]
	v_mfma_f32_16x16x32_bf16 v[88:91], v[156:159], v[212:215], v[88:91]
	v_mfma_f32_16x16x32_bf16 v[76:79], v[132:135], v[220:223], v[76:79]
	v_mfma_f32_16x16x32_bf16 v[72:75], v[156:159], v[220:223], v[72:75]
	v_mfma_f32_16x16x32_bf16 v[116:119], v[172:175], v[188:191], v[116:119]
	v_mfma_f32_16x16x32_bf16 v[112:115], v[180:183], v[188:191], v[112:115]
	v_mfma_f32_16x16x32_bf16 v[100:103], v[172:175], v[200:203], v[100:103]
	v_mfma_f32_16x16x32_bf16 v[96:99], v[180:183], v[200:203], v[96:99]
	v_mfma_f32_16x16x32_bf16 v[84:87], v[172:175], v[208:211], v[84:87]
	v_mfma_f32_16x16x32_bf16 v[80:83], v[180:183], v[208:211], v[80:83]
	v_mfma_f32_16x16x32_bf16 v[68:71], v[172:175], v[216:219], v[68:71]
	v_mfma_f32_16x16x32_bf16 v[64:67], v[180:183], v[216:219], v[64:67]
	v_mfma_f32_16x16x32_bf16 v[116:119], v[176:179], v[196:199], v[116:119]
	v_mfma_f32_16x16x32_bf16 v[112:115], v[184:187], v[196:199], v[112:115]
	v_mfma_f32_16x16x32_bf16 v[100:103], v[176:179], v[204:207], v[100:103]
	v_mfma_f32_16x16x32_bf16 v[96:99], v[184:187], v[204:207], v[96:99]
	v_mfma_f32_16x16x32_bf16 v[84:87], v[176:179], v[212:215], v[84:87]
	v_mfma_f32_16x16x32_bf16 v[80:83], v[184:187], v[212:215], v[80:83]
	v_mfma_f32_16x16x32_bf16 v[68:71], v[176:179], v[220:223], v[68:71]
	v_mfma_f32_16x16x32_bf16 v[64:67], v[184:187], v[220:223], v[64:67]
	s_barrier
	s_setprio 0
	s_add_i32 s22, s56, s26
	s_mov_b32 m0, s22
	ds_read_b128 v[188:191], v167 offset:49152
	ds_read_b128 v[196:199], v167 offset:50176
	ds_read_b128 v[200:203], v167 offset:51200
	ds_read_b128 v[204:207], v167 offset:52224
	ds_read_b128 v[208:211], v167 offset:53248
	ds_read_b128 v[212:215], v167 offset:54272
	ds_read_b128 v[216:219], v167 offset:55296
	ds_read_b128 v[220:223], v167 offset:56320
	global_load_lds_dwordx4 v150, s[98:99]
	s_add_i32 m0, s22, 0x2000
	s_add_u32 s2, s2, 0xb0080
	s_addc_u32 s3, s3, 0
	s_add_i32 s22, s57, s26
	global_load_lds_dwordx4 v154, s[98:99]
	s_mov_b32 m0, s22
	s_nop 0
	global_load_lds_dwordx4 v150, s[2:3]
	s_add_i32 m0, s22, 0x2000
	s_nop 0
	global_load_lds_dwordx4 v154, s[2:3]
	s_mov_b32 m0, s36
	s_nop 0
	global_load_lds_dwordx4 v148, s[100:101]
	s_mov_b32 m0, s37
	s_nop 0
	global_load_lds_dwordx4 v152, s[100:101]
	s_waitcnt vmcnt(8)
	s_waitcnt lgkmcnt(0)
	s_barrier
	s_setprio 1
	v_mfma_f32_16x16x32_bf16 v[60:63], v[128:131], v[188:191], v[60:63]
	v_mfma_f32_16x16x32_bf16 v[56:59], v[136:139], v[188:191], v[56:59]
	v_mfma_f32_16x16x32_bf16 v[44:47], v[128:131], v[200:203], v[44:47]
	v_mfma_f32_16x16x32_bf16 v[40:43], v[136:139], v[200:203], v[40:43]
	v_mfma_f32_16x16x32_bf16 v[28:31], v[128:131], v[208:211], v[28:31]
	v_mfma_f32_16x16x32_bf16 v[24:27], v[136:139], v[208:211], v[24:27]
	v_mfma_f32_16x16x32_bf16 v[12:15], v[128:131], v[216:219], v[12:15]
	v_mfma_f32_16x16x32_bf16 v[8:11], v[136:139], v[216:219], v[8:11]
	v_mfma_f32_16x16x32_bf16 v[60:63], v[132:135], v[196:199], v[60:63]
	v_mfma_f32_16x16x32_bf16 v[56:59], v[156:159], v[196:199], v[56:59]
	v_mfma_f32_16x16x32_bf16 v[44:47], v[132:135], v[204:207], v[44:47]
	v_mfma_f32_16x16x32_bf16 v[40:43], v[156:159], v[204:207], v[40:43]
	v_mfma_f32_16x16x32_bf16 v[28:31], v[132:135], v[212:215], v[28:31]
	v_mfma_f32_16x16x32_bf16 v[24:27], v[156:159], v[212:215], v[24:27]
	v_mfma_f32_16x16x32_bf16 v[12:15], v[132:135], v[220:223], v[12:15]
	v_mfma_f32_16x16x32_bf16 v[8:11], v[156:159], v[220:223], v[8:11]
	v_mfma_f32_16x16x32_bf16 v[52:55], v[172:175], v[188:191], v[52:55]
	v_mfma_f32_16x16x32_bf16 v[48:51], v[180:183], v[188:191], v[48:51]
	v_mfma_f32_16x16x32_bf16 v[36:39], v[172:175], v[200:203], v[36:39]
	v_mfma_f32_16x16x32_bf16 v[32:35], v[180:183], v[200:203], v[32:35]
	v_mfma_f32_16x16x32_bf16 v[20:23], v[172:175], v[208:211], v[20:23]
	v_mfma_f32_16x16x32_bf16 v[16:19], v[180:183], v[208:211], v[16:19]
	v_mfma_f32_16x16x32_bf16 v[4:7], v[172:175], v[216:219], v[4:7]
	v_mfma_f32_16x16x32_bf16 v[0:3], v[180:183], v[216:219], v[0:3]
	v_mfma_f32_16x16x32_bf16 v[52:55], v[176:179], v[196:199], v[52:55]
	v_mfma_f32_16x16x32_bf16 v[48:51], v[184:187], v[196:199], v[48:51]
	v_mfma_f32_16x16x32_bf16 v[36:39], v[176:179], v[204:207], v[36:39]
	v_mfma_f32_16x16x32_bf16 v[32:35], v[184:187], v[204:207], v[32:35]
	v_mfma_f32_16x16x32_bf16 v[20:23], v[176:179], v[212:215], v[20:23]
	v_mfma_f32_16x16x32_bf16 v[16:19], v[184:187], v[212:215], v[16:19]
	v_mfma_f32_16x16x32_bf16 v[4:7], v[176:179], v[220:223], v[4:7]
	v_mfma_f32_16x16x32_bf16 v[0:3], v[184:187], v[220:223], v[0:3]
	s_barrier
	s_setprio 0
	s_add_i32 s55, s55, 2
	s_add_u32 s14, s14, 0x100
	s_addc_u32 s15, s15, 0
	s_add_u32 s53, s53, 0x100
	s_addc_u32 s54, s54, 0
	s_cmp_gt_u32 s55, 41
	s_cbranch_scc1 .Lgemm_kdone_6
.LBB0_891:
	ds_read_b128 v[128:131], v165
	ds_read_b128 v[132:135], v165 offset:1024
	ds_read_b128 v[136:139], v165 offset:2048
	ds_read_b128 v[156:159], v165 offset:3072
	ds_read_b128 v[172:175], v166
	ds_read_b128 v[176:179], v166 offset:1024
	ds_read_b128 v[180:183], v166 offset:2048
	ds_read_b128 v[184:187], v166 offset:3072
	s_add_u32 s2, s14, 0xfff50080
	s_addc_u32 s3, s15, -1
	s_cmp_eq_u32 s55, 40
	s_cselect_b32 s23, s1, s3
	s_cselect_b32 s22, s0, s2
	s_cselect_b32 s3, s21, s54
	s_cselect_b32 s2, s20, s53
	s_add_i32 m0, s27, 0xc000
	ds_read_b128 v[188:191], v167
	ds_read_b128 v[196:199], v167 offset:1024
	ds_read_b128 v[200:203], v167 offset:2048
	ds_read_b128 v[204:207], v167 offset:3072
	ds_read_b128 v[208:211], v167 offset:4096
	ds_read_b128 v[212:215], v167 offset:5120
	ds_read_b128 v[216:219], v167 offset:6144
	ds_read_b128 v[220:223], v167 offset:7168
	global_load_lds_dwordx4 v140, s[14:15]
	s_add_i32 m0, s27, 0xe000
	s_nop 0
	global_load_lds_dwordx4 v142, s[14:15]
	s_waitcnt vmcnt(8)
	s_waitcnt lgkmcnt(0)
	s_barrier
	s_setprio 1
	v_mfma_f32_16x16x32_bf16 v[124:127], v[128:131], v[188:191], v[124:127]
	v_mfma_f32_16x16x32_bf16 v[120:123], v[136:139], v[188:191], v[120:123]
	v_mfma_f32_16x16x32_bf16 v[108:111], v[128:131], v[200:203], v[108:111]
	v_mfma_f32_16x16x32_bf16 v[104:107], v[136:139], v[200:203], v[104:107]
	v_mfma_f32_16x16x32_bf16 v[92:95], v[128:131], v[208:211], v[92:95]
	v_mfma_f32_16x16x32_bf16 v[88:91], v[136:139], v[208:211], v[88:91]
	v_mfma_f32_16x16x32_bf16 v[76:79], v[128:131], v[216:219], v[76:79]
	v_mfma_f32_16x16x32_bf16 v[72:75], v[136:139], v[216:219], v[72:75]
	v_mfma_f32_16x16x32_bf16 v[124:127], v[132:135], v[196:199], v[124:127]
	v_mfma_f32_16x16x32_bf16 v[120:123], v[156:159], v[196:199], v[120:123]
	v_mfma_f32_16x16x32_bf16 v[108:111], v[132:135], v[204:207], v[108:111]
	v_mfma_f32_16x16x32_bf16 v[104:107], v[156:159], v[204:207], v[104:107]
	v_mfma_f32_16x16x32_bf16 v[92:95], v[132:135], v[212:215], v[92:95]
	v_mfma_f32_16x16x32_bf16 v[88:91], v[156:159], v[212:215], v[88:91]
	v_mfma_f32_16x16x32_bf16 v[76:79], v[132:135], v[220:223], v[76:79]
	v_mfma_f32_16x16x32_bf16 v[72:75], v[156:159], v[220:223], v[72:75]
	v_mfma_f32_16x16x32_bf16 v[116:119], v[172:175], v[188:191], v[116:119]
	v_mfma_f32_16x16x32_bf16 v[112:115], v[180:183], v[188:191], v[112:115]
	v_mfma_f32_16x16x32_bf16 v[100:103], v[172:175], v[200:203], v[100:103]
	v_mfma_f32_16x16x32_bf16 v[96:99], v[180:183], v[200:203], v[96:99]
	v_mfma_f32_16x16x32_bf16 v[84:87], v[172:175], v[208:211], v[84:87]
	v_mfma_f32_16x16x32_bf16 v[80:83], v[180:183], v[208:211], v[80:83]
	v_mfma_f32_16x16x32_bf16 v[68:71], v[172:175], v[216:219], v[68:71]
	v_mfma_f32_16x16x32_bf16 v[64:67], v[180:183], v[216:219], v[64:67]
	v_mfma_f32_16x16x32_bf16 v[116:119], v[176:179], v[196:199], v[116:119]
	v_mfma_f32_16x16x32_bf16 v[112:115], v[184:187], v[196:199], v[112:115]
	v_mfma_f32_16x16x32_bf16 v[100:103], v[176:179], v[204:207], v[100:103]
	v_mfma_f32_16x16x32_bf16 v[96:99], v[184:187], v[204:207], v[96:99]
	v_mfma_f32_16x16x32_bf16 v[84:87], v[176:179], v[212:215], v[84:87]
	v_mfma_f32_16x16x32_bf16 v[80:83], v[184:187], v[212:215], v[80:83]
	v_mfma_f32_16x16x32_bf16 v[68:71], v[176:179], v[220:223], v[68:71]
	v_mfma_f32_16x16x32_bf16 v[64:67], v[184:187], v[220:223], v[64:67]
	s_barrier
	s_setprio 0
	s_add_i32 s56, s43, s26
	s_add_u32 s98, s2, s12
	s_addc_u32 s99, s3, s13
	s_mov_b32 m0, s56
	ds_read_b128 v[188:191], v167 offset:16384
	ds_read_b128 v[196:199], v167 offset:17408
	ds_read_b128 v[200:203], v167 offset:18432
	ds_read_b128 v[204:207], v167 offset:19456
	ds_read_b128 v[208:211], v167 offset:20480
	ds_read_b128 v[212:215], v167 offset:21504
	ds_read_b128 v[216:219], v167 offset:22528
	ds_read_b128 v[220:223], v167 offset:23552
	global_load_lds_dwordx4 v150, s[2:3]
	s_add_i32 m0, s56, 0x2000
	s_add_u32 s56, s2, 0xb0000
	s_addc_u32 s57, s3, 0
	s_add_i32 s58, s44, s26
	global_load_lds_dwordx4 v154, s[2:3]
	s_mov_b32 m0, s58
	s_nop 0
	global_load_lds_dwordx4 v150, s[56:57]
	s_add_i32 m0, s58, 0x2000
	s_nop 0
	global_load_lds_dwordx4 v154, s[56:57]
	s_add_u32 s100, s22, s12
	s_addc_u32 s101, s23, s13
	s_mov_b32 m0, s27
	s_nop 0
	global_load_lds_dwordx4 v148, s[22:23]
	s_mov_b32 m0, s28
	s_nop 0
	global_load_lds_dwordx4 v152, s[22:23]
	s_waitcnt vmcnt(8)
	s_waitcnt lgkmcnt(0)
	s_barrier
	s_setprio 1
	v_mfma_f32_16x16x32_bf16 v[60:63], v[128:131], v[188:191], v[60:63]
	v_mfma_f32_16x16x32_bf16 v[56:59], v[136:139], v[188:191], v[56:59]
	v_mfma_f32_16x16x32_bf16 v[44:47], v[128:131], v[200:203], v[44:47]
	v_mfma_f32_16x16x32_bf16 v[40:43], v[136:139], v[200:203], v[40:43]
	v_mfma_f32_16x16x32_bf16 v[28:31], v[128:131], v[208:211], v[28:31]
	v_mfma_f32_16x16x32_bf16 v[24:27], v[136:139], v[208:211], v[24:27]
	v_mfma_f32_16x16x32_bf16 v[12:15], v[128:131], v[216:219], v[12:15]
	v_mfma_f32_16x16x32_bf16 v[8:11], v[136:139], v[216:219], v[8:11]
	v_mfma_f32_16x16x32_bf16 v[60:63], v[132:135], v[196:199], v[60:63]
	v_mfma_f32_16x16x32_bf16 v[56:59], v[156:159], v[196:199], v[56:59]
	v_mfma_f32_16x16x32_bf16 v[44:47], v[132:135], v[204:207], v[44:47]
	v_mfma_f32_16x16x32_bf16 v[40:43], v[156:159], v[204:207], v[40:43]
	v_mfma_f32_16x16x32_bf16 v[28:31], v[132:135], v[212:215], v[28:31]
	v_mfma_f32_16x16x32_bf16 v[24:27], v[156:159], v[212:215], v[24:27]
	v_mfma_f32_16x16x32_bf16 v[12:15], v[132:135], v[220:223], v[12:15]
	v_mfma_f32_16x16x32_bf16 v[8:11], v[156:159], v[220:223], v[8:11]
	v_mfma_f32_16x16x32_bf16 v[52:55], v[172:175], v[188:191], v[52:55]
	v_mfma_f32_16x16x32_bf16 v[48:51], v[180:183], v[188:191], v[48:51]
	v_mfma_f32_16x16x32_bf16 v[36:39], v[172:175], v[200:203], v[36:39]
	v_mfma_f32_16x16x32_bf16 v[32:35], v[180:183], v[200:203], v[32:35]
	v_mfma_f32_16x16x32_bf16 v[20:23], v[172:175], v[208:211], v[20:23]
	v_mfma_f32_16x16x32_bf16 v[16:19], v[180:183], v[208:211], v[16:19]
	v_mfma_f32_16x16x32_bf16 v[4:7], v[172:175], v[216:219], v[4:7]
	v_mfma_f32_16x16x32_bf16 v[0:3], v[180:183], v[216:219], v[0:3]
	v_mfma_f32_16x16x32_bf16 v[52:55], v[176:179], v[196:199], v[52:55]
	v_mfma_f32_16x16x32_bf16 v[48:51], v[184:187], v[196:199], v[48:51]
	v_mfma_f32_16x16x32_bf16 v[36:39], v[176:179], v[204:207], v[36:39]
	v_mfma_f32_16x16x32_bf16 v[32:35], v[184:187], v[204:207], v[32:35]
	v_mfma_f32_16x16x32_bf16 v[20:23], v[176:179], v[212:215], v[20:23]
	v_mfma_f32_16x16x32_bf16 v[16:19], v[184:187], v[212:215], v[16:19]
	v_mfma_f32_16x16x32_bf16 v[4:7], v[176:179], v[220:223], v[4:7]
	v_mfma_f32_16x16x32_bf16 v[0:3], v[184:187], v[220:223], v[0:3]
	s_barrier
	s_setprio 0
	s_add_i32 s56, 0, 0x18000
	s_add_i32 s57, 0, 0x1c000
	v_add_u32_e32 v156, s56, v162
	v_add_u32_e32 v169, s57, v162
	ds_read_b128 v[128:131], v156
	ds_read_b128 v[132:135], v156 offset:1024
	ds_read_b128 v[136:139], v156 offset:2048
	ds_read_b128 v[156:159], v156 offset:3072
	ds_read_b128 v[172:175], v169
	ds_read_b128 v[176:179], v169 offset:1024
	ds_read_b128 v[180:183], v169 offset:2048
	ds_read_b128 v[184:187], v169 offset:3072
	s_add_u32 s22, s22, 0xb0000
	s_addc_u32 s23, s23, 0
	s_mov_b32 m0, s29
	ds_read_b128 v[188:191], v167 offset:32768
	ds_read_b128 v[196:199], v167 offset:33792
	ds_read_b128 v[200:203], v167 offset:34816
	ds_read_b128 v[204:207], v167 offset:35840
	ds_read_b128 v[208:211], v167 offset:36864
	ds_read_b128 v[212:215], v167 offset:37888
	ds_read_b128 v[216:219], v167 offset:38912
	ds_read_b128 v[220:223], v167 offset:39936
	global_load_lds_dwordx4 v148, s[22:23]
	s_mov_b32 m0, s30
	s_nop 0
	global_load_lds_dwordx4 v152, s[22:23]
	s_waitcnt vmcnt(8)
	s_waitcnt lgkmcnt(0)
	s_barrier
	s_setprio 1
	v_mfma_f32_16x16x32_bf16 v[124:127], v[128:131], v[188:191], v[124:127]
	v_mfma_f32_16x16x32_bf16 v[120:123], v[136:139], v[188:191], v[120:123]
	v_mfma_f32_16x16x32_bf16 v[108:111], v[128:131], v[200:203], v[108:111]
	v_mfma_f32_16x16x32_bf16 v[104:107], v[136:139], v[200:203], v[104:107]
	v_mfma_f32_16x16x32_bf16 v[92:95], v[128:131], v[208:211], v[92:95]
	v_mfma_f32_16x16x32_bf16 v[88:91], v[136:139], v[208:211], v[88:91]
	v_mfma_f32_16x16x32_bf16 v[76:79], v[128:131], v[216:219], v[76:79]
	v_mfma_f32_16x16x32_bf16 v[72:75], v[136:139], v[216:219], v[72:75]
	v_mfma_f32_16x16x32_bf16 v[124:127], v[132:135], v[196:199], v[124:127]
	v_mfma_f32_16x16x32_bf16 v[120:123], v[156:159], v[196:199], v[120:123]
	v_mfma_f32_16x16x32_bf16 v[108:111], v[132:135], v[204:207], v[108:111]
	v_mfma_f32_16x16x32_bf16 v[104:107], v[156:159], v[204:207], v[104:107]
	v_mfma_f32_16x16x32_bf16 v[92:95], v[132:135], v[212:215], v[92:95]
	v_mfma_f32_16x16x32_bf16 v[88:91], v[156:159], v[212:215], v[88:91]
	v_mfma_f32_16x16x32_bf16 v[76:79], v[132:135], v[220:223], v[76:79]
	v_mfma_f32_16x16x32_bf16 v[72:75], v[156:159], v[220:223], v[72:75]
	v_mfma_f32_16x16x32_bf16 v[116:119], v[172:175], v[188:191], v[116:119]
	v_mfma_f32_16x16x32_bf16 v[112:115], v[180:183], v[188:191], v[112:115]
	v_mfma_f32_16x16x32_bf16 v[100:103], v[172:175], v[200:203], v[100:103]
	v_mfma_f32_16x16x32_bf16 v[96:99], v[180:183], v[200:203], v[96:99]
	v_mfma_f32_16x16x32_bf16 v[84:87], v[172:175], v[208:211], v[84:87]
	v_mfma_f32_16x16x32_bf16 v[80:83], v[180:183], v[208:211], v[80:83]
	v_mfma_f32_16x16x32_bf16 v[68:71], v[172:175], v[216:219], v[68:71]
	v_mfma_f32_16x16x32_bf16 v[64:67], v[180:183], v[216:219], v[64:67]
	v_mfma_f32_16x16x32_bf16 v[116:119], v[176:179], v[196:199], v[116:119]
	v_mfma_f32_16x16x32_bf16 v[112:115], v[184:187], v[196:199], v[112:115]
	v_mfma_f32_16x16x32_bf16 v[100:103], v[176:179], v[204:207], v[100:103]
	v_mfma_f32_16x16x32_bf16 v[96:99], v[184:187], v[204:207], v[96:99]
	v_mfma_f32_16x16x32_bf16 v[84:87], v[176:179], v[212:215], v[84:87]
	v_mfma_f32_16x16x32_bf16 v[80:83], v[184:187], v[212:215], v[80:83]
	v_mfma_f32_16x16x32_bf16 v[68:71], v[176:179], v[220:223], v[68:71]
	v_mfma_f32_16x16x32_bf16 v[64:67], v[184:187], v[220:223], v[64:67]
	s_barrier
	s_setprio 0
	s_add_i32 s22, s56, s26
	s_mov_b32 m0, s22
	ds_read_b128 v[188:191], v167 offset:49152
	ds_read_b128 v[196:199], v167 offset:50176
	ds_read_b128 v[200:203], v167 offset:51200
	ds_read_b128 v[204:207], v167 offset:52224
	ds_read_b128 v[208:211], v167 offset:53248
	ds_read_b128 v[212:215], v167 offset:54272
	ds_read_b128 v[216:219], v167 offset:55296
	ds_read_b128 v[220:223], v167 offset:56320
	global_load_lds_dwordx4 v150, s[98:99]
	s_add_i32 m0, s22, 0x2000
	s_add_u32 s2, s2, 0xb0080
	s_addc_u32 s3, s3, 0
	s_add_i32 s22, s57, s26
	global_load_lds_dwordx4 v154, s[98:99]
	s_mov_b32 m0, s22
	s_nop 0
	global_load_lds_dwordx4 v150, s[2:3]
	s_add_i32 m0, s22, 0x2000
	s_nop 0
	global_load_lds_dwordx4 v154, s[2:3]
	s_mov_b32 m0, s36
	s_nop 0
	global_load_lds_dwordx4 v148, s[100:101]
	s_mov_b32 m0, s37
	s_nop 0
	global_load_lds_dwordx4 v152, s[100:101]
	s_waitcnt vmcnt(8)
	s_waitcnt lgkmcnt(0)
	s_barrier
	s_setprio 1
	v_mfma_f32_16x16x32_bf16 v[60:63], v[128:131], v[188:191], v[60:63]
	v_mfma_f32_16x16x32_bf16 v[56:59], v[136:139], v[188:191], v[56:59]
	v_mfma_f32_16x16x32_bf16 v[44:47], v[128:131], v[200:203], v[44:47]
	v_mfma_f32_16x16x32_bf16 v[40:43], v[136:139], v[200:203], v[40:43]
	v_mfma_f32_16x16x32_bf16 v[28:31], v[128:131], v[208:211], v[28:31]
	v_mfma_f32_16x16x32_bf16 v[24:27], v[136:139], v[208:211], v[24:27]
	v_mfma_f32_16x16x32_bf16 v[12:15], v[128:131], v[216:219], v[12:15]
	v_mfma_f32_16x16x32_bf16 v[8:11], v[136:139], v[216:219], v[8:11]
	v_mfma_f32_16x16x32_bf16 v[60:63], v[132:135], v[196:199], v[60:63]
	v_mfma_f32_16x16x32_bf16 v[56:59], v[156:159], v[196:199], v[56:59]
	v_mfma_f32_16x16x32_bf16 v[44:47], v[132:135], v[204:207], v[44:47]
	v_mfma_f32_16x16x32_bf16 v[40:43], v[156:159], v[204:207], v[40:43]
	v_mfma_f32_16x16x32_bf16 v[28:31], v[132:135], v[212:215], v[28:31]
	v_mfma_f32_16x16x32_bf16 v[24:27], v[156:159], v[212:215], v[24:27]
	v_mfma_f32_16x16x32_bf16 v[12:15], v[132:135], v[220:223], v[12:15]
	v_mfma_f32_16x16x32_bf16 v[8:11], v[156:159], v[220:223], v[8:11]
	v_mfma_f32_16x16x32_bf16 v[52:55], v[172:175], v[188:191], v[52:55]
	v_mfma_f32_16x16x32_bf16 v[48:51], v[180:183], v[188:191], v[48:51]
	v_mfma_f32_16x16x32_bf16 v[36:39], v[172:175], v[200:203], v[36:39]
	v_mfma_f32_16x16x32_bf16 v[32:35], v[180:183], v[200:203], v[32:35]
	v_mfma_f32_16x16x32_bf16 v[20:23], v[172:175], v[208:211], v[20:23]
	v_mfma_f32_16x16x32_bf16 v[16:19], v[180:183], v[208:211], v[16:19]
	v_mfma_f32_16x16x32_bf16 v[4:7], v[172:175], v[216:219], v[4:7]
	v_mfma_f32_16x16x32_bf16 v[0:3], v[180:183], v[216:219], v[0:3]
	v_mfma_f32_16x16x32_bf16 v[52:55], v[176:179], v[196:199], v[52:55]
	v_mfma_f32_16x16x32_bf16 v[48:51], v[184:187], v[196:199], v[48:51]
	v_mfma_f32_16x16x32_bf16 v[36:39], v[176:179], v[204:207], v[36:39]
	v_mfma_f32_16x16x32_bf16 v[32:35], v[184:187], v[204:207], v[32:35]
	v_mfma_f32_16x16x32_bf16 v[20:23], v[176:179], v[212:215], v[20:23]
	v_mfma_f32_16x16x32_bf16 v[16:19], v[184:187], v[212:215], v[16:19]
	v_mfma_f32_16x16x32_bf16 v[4:7], v[176:179], v[220:223], v[4:7]
	v_mfma_f32_16x16x32_bf16 v[0:3], v[184:187], v[220:223], v[0:3]
	s_barrier
	s_setprio 0
	s_add_i32 s55, s55, 2
	s_add_u32 s14, s14, 0x100
	s_addc_u32 s15, s15, 0
	s_add_u32 s53, s53, 0x100
	s_addc_u32 s54, s54, 0
	s_cmp_gt_u32 s55, 41
	s_cbranch_scc0 .LBB0_891
